# GEMM K-loops: LDS-DMA staging rebalanced 4/4 per load segment; redundant grid sync removed; attention: 1 barrier per KV tile, deeper K prefetch, conflict-free 4-bit K swizzle
# speedup vs baseline: 1.0110x; 1.0110x over previous
; #define PG8_STAGE(bufoff, gbase, voff) do { _Pragma("unroll") for (int _i = 0; _i < 2; ++_i) \
;         __builtin_amdgcn_global_load_lds((const unsigned*)((const char*)(gbase) + (voff)[_i]), (PG8_LAS unsigned*)(lds + (bufoff) + ldsw + _i * 8192), 16, 0, 0); } while (0)
; #define PG8_LDA(dst, b, h) do { _Pragma("unroll") for (int m = 0; m < 4; ++m) _Pragma("unroll") for (int k = 0; k < 2; ++k) dst[m][k] = *(const PG8_LAS bf16x8*)(lds + PG8_SA(b, h) + aoff + m * 2048 + k * 1024); } while (0)
; #define PG8_LDB(dst, b, h) do { _Pragma("unroll") for (int n = 0; n < 2; ++n) _Pragma("unroll") for (int k = 0; k < 2; ++k) dst[n][k] = *(const PG8_LAS bf16x8*)(lds + PG8_SB(b, h) + boff + n * 2048 + k * 1024); } while (0)
; #define PG8_MMA(ai, bj, At, Bt) do { __builtin_amdgcn_s_setprio(1); _Pragma("unroll") for (int m = 0; m < 4; ++m) _Pragma("unroll") for (int n = 0; n < 2; ++n) _Pragma("unroll") for (int k = 0; k < 2; ++k) \
;         acc[ai][bj][m][n] = __builtin_amdgcn_mfma_f32_16x16x32_bf16(Bt[n][k], At[m][k], acc[ai][bj][m][n], 0, 0, 0); __builtin_amdgcn_s_setprio(0); } while (0)
; #define PG8_WAIT_V(n) asm volatile("s_waitcnt vmcnt(" #n ")" ::: "memory")
; #define PG8_WAIT_L(n) asm volatile("s_waitcnt lgkmcnt(" #n ")" ::: "memory")
; #define PG8_BAR __builtin_amdgcn_s_barrier()
; #define PG8_SCHED __builtin_amdgcn_sched_barrier(0)
; template <class Epi, class Sched, bool ALIGN_EPI = false, bool SP2 = false, bool KSEG = false>
; __device__ __forceinline__ void gemm_phase(PG8_LAS unsigned char* lds, const Gemm g, const Sched& S, const Epi& E) {
;     ...
;             const char* a2 = last ? nA : cA + (size_t)(t + 2) * kstep; const char* b2 = last ? nB : cB + (size_t)(t + 2) * kstep;
;             const char* a3 = a2 + kstep; const char* b3 = b2 + kstep;
;             if (last && has_next) S.a_ready(nxt);
;             if constexpr (SP2) {
;             PG8_LDB(B0, 0, 0); PG8_LDB(B1, 0, 1); PG8_SCHED; PG8_LDA(At, 0, 0); PG8_STAGE(PG8_SA(1, 1), a1 + hstep, voffA);
;             PG8_WAIT_V(8); PG8_WAIT_L(0); PG8_BAR; PG8_MMA(0, 0, At, B0); PG8_MMA(0, 1, At, B1); PG8_BAR; PG8_SCHED;
;             PG8_LDA(At, 0, 1); PG8_STAGE(PG8_SB(0, 0), b2, voffB); PG8_STAGE(PG8_SB(0, 1), b2 + hstep, voffB); PG8_STAGE(PG8_SA(0, 0), a2, voffA);
;             PG8_WAIT_V(8); PG8_WAIT_L(0); PG8_BAR; PG8_MMA(1, 0, At, B0); PG8_MMA(1, 1, At, B1); PG8_BAR; PG8_SCHED;
.LBB0_120:
	ds_read_b128 v[146:149], v156
	ds_read_b128 v[150:153], v156 offset:1024
	ds_read_b128 v[160:163], v156 offset:2048
	ds_read_b128 v[164:167], v156 offset:3072
	ds_read_b128 v[168:171], v157
	ds_read_b128 v[172:175], v157 offset:1024
	ds_read_b128 v[176:179], v157 offset:2048
	ds_read_b128 v[180:183], v157 offset:3072
	s_add_u32 s30, s28, 0xfff80080
	s_addc_u32 s31, s29, -1
	s_cmp_eq_u32 s80, 28
	s_cselect_b32 s43, s21, s31
	s_cselect_b32 s42, s64, s30
	s_cselect_b32 s31, s19, s67
	s_cselect_b32 s30, s65, s66
	s_add_u32 s98, s28, 0xfff80000
	s_addc_u32 s99, s29, -1
	v_lshl_add_u64 v[216:217], s[98:99], 0, v[136:137]
	s_mov_b32 m0, s51
	s_nop 0
	global_load_lds_dwordx4 v[216:217], off
	v_lshl_add_u64 v[216:217], s[98:99], 0, v[132:133]
	s_mov_b32 m0, s58
	s_nop 0
	global_load_lds_dwordx4 v[216:217], off
	v_lshl_add_u64 v[216:217], s[28:29], 0, v[138:139]
	s_add_i32 m0, s27, 0xc000
	ds_read_b128 v[184:187], v158
	ds_read_b128 v[188:191], v158 offset:1024
	ds_read_b128 v[192:195], v158 offset:2048
	ds_read_b128 v[196:199], v158 offset:3072
	ds_read_b128 v[200:203], v158 offset:4096
	ds_read_b128 v[204:207], v158 offset:5120
	ds_read_b128 v[208:211], v158 offset:6144
	ds_read_b128 v[212:215], v158 offset:7168
	global_load_lds_dwordx4 v[216:217], off
	v_lshl_add_u64 v[216:217], s[28:29], 0, v[140:141]
	s_add_i32 m0, s27, 0xe000
	s_nop 0
	global_load_lds_dwordx4 v[216:217], off
	s_waitcnt vmcnt(8)
	s_waitcnt lgkmcnt(0)
	s_barrier
	s_setprio 1
	s_waitcnt lgkmcnt(0)
	v_mfma_f32_16x16x32_bf16 v[126:129], v[146:149], v[184:187], v[126:129]
	v_mfma_f32_16x16x32_bf16 v[122:125], v[160:163], v[184:187], v[122:125]
	v_mfma_f32_16x16x32_bf16 v[110:113], v[146:149], v[192:195], v[110:113]
	v_mfma_f32_16x16x32_bf16 v[106:109], v[160:163], v[192:195], v[106:109]
	v_mfma_f32_16x16x32_bf16 v[94:97], v[146:149], v[200:203], v[94:97]
	v_mfma_f32_16x16x32_bf16 v[90:93], v[160:163], v[200:203], v[90:93]
	v_mfma_f32_16x16x32_bf16 v[78:81], v[146:149], v[208:211], v[78:81]
	v_mfma_f32_16x16x32_bf16 v[74:77], v[160:163], v[208:211], v[74:77]
	v_mfma_f32_16x16x32_bf16 v[126:129], v[150:153], v[188:191], v[126:129]
	v_mfma_f32_16x16x32_bf16 v[122:125], v[164:167], v[188:191], v[122:125]
	v_mfma_f32_16x16x32_bf16 v[110:113], v[150:153], v[196:199], v[110:113]
	v_mfma_f32_16x16x32_bf16 v[106:109], v[164:167], v[196:199], v[106:109]
	v_mfma_f32_16x16x32_bf16 v[94:97], v[150:153], v[204:207], v[94:97]
	v_mfma_f32_16x16x32_bf16 v[90:93], v[164:167], v[204:207], v[90:93]
	v_mfma_f32_16x16x32_bf16 v[78:81], v[150:153], v[212:215], v[78:81]
	v_mfma_f32_16x16x32_bf16 v[74:77], v[164:167], v[212:215], v[74:77]
	s_setprio 0
	s_setprio 1
	v_mfma_f32_16x16x32_bf16 v[118:121], v[168:171], v[184:187], v[118:121]
	v_mfma_f32_16x16x32_bf16 v[114:117], v[176:179], v[184:187], v[114:117]
	v_mfma_f32_16x16x32_bf16 v[102:105], v[168:171], v[192:195], v[102:105]
	v_mfma_f32_16x16x32_bf16 v[98:101], v[176:179], v[192:195], v[98:101]
	v_mfma_f32_16x16x32_bf16 v[86:89], v[168:171], v[200:203], v[86:89]
	v_mfma_f32_16x16x32_bf16 v[82:85], v[176:179], v[200:203], v[82:85]
	v_mfma_f32_16x16x32_bf16 v[70:73], v[168:171], v[208:211], v[70:73]
	v_mfma_f32_16x16x32_bf16 v[66:69], v[176:179], v[208:211], v[66:69]
	v_mfma_f32_16x16x32_bf16 v[118:121], v[172:175], v[188:191], v[118:121]
	v_mfma_f32_16x16x32_bf16 v[114:117], v[180:183], v[188:191], v[114:117]
	v_mfma_f32_16x16x32_bf16 v[102:105], v[172:175], v[196:199], v[102:105]
	v_mfma_f32_16x16x32_bf16 v[98:101], v[180:183], v[196:199], v[98:101]
	v_mfma_f32_16x16x32_bf16 v[86:89], v[172:175], v[204:207], v[86:89]
	v_mfma_f32_16x16x32_bf16 v[82:85], v[180:183], v[204:207], v[82:85]
	v_mfma_f32_16x16x32_bf16 v[70:73], v[172:175], v[212:215], v[70:73]
	v_mfma_f32_16x16x32_bf16 v[66:69], v[180:183], v[212:215], v[66:69]
	s_setprio 0
	s_barrier
	s_add_i32 s33, s60, s44
	v_lshl_add_u64 v[216:217], s[30:31], 0, v[134:135]
	s_mov_b32 m0, s33
	ds_read_b128 v[184:187], v158 offset:16384
	ds_read_b128 v[188:191], v158 offset:17408
	ds_read_b128 v[192:195], v158 offset:18432
	ds_read_b128 v[196:199], v158 offset:19456
	ds_read_b128 v[200:203], v158 offset:20480
	ds_read_b128 v[204:207], v158 offset:21504
	ds_read_b128 v[208:211], v158 offset:22528
	ds_read_b128 v[212:215], v158 offset:23552
	global_load_lds_dwordx4 v[216:217], off
	s_add_i32 m0, s33, 0x2000
	s_add_u32 s84, s30, 0x80000
	v_lshl_add_u64 v[218:219], s[30:31], 0, v[130:131]
	s_addc_u32 s85, s31, 0
	s_add_i32 s33, s61, s44
	global_load_lds_dwordx4 v[218:219], off
	v_lshl_add_u64 v[220:221], s[84:85], 0, v[134:135]
	s_mov_b32 m0, s33
	s_nop 0
	global_load_lds_dwordx4 v[220:221], off
	v_lshl_add_u64 v[220:221], s[84:85], 0, v[130:131]
	s_add_i32 m0, s33, 0x2000
	s_nop 0
	global_load_lds_dwordx4 v[220:221], off
	s_waitcnt vmcnt(6)
	s_waitcnt lgkmcnt(0)
	s_barrier
; #define PG8_STAGE(bufoff, gbase, voff) do { _Pragma("unroll") for (int _i = 0; _i < 2; ++_i) \
;         __builtin_amdgcn_global_load_lds((const unsigned*)((const char*)(gbase) + (voff)[_i]), (PG8_LAS unsigned*)(lds + (bufoff) + ldsw + _i * 8192), 16, 0, 0); } while (0)
; #define PG8_LDA(dst, b, h) do { _Pragma("unroll") for (int m = 0; m < 4; ++m) _Pragma("unroll") for (int k = 0; k < 2; ++k) dst[m][k] = *(const PG8_LAS bf16x8*)(lds + PG8_SA(b, h) + aoff + m * 2048 + k * 1024); } while (0)
; #define PG8_LDB(dst, b, h) do { _Pragma("unroll") for (int n = 0; n < 2; ++n) _Pragma("unroll") for (int k = 0; k < 2; ++k) dst[n][k] = *(const PG8_LAS bf16x8*)(lds + PG8_SB(b, h) + boff + n * 2048 + k * 1024); } while (0)
; #define PG8_MMA(ai, bj, At, Bt) do { __builtin_amdgcn_s_setprio(1); _Pragma("unroll") for (int m = 0; m < 4; ++m) _Pragma("unroll") for (int n = 0; n < 2; ++n) _Pragma("unroll") for (int k = 0; k < 2; ++k) \
;         acc[ai][bj][m][n] = __builtin_amdgcn_mfma_f32_16x16x32_bf16(Bt[n][k], At[m][k], acc[ai][bj][m][n], 0, 0, 0); __builtin_amdgcn_s_setprio(0); } while (0)
; #define PG8_WAIT_V(n) asm volatile("s_waitcnt vmcnt(" #n ")" ::: "memory")
; #define PG8_WAIT_L(n) asm volatile("s_waitcnt lgkmcnt(" #n ")" ::: "memory")
; #define PG8_BAR __builtin_amdgcn_s_barrier()
; #define PG8_SCHED __builtin_amdgcn_sched_barrier(0)
; template <class Epi, class Sched, bool ALIGN_EPI = false, bool SP2 = false, bool KSEG = false>
; __device__ __forceinline__ void gemm_phase(PG8_LAS unsigned char* lds, const Gemm g, const Sched& S, const Epi& E) {
;     ...
;             PG8_WAIT_V(8); PG8_WAIT_L(0); PG8_BAR; PG8_MMA(1, 0, At, B0); PG8_MMA(1, 1, At, B1); PG8_BAR; PG8_SCHED;
;             PG8_LDB(B0, 1, 0); PG8_LDB(B1, 1, 1); PG8_SCHED; PG8_LDA(At, 1, 0); PG8_STAGE(PG8_SA(0, 1), a2 + hstep, voffA);
;             PG8_WAIT_V(8); PG8_WAIT_L(0); PG8_BAR; PG8_MMA(0, 0, At, B0); PG8_MMA(0, 1, At, B1); PG8_BAR; PG8_SCHED;
	s_setprio 1
	s_waitcnt lgkmcnt(0)
	v_mfma_f32_16x16x32_bf16 v[62:65], v[146:149], v[184:187], v[62:65]
	v_mfma_f32_16x16x32_bf16 v[58:61], v[160:163], v[184:187], v[58:61]
	v_mfma_f32_16x16x32_bf16 v[46:49], v[146:149], v[192:195], v[46:49]
	v_mfma_f32_16x16x32_bf16 v[42:45], v[160:163], v[192:195], v[42:45]
	v_mfma_f32_16x16x32_bf16 v[30:33], v[146:149], v[200:203], v[30:33]
	v_mfma_f32_16x16x32_bf16 v[26:29], v[160:163], v[200:203], v[26:29]
	v_mfma_f32_16x16x32_bf16 v[14:17], v[146:149], v[208:211], v[14:17]
	v_mfma_f32_16x16x32_bf16 v[10:13], v[160:163], v[208:211], v[10:13]
	v_mfma_f32_16x16x32_bf16 v[62:65], v[150:153], v[188:191], v[62:65]
	v_mfma_f32_16x16x32_bf16 v[58:61], v[164:167], v[188:191], v[58:61]
	v_mfma_f32_16x16x32_bf16 v[46:49], v[150:153], v[196:199], v[46:49]
	v_mfma_f32_16x16x32_bf16 v[42:45], v[164:167], v[196:199], v[42:45]
	v_mfma_f32_16x16x32_bf16 v[30:33], v[150:153], v[204:207], v[30:33]
	v_mfma_f32_16x16x32_bf16 v[26:29], v[164:167], v[204:207], v[26:29]
	v_mfma_f32_16x16x32_bf16 v[14:17], v[150:153], v[212:215], v[14:17]
	v_mfma_f32_16x16x32_bf16 v[10:13], v[164:167], v[212:215], v[10:13]
	s_setprio 0
	s_setprio 1
	v_mfma_f32_16x16x32_bf16 v[54:57], v[168:171], v[184:187], v[54:57]
	v_mfma_f32_16x16x32_bf16 v[50:53], v[176:179], v[184:187], v[50:53]
	v_mfma_f32_16x16x32_bf16 v[38:41], v[168:171], v[192:195], v[38:41]
	v_mfma_f32_16x16x32_bf16 v[34:37], v[176:179], v[192:195], v[34:37]
	v_mfma_f32_16x16x32_bf16 v[22:25], v[168:171], v[200:203], v[22:25]
	v_mfma_f32_16x16x32_bf16 v[18:21], v[176:179], v[200:203], v[18:21]
	v_mfma_f32_16x16x32_bf16 v[6:9], v[168:171], v[208:211], v[6:9]
	v_mfma_f32_16x16x32_bf16 v[2:5], v[176:179], v[208:211], v[2:5]
	v_mfma_f32_16x16x32_bf16 v[54:57], v[172:175], v[188:191], v[54:57]
	v_mfma_f32_16x16x32_bf16 v[50:53], v[180:183], v[188:191], v[50:53]
	v_mfma_f32_16x16x32_bf16 v[38:41], v[172:175], v[196:199], v[38:41]
	v_mfma_f32_16x16x32_bf16 v[34:37], v[180:183], v[196:199], v[34:37]
	v_mfma_f32_16x16x32_bf16 v[22:25], v[172:175], v[204:207], v[22:25]
	v_mfma_f32_16x16x32_bf16 v[18:21], v[180:183], v[204:207], v[18:21]
	v_mfma_f32_16x16x32_bf16 v[6:9], v[172:175], v[212:215], v[6:9]
	v_mfma_f32_16x16x32_bf16 v[2:5], v[180:183], v[212:215], v[2:5]
	s_setprio 0
	s_barrier
	s_add_i32 s33, 0, 0x18000
	v_add_u32_e32 v159, s33, v154
	s_add_i32 s81, 0, 0x1c000
	ds_read_b128 v[146:149], v159
	ds_read_b128 v[150:153], v159 offset:1024
	ds_read_b128 v[160:163], v159 offset:2048
	ds_read_b128 v[164:167], v159 offset:3072
	v_add_u32_e32 v159, s81, v154
	ds_read_b128 v[168:171], v159
	ds_read_b128 v[172:175], v159 offset:1024
	ds_read_b128 v[176:179], v159 offset:2048
	ds_read_b128 v[180:183], v159 offset:3072
	v_lshl_add_u64 v[224:225], s[42:43], 0, v[136:137]
	s_mov_b32 m0, s27
	s_nop 0
	global_load_lds_dwordx4 v[224:225], off
	v_lshl_add_u64 v[224:225], s[42:43], 0, v[132:133]
	s_mov_b32 m0, s47
	s_nop 0
	global_load_lds_dwordx4 v[224:225], off
	s_add_u32 s42, s42, 0x80000
	s_addc_u32 s43, s43, 0
	s_mov_b32 m0, s48
	v_lshl_add_u64 v[224:225], s[42:43], 0, v[136:137]
	ds_read_b128 v[184:187], v158 offset:32768
	ds_read_b128 v[188:191], v158 offset:33792
	ds_read_b128 v[192:195], v158 offset:34816
	ds_read_b128 v[196:199], v158 offset:35840
	ds_read_b128 v[200:203], v158 offset:36864
	ds_read_b128 v[204:207], v158 offset:37888
	ds_read_b128 v[208:211], v158 offset:38912
	ds_read_b128 v[212:215], v158 offset:39936
	global_load_lds_dwordx4 v[224:225], off
	v_lshl_add_u64 v[224:225], s[42:43], 0, v[132:133]
	s_mov_b32 m0, s49
	s_nop 0
	global_load_lds_dwordx4 v[224:225], off
	s_waitcnt vmcnt(8)
	s_waitcnt lgkmcnt(0)
	s_barrier
; #define PG8_STAGE(bufoff, gbase, voff) do { _Pragma("unroll") for (int _i = 0; _i < 2; ++_i) \
;         __builtin_amdgcn_global_load_lds((const unsigned*)((const char*)(gbase) + (voff)[_i]), (PG8_LAS unsigned*)(lds + (bufoff) + ldsw + _i * 8192), 16, 0, 0); } while (0)
; #define PG8_LDA(dst, b, h) do { _Pragma("unroll") for (int m = 0; m < 4; ++m) _Pragma("unroll") for (int k = 0; k < 2; ++k) dst[m][k] = *(const PG8_LAS bf16x8*)(lds + PG8_SA(b, h) + aoff + m * 2048 + k * 1024); } while (0)
; #define PG8_MMA(ai, bj, At, Bt) do { __builtin_amdgcn_s_setprio(1); _Pragma("unroll") for (int m = 0; m < 4; ++m) _Pragma("unroll") for (int n = 0; n < 2; ++n) _Pragma("unroll") for (int k = 0; k < 2; ++k) \
;         acc[ai][bj][m][n] = __builtin_amdgcn_mfma_f32_16x16x32_bf16(Bt[n][k], At[m][k], acc[ai][bj][m][n], 0, 0, 0); __builtin_amdgcn_s_setprio(0); } while (0)
; #define PG8_WAIT_V(n) asm volatile("s_waitcnt vmcnt(" #n ")" ::: "memory")
; #define PG8_WAIT_L(n) asm volatile("s_waitcnt lgkmcnt(" #n ")" ::: "memory")
; #define PG8_BAR __builtin_amdgcn_s_barrier()
; #define PG8_SCHED __builtin_amdgcn_sched_barrier(0)
; template <class Epi, class Sched, bool ALIGN_EPI = false, bool SP2 = false, bool KSEG = false>
; __device__ __forceinline__ void gemm_phase(PG8_LAS unsigned char* lds, const Gemm g, const Sched& S, const Epi& E) {
;     ...
;             PG8_WAIT_V(8); PG8_WAIT_L(0); PG8_BAR; PG8_MMA(0, 0, At, B0); PG8_MMA(0, 1, At, B1); PG8_BAR; PG8_SCHED;
;             PG8_LDA(At, 1, 1); PG8_STAGE(PG8_SB(1, 0), b3, voffB); PG8_STAGE(PG8_SB(1, 1), b3 + hstep, voffB); PG8_STAGE(PG8_SA(1, 0), a3, voffA);
;             PG8_WAIT_V(8); PG8_WAIT_L(0); PG8_BAR; PG8_MMA(1, 0, At, B0); PG8_MMA(1, 1, At, B1); PG8_BAR; PG8_SCHED;
	s_setprio 1
	s_waitcnt lgkmcnt(0)
	v_mfma_f32_16x16x32_bf16 v[126:129], v[146:149], v[184:187], v[126:129]
	v_mfma_f32_16x16x32_bf16 v[122:125], v[160:163], v[184:187], v[122:125]
	v_mfma_f32_16x16x32_bf16 v[110:113], v[146:149], v[192:195], v[110:113]
	v_mfma_f32_16x16x32_bf16 v[106:109], v[160:163], v[192:195], v[106:109]
	v_mfma_f32_16x16x32_bf16 v[94:97], v[146:149], v[200:203], v[94:97]
	v_mfma_f32_16x16x32_bf16 v[90:93], v[160:163], v[200:203], v[90:93]
	v_mfma_f32_16x16x32_bf16 v[78:81], v[146:149], v[208:211], v[78:81]
	v_mfma_f32_16x16x32_bf16 v[74:77], v[160:163], v[208:211], v[74:77]
	v_mfma_f32_16x16x32_bf16 v[126:129], v[150:153], v[188:191], v[126:129]
	v_mfma_f32_16x16x32_bf16 v[122:125], v[164:167], v[188:191], v[122:125]
	v_mfma_f32_16x16x32_bf16 v[110:113], v[150:153], v[196:199], v[110:113]
	v_mfma_f32_16x16x32_bf16 v[106:109], v[164:167], v[196:199], v[106:109]
	v_mfma_f32_16x16x32_bf16 v[94:97], v[150:153], v[204:207], v[94:97]
	v_mfma_f32_16x16x32_bf16 v[90:93], v[164:167], v[204:207], v[90:93]
	v_mfma_f32_16x16x32_bf16 v[78:81], v[150:153], v[212:215], v[78:81]
	v_mfma_f32_16x16x32_bf16 v[74:77], v[164:167], v[212:215], v[74:77]
	s_setprio 0
	s_setprio 1
	v_mfma_f32_16x16x32_bf16 v[118:121], v[168:171], v[184:187], v[118:121]
	v_mfma_f32_16x16x32_bf16 v[114:117], v[176:179], v[184:187], v[114:117]
	v_mfma_f32_16x16x32_bf16 v[102:105], v[168:171], v[192:195], v[102:105]
	v_mfma_f32_16x16x32_bf16 v[98:101], v[176:179], v[192:195], v[98:101]
	v_mfma_f32_16x16x32_bf16 v[86:89], v[168:171], v[200:203], v[86:89]
	v_mfma_f32_16x16x32_bf16 v[82:85], v[176:179], v[200:203], v[82:85]
	v_mfma_f32_16x16x32_bf16 v[70:73], v[168:171], v[208:211], v[70:73]
	v_mfma_f32_16x16x32_bf16 v[66:69], v[176:179], v[208:211], v[66:69]
	v_mfma_f32_16x16x32_bf16 v[118:121], v[172:175], v[188:191], v[118:121]
	v_mfma_f32_16x16x32_bf16 v[114:117], v[180:183], v[188:191], v[114:117]
	v_mfma_f32_16x16x32_bf16 v[102:105], v[172:175], v[196:199], v[102:105]
	v_mfma_f32_16x16x32_bf16 v[98:101], v[180:183], v[196:199], v[98:101]
	v_mfma_f32_16x16x32_bf16 v[86:89], v[172:175], v[204:207], v[86:89]
	v_mfma_f32_16x16x32_bf16 v[82:85], v[180:183], v[204:207], v[82:85]
	v_mfma_f32_16x16x32_bf16 v[70:73], v[172:175], v[212:215], v[70:73]
	v_mfma_f32_16x16x32_bf16 v[66:69], v[180:183], v[212:215], v[66:69]
	s_setprio 0
	s_barrier
	s_add_i32 s33, s33, s44
	v_lshl_add_u64 v[216:217], v[216:217], 0, s[12:13]
	s_mov_b32 m0, s33
	ds_read_b128 v[184:187], v158 offset:49152
	ds_read_b128 v[188:191], v158 offset:50176
	ds_read_b128 v[192:195], v158 offset:51200
	ds_read_b128 v[196:199], v158 offset:52224
	ds_read_b128 v[200:203], v158 offset:53248
	ds_read_b128 v[204:207], v158 offset:54272
	ds_read_b128 v[208:211], v158 offset:55296
	ds_read_b128 v[212:215], v158 offset:56320
	global_load_lds_dwordx4 v[216:217], off
	s_add_i32 m0, s33, 0x2000
	s_add_u32 s30, s30, 0x80080
	v_lshl_add_u64 v[216:217], v[218:219], 0, s[12:13]
	s_addc_u32 s31, s31, 0
	s_add_i32 s33, s81, s44
	global_load_lds_dwordx4 v[216:217], off
	v_lshl_add_u64 v[216:217], s[30:31], 0, v[134:135]
	s_mov_b32 m0, s33
	s_nop 0
	global_load_lds_dwordx4 v[216:217], off
	v_lshl_add_u64 v[216:217], s[30:31], 0, v[130:131]
	s_add_i32 m0, s33, 0x2000
	s_nop 0
	global_load_lds_dwordx4 v[216:217], off
	s_waitcnt vmcnt(6)
	s_waitcnt lgkmcnt(0)
	s_barrier
	s_setprio 1
	s_waitcnt lgkmcnt(0)
	v_mfma_f32_16x16x32_bf16 v[62:65], v[146:149], v[184:187], v[62:65]
	v_mfma_f32_16x16x32_bf16 v[58:61], v[160:163], v[184:187], v[58:61]
	v_mfma_f32_16x16x32_bf16 v[46:49], v[146:149], v[192:195], v[46:49]
	v_mfma_f32_16x16x32_bf16 v[42:45], v[160:163], v[192:195], v[42:45]
	v_mfma_f32_16x16x32_bf16 v[30:33], v[146:149], v[200:203], v[30:33]
	v_mfma_f32_16x16x32_bf16 v[26:29], v[160:163], v[200:203], v[26:29]
	v_mfma_f32_16x16x32_bf16 v[14:17], v[146:149], v[208:211], v[14:17]
	v_mfma_f32_16x16x32_bf16 v[10:13], v[160:163], v[208:211], v[10:13]
	v_mfma_f32_16x16x32_bf16 v[62:65], v[150:153], v[188:191], v[62:65]
	v_mfma_f32_16x16x32_bf16 v[58:61], v[164:167], v[188:191], v[58:61]
	v_mfma_f32_16x16x32_bf16 v[46:49], v[150:153], v[196:199], v[46:49]
	v_mfma_f32_16x16x32_bf16 v[42:45], v[164:167], v[196:199], v[42:45]
	v_mfma_f32_16x16x32_bf16 v[30:33], v[150:153], v[204:207], v[30:33]
	v_mfma_f32_16x16x32_bf16 v[26:29], v[164:167], v[204:207], v[26:29]
	v_mfma_f32_16x16x32_bf16 v[14:17], v[150:153], v[212:215], v[14:17]
	v_mfma_f32_16x16x32_bf16 v[10:13], v[164:167], v[212:215], v[10:13]
	s_setprio 0
	s_setprio 1
	v_mfma_f32_16x16x32_bf16 v[54:57], v[168:171], v[184:187], v[54:57]
	v_mfma_f32_16x16x32_bf16 v[50:53], v[176:179], v[184:187], v[50:53]
	v_mfma_f32_16x16x32_bf16 v[38:41], v[168:171], v[192:195], v[38:41]
	v_mfma_f32_16x16x32_bf16 v[34:37], v[176:179], v[192:195], v[34:37]
	v_mfma_f32_16x16x32_bf16 v[22:25], v[168:171], v[200:203], v[22:25]
	v_mfma_f32_16x16x32_bf16 v[18:21], v[176:179], v[200:203], v[18:21]
	v_mfma_f32_16x16x32_bf16 v[6:9], v[168:171], v[208:211], v[6:9]
	v_mfma_f32_16x16x32_bf16 v[2:5], v[176:179], v[208:211], v[2:5]
	v_mfma_f32_16x16x32_bf16 v[54:57], v[172:175], v[188:191], v[54:57]
	v_mfma_f32_16x16x32_bf16 v[50:53], v[180:183], v[188:191], v[50:53]
	v_mfma_f32_16x16x32_bf16 v[38:41], v[172:175], v[196:199], v[38:41]
	v_mfma_f32_16x16x32_bf16 v[34:37], v[180:183], v[196:199], v[34:37]
	v_mfma_f32_16x16x32_bf16 v[22:25], v[172:175], v[204:207], v[22:25]
	v_mfma_f32_16x16x32_bf16 v[18:21], v[180:183], v[204:207], v[18:21]
	v_mfma_f32_16x16x32_bf16 v[6:9], v[172:175], v[212:215], v[6:9]
	v_mfma_f32_16x16x32_bf16 v[2:5], v[180:183], v[212:215], v[2:5]
	s_setprio 0
	s_barrier
	s_add_i32 s80, s80, 2
	s_add_u32 s28, s28, 0x100
	s_addc_u32 s29, s29, 0
	s_add_u32 s66, s66, 0x100
	s_addc_u32 s67, s67, 0
	s_cmp_gt_u32 s80, 29
	s_cbranch_scc0 .LBB0_120
	s_and_b64 vcc, exec, s[16:17]
	s_cbranch_vccz .LBB0_123
	s_barrier

; __device__ __forceinline__ int v_st(int k, int c) { const int kk = (k & ~0xC) | ((k & 4) << 1) | ((k & 8) >> 1); return ((kk >> 3) * 4 + (c >> 5)) * 512 + ((kk & 7) * 32 + (c & 31)) * 2; }
; __device__ __forceinline__ int v_rd_base(int lane) { return ((lane & 3) << 3) | (((lane >> 2) & 3) << 6) | (((lane >> 4) & 1) << 5) | (((lane >> 5) & 1) << 8); }
; #define SLOAD(i, k0) do { const long to_ = (long)(k0) * ldk * 2; const char* vt_ = (const char*)Vh + to_; const char* kt_ = (const char*)Kh + to_; \
;     sr_[i].vs0 = *(const bf16x8*)(vt_ + toff); sr_[i].vs1 = *(const bf16x8*)(vt_ + h32 + toff); \
;     sr_[i].ks0 = *(const bf16x8*)(kt_ + toff); sr_[i].ks1 = *(const bf16x8*)(kt_ + h32 + toff); } while (0)
; #define MASK(P0, P1, k0) do { if constexpr (MODE == 1) { const int k0_ = (k0); \
;     if ((k0_ + 63 - qw0 > 128) || (k0_ - (qw0 + 31) < -128)) maskwin(P0, P1, k0_ - (qw0 + r32) + 128 + 4 * hi); } } while (0)
; __device__ __forceinline__ void qkt(f32x16& p0, f32x16& p1, const bf16* Ks, const bf16x8* qr, int r32, int hi) {
;   p0 = f32x16{}; p1 = f32x16{};
;   for (int d0 = 0; d0 < 8; ++d0) { int cb = (d0 * 16 + hi * 8) * 2;
;     bf16x8 b0 = *reinterpret_cast<const bf16x8*>((const char*)Ks + KSWZ(r32, cb));
;     bf16x8 b1 = *reinterpret_cast<const bf16x8*>((const char*)Ks + KSWZ(32 + r32, cb));
;     p0 = __builtin_amdgcn_mfma_f32_32x32x16_bf16(b0, qr[d0], p0, 0, 0, 0);
;     p1 = __builtin_amdgcn_mfma_f32_32x32x16_bf16(b1, qr[d0], p1, 0, 0, 0); }
; }
; template <int MODE, int QMODE> ...
;     ...
;   const int sr = tid >> 4, sc = (tid & 15) * 8, vst0 = v_st(sr, sc), vst1 = v_st(32 + sr, sc);
;   const int vb0 = (int)(uintptr_t)V_lds + v_rd_base(lane);
;   const unsigned toff = (unsigned)(sr * ldk + sc) * 2u; const long h32 = (long)ldk * 64;
;   constexpr int SDEPTH = (MODE == 0 && QMODE == 2) ? 2 : 1;
;   struct { typename St::T vs0, vs1, ks0, ks1; } sr_[SDEPTH];
;     ...
;   const int qw0 = qrel + wrow;
;     ...
;   if (wid >= 4) __builtin_amdgcn_s_setprio(1);
;   f32x16 pA0, pA1, pB0, pB1; float mnA, mnB, alA, alB; bf16x8 pa0, pa1, pa2, pa3; const int NT = seq / KVBLK;
;   constexpr int SE = 0, SO = SDEPTH - 1;
;   SLOAD(SE, 0); asm volatile("s_waitcnt vmcnt(0)" ::: "memory"); SWRITE(0, SE); __syncthreads();
;   qkt(pA0, pA1, K_lds, qr, r32, hi); MASK(pA0, pA1, 0); partialSM(pA0, pA1, m_reg, mnA, alA);
.LBB0_170:
	s_mul_i32 s33, s17, 0x1800
	s_mul_hi_u32 s97, s17, 0x1800
	s_add_u32 s2, s40, s33
	v_ashrrev_i32_e32 v18, 4, v229
	v_lshlrev_b32_e32 v19, 3, v229
	s_addc_u32 s3, s41, s97
	s_and_b32 s17, s47, 0xffffff00
	v_and_b32_e32 v20, 0x78, v19
	v_mul_lo_u32 v2, v18, s59
	s_add_u32 s2, s2, s17
	v_or_b32_e32 v2, v2, v20
	s_addc_u32 s3, s3, 0
	v_lshlrev_b32_e32 v50, 1, v2
	v_mov_b32_e32 v51, v211
	v_lshl_add_u64 v[52:53], s[2:3], 0, v[50:51]
	v_add_co_u32_e32 v10, vcc, s60, v52
	v_lshlrev_b32_e32 v22, 4, v233
	s_nop 0
	v_addc_co_u32_e32 v11, vcc, 0, v53, vcc
	v_add_co_u32_e32 v14, vcc, s61, v52
	global_load_dwordx4 v[2:5], v[10:11], off offset:512
	s_nop 0
	v_addc_co_u32_e32 v15, vcc, 0, v53, vcc
	global_load_dwordx4 v[6:9], v[14:15], off offset:512
	s_nop 0
	global_load_dwordx4 v[10:13], v[10:11], off
	s_nop 0
	global_load_dwordx4 v[14:17], v[14:15], off
	v_and_b32_e32 v23, 0xfffff0, v18
	v_lshlrev_b32_e32 v24, 1, v18
	v_lshrrev_b32_e32 v25, 1, v18
	v_and_b32_e32 v26, 3, v18
	v_add_u32_e32 v27, 32, v18
	v_and_b32_e32 v71, 0xf0, v22
	v_and_or_b32 v22, v24, 8, v23
	v_and_or_b32 v23, v25, 4, v26
	v_and_b32_e32 v24, 0xfffff0, v27
	v_lshlrev_b32_e32 v25, 1, v27
	v_and_b32_e32 v21, 0xf0, v229
	v_bfe_u32 v19, v19, 5, 2
	v_lshlrev_b32_e32 v18, 8, v18
	v_lshlrev_b32_e32 v20, 1, v20
	v_lshlrev_b32_e32 v26, 8, v27
	v_lshrrev_b32_e32 v22, 1, v22
	v_and_or_b32 v24, v25, 8, v24
	v_and_b32_e32 v28, 48, v20
	v_bitop3_b32 v18, v20, v18, v21 bitop3:0xde
	v_bitop3_b32 v20, v20, v26, v21 bitop3:0xde
	v_or_b32_e32 v21, v22, v19
	v_lshrrev_b32_e32 v22, 1, v24
	v_lshlrev_b32_e32 v70, 8, v233
	v_lshlrev_b32_e32 v23, 6, v23
	v_add_u32_e32 v219, 0, v18
	v_lshlrev_b32_e32 v18, 9, v21
	v_or_b32_e32 v19, v22, v19
	v_bitop3_b32 v27, v210, v70, v71 bitop3:0xde
	v_or3_b32 v18, v18, v23, v28
	v_lshlrev_b32_e32 v19, 9, v19
	v_add_u32_e32 v218, 0, v27
	v_or3_b32 v19, v19, v23, v28
	v_add_u32_e32 v221, 0, v18
	v_add_u32_e32 v220, 0, v20
	s_waitcnt vmcnt(0)
	v_add_u32_e32 v222, 0, v19
	v_and_b32_e32 v98, 63, v229
	s_and_b32 s2, s16, 0x3fffffc0
	s_lshl_b32 s2, s2, 2
	s_add_i32 s95, s2, 0
	s_add_i32 s95, s95, 0x10000
	s_cmp_lg_u32 0, -1
	s_cselect_b32 s4, 0, 0
	s_mov_b32 s16, s9
	s_mov_b32 s17, s9
	s_mov_b32 s18, s9
	s_mov_b32 s19, s9
	s_mov_b32 s20, s9
	s_mov_b32 s21, s9
	s_mov_b32 s22, s9
	s_mov_b32 s23, s9
	s_mov_b32 s24, s9
	s_mov_b32 s25, s9
	s_mov_b32 s26, s9
	s_mov_b32 s27, s9
	s_mov_b32 s28, s9
	s_mov_b32 s29, s9
	s_mov_b32 s30, s9
	s_mov_b32 s31, s9
	s_mov_b32 s49, s9
	s_mov_b32 s96, 2
	v_cmp_gt_u32_e64 s[2:3], 32, v98
	v_lshl_add_u32 v214, v233, 2, s95
	v_mov_b32_e32 v215, 0
	s_waitcnt vmcnt(3)
	ds_write_b128 v221, v[2:5]
	s_waitcnt vmcnt(2)
	ds_write_b128 v222, v[6:9]
	s_waitcnt vmcnt(1)
	ds_write_b128 v219, v[10:13] offset:32768
	s_waitcnt vmcnt(0)
	ds_write_b128 v220, v[14:17] offset:32768
	s_waitcnt lgkmcnt(0)
	s_barrier
	ds_read_b128 v[2:5], v218 offset:32768
	ds_read_b128 v[6:9], v218 offset:40960
	s_waitcnt lgkmcnt(1)
	v_mfma_f32_32x32x16_bf16 v[18:33], v[2:5], v[134:137], 0
	v_or_b32_e32 v2, 32, v210
	v_bitop3_b32 v2, v2, v70, v71 bitop3:0xde
	v_add_u32_e32 v223, 0, v2
	v_or_b32_e32 v10, 0xa0, v210
	v_or_b32_e32 v11, 0xc0, v210
	v_lshlrev_b32_e32 v14, 3, v98
	s_waitcnt lgkmcnt(0)
	v_mfma_f32_32x32x16_bf16 v[34:49], v[6:9], v[134:137], 0
	ds_read_b128 v[2:5], v223 offset:32768
	ds_read_b128 v[6:9], v223 offset:40960
	s_waitcnt lgkmcnt(1)
	v_mfma_f32_32x32x16_bf16 v[18:33], v[2:5], v[142:145], v[18:33]
	v_or_b32_e32 v2, 64, v210
	v_bitop3_b32 v2, v2, v70, v71 bitop3:0xde
	v_add_u32_e32 v227, 0, v2
	s_waitcnt lgkmcnt(0)
	v_mfma_f32_32x32x16_bf16 v[34:49], v[6:9], v[142:145], v[34:49]
	ds_read_b128 v[2:5], v227 offset:32768
	ds_read_b128 v[6:9], v227 offset:40960
	s_waitcnt lgkmcnt(1)
	v_mfma_f32_32x32x16_bf16 v[18:33], v[2:5], v[130:133], v[18:33]
	v_or_b32_e32 v2, 0x60, v210
	v_bitop3_b32 v2, v2, v70, v71 bitop3:0xde
	v_add_u32_e32 v228, 0, v2
	ds_read_b128 v[2:5], v228 offset:32768
	s_waitcnt lgkmcnt(1)
	v_mfma_f32_32x32x16_bf16 v[34:49], v[6:9], v[130:133], v[34:49]
	ds_read_b128 v[6:9], v228 offset:40960
	s_waitcnt lgkmcnt(1)
	v_mfma_f32_32x32x16_bf16 v[18:33], v[2:5], v[138:141], v[18:33]
	v_or_b32_e32 v2, 0x80, v210
	v_bitop3_b32 v2, v2, v70, v71 bitop3:0xde
	v_add_u32_e32 v229, 0, v2
	ds_read_b128 v[2:5], v229 offset:32768
	s_waitcnt lgkmcnt(1)
	v_mfma_f32_32x32x16_bf16 v[34:49], v[6:9], v[138:141], v[34:49]
	v_lshlrev_b32_e32 v6, 4, v98
	v_lshlrev_b32_e32 v7, 1, v98
	v_and_b32_e32 v12, 0xc0, v6
	v_and_b32_e32 v15, 32, v7
	ds_read_b128 v[6:9], v229 offset:40960
	v_and_or_b32 v16, v14, 24, v12
	s_waitcnt lgkmcnt(1)
	v_mfma_f32_32x32x16_bf16 v[18:33], v[2:5], v[150:153], v[18:33]
	v_bitop3_b32 v2, v10, v70, v71 bitop3:0xde
	v_bitop3_b32 v3, v11, v70, v71 bitop3:0xde
	v_add_u32_e32 v231, 0, v2
	v_add_u32_e32 v230, 0, v3
	ds_read_b128 v[2:5], v231 offset:32768
	v_add_co_u32_e32 v10, vcc, s63, v52
	s_waitcnt lgkmcnt(1)
	v_mfma_f32_32x32x16_bf16 v[34:49], v[6:9], v[150:153], v[34:49]
	v_addc_co_u32_e32 v11, vcc, 0, v53, vcc
	v_add_co_u32_e32 v12, vcc, s64, v52
	ds_read_b128 v[6:9], v231 offset:40960
	s_nop 0
	v_addc_co_u32_e32 v13, vcc, 0, v53, vcc
	global_load_dwordx4 v[54:57], v[10:11], off offset:512
	s_waitcnt lgkmcnt(1)
	v_mfma_f32_32x32x16_bf16 v[18:33], v[2:5], v[158:161], v[18:33]
	global_load_dwordx4 v[58:61], v[12:13], off offset:512
	global_load_dwordx4 v[62:65], v[10:11], off
	global_load_dwordx4 v[66:69], v[12:13], off
	ds_read_b128 v[2:5], v230 offset:32768
	s_waitcnt lgkmcnt(1)
	v_mfma_f32_32x32x16_bf16 v[34:49], v[6:9], v[158:161], v[34:49]
	v_and_b32_e32 v6, 0x100, v14
	v_or3_b32 v99, v16, v15, v6
	ds_read_b128 v[6:9], v230 offset:40960
	v_add_u32_e32 v217, s4, v99
	s_waitcnt lgkmcnt(1)
; #define SLOAD(i, k0) do { const long to_ = (long)(k0) * ldk * 2; const char* vt_ = (const char*)Vh + to_; const char* kt_ = (const char*)Kh + to_; \
;     sr_[i].vs0 = *(const bf16x8*)(vt_ + toff); sr_[i].vs1 = *(const bf16x8*)(vt_ + h32 + toff); \
;     sr_[i].ks0 = *(const bf16x8*)(kt_ + toff); sr_[i].ks1 = *(const bf16x8*)(kt_ + h32 + toff); } while (0)
; #define SWAIT() do { if constexpr (SDEPTH == 2) asm volatile("s_waitcnt vmcnt(4)" ::: "memory"); else asm volatile("s_waitcnt vmcnt(0)" ::: "memory"); } while (0)
; #define MASK(P0, P1, k0) do { if constexpr (MODE == 1) { const int k0_ = (k0); \
;     if ((k0_ + 63 - qw0 > 128) || (k0_ - (qw0 + 31) < -128)) maskwin(P0, P1, k0_ - (qw0 + r32) + 128 + 4 * hi); } } while (0)
; __device__ __forceinline__ void partialSM(f32x16& p0, f32x16& p1, float& m_reg, float& mn, float& alpha) {
;   constexpr float C = SCALE * 1.4426950408889634f;
;   float pmax = p0[0]; for (int r = 1; r < 16; ++r) pmax = fmaxf(pmax, p0[r]); for (int r = 0; r < 16; ++r) pmax = fmaxf(pmax, p1[r]);
;   { auto rr = __builtin_amdgcn_permlane32_swap(__float_as_uint(pmax), __float_as_uint(pmax), false, false);
;     pmax = fmaxf(__uint_as_float(rr[0]), __uint_as_float(rr[1])); }
;   if (__builtin_expect(__all(pmax - m_reg <= THR / SCALE), 1)) { mn = m_reg; alpha = 1.f; }
;   else { mn = fmaxf(m_reg, pmax); alpha = __builtin_amdgcn_exp2f((m_reg - mn) * C); m_reg = mn; }
;   float mnC = -mn * C;
;   for (int r = 0; r < 16; ++r) p0[r] = fmaf(p0[r], C, mnC); for (int r = 0; r < 16; ++r) p1[r] = fmaf(p1[r], C, mnC);
;   for (int r = 0; r < 16; ++r) p0[r] = __builtin_amdgcn_exp2f(p0[r]);
; }
; template <int MODE, int QMODE> ...
;     ...
;   qkt(pA0, pA1, K_lds, qr, r32, hi); MASK(pA0, pA1, 0); partialSM(pA0, pA1, m_reg, mnA, alA);
;   SLOAD(SO, KVBLK); if constexpr (SDEPTH == 2) { if (2 < NT) SLOAD(SE, 2 * KVBLK); }
;   SWAIT(); SWRITE(1, SO); __syncthreads();
	v_mfma_f32_32x32x16_bf16 v[18:33], v[2:5], v[146:149], v[18:33]
	v_or_b32_e32 v2, 0xe0, v210
	v_bitop3_b32 v2, v2, v70, v71 bitop3:0xde
	v_add_u32_e32 v232, 0, v2
	ds_read_b128 v[2:5], v232 offset:32768
	ds_read_b128 v[70:73], v232 offset:40960
	s_waitcnt lgkmcnt(2)
	v_mfma_f32_32x32x16_bf16 v[34:49], v[6:9], v[146:149], v[34:49]
	s_waitcnt lgkmcnt(1)
	v_mfma_f32_32x32x16_bf16 v[18:33], v[2:5], v[154:157], v[18:33]
	v_mov_b64_e32 v[2:3], s[16:17]
	v_mov_b64_e32 v[4:5], s[18:19]
	v_mov_b64_e32 v[6:7], s[20:21]
	v_mov_b64_e32 v[8:9], s[22:23]
	v_mov_b64_e32 v[10:11], s[24:25]
	v_mov_b64_e32 v[12:13], s[26:27]
	v_mov_b64_e32 v[14:15], s[28:29]
	s_waitcnt lgkmcnt(0)
	v_mfma_f32_32x32x16_bf16 v[34:49], v[70:73], v[154:157], v[34:49]
	s_nop 2
	v_max_f32_e32 v70, v19, v19
	v_max_f32_e32 v71, v18, v18
	v_max_f32_e32 v70, v71, v70
	v_max3_f32 v70, v70, v20, v21
	v_max3_f32 v70, v70, v22, v23
	v_max3_f32 v70, v70, v24, v25
	v_max3_f32 v70, v70, v26, v27
	v_max3_f32 v70, v70, v28, v29
	v_max3_f32 v70, v70, v30, v31
	v_max3_f32 v70, v70, v32, v33
	v_max3_f32 v70, v70, v34, v35
	v_max3_f32 v70, v70, v36, v37
	v_max3_f32 v70, v70, v38, v39
	v_max3_f32 v70, v70, v40, v41
	v_max3_f32 v70, v70, v42, v43
	v_max3_f32 v70, v70, v44, v45
	v_max3_f32 v70, v70, v46, v47
	v_max3_f32 v72, v70, v48, v49
	v_add_co_u32_e32 v70, vcc, s65, v52
	v_mov_b32_e32 v73, v72
	s_nop 0
	v_addc_co_u32_e32 v71, vcc, 0, v53, vcc
	v_add_co_u32_e32 v52, vcc, s66, v52
	v_permlane32_swap_b32_e32 v72, v73
	s_nop 0
	v_addc_co_u32_e32 v53, vcc, 0, v53, vcc
	global_load_dwordx4 v[162:165], v[70:71], off
	global_load_dwordx4 v[170:173], v[70:71], off offset:512
	global_load_dwordx4 v[174:177], v[52:53], off
	global_load_dwordx4 v[166:169], v[52:53], off offset:512
	v_max_f32_e32 v52, v73, v73
	v_max_f32_e32 v53, v72, v72
	v_max_f32_e32 v52, v53, v52
	v_add_f32_e32 v53, 0x7149f2ca, v52
	v_cmp_ge_f32_e32 vcc, s62, v53
	s_cmp_eq_u64 vcc, exec
	v_max_f32_e32 v52, 0xf149f2ca, v52
	s_cselect_b64 vcc, -1, 0
	v_cndmask_b32_e32 v237, v52, v225, vcc
	v_sub_f32_e32 v53, 0xf149f2ca, v52
	v_mul_f32_e32 v52, 0xbe0293ee, v237
	v_fmamk_f32 v18, v18, 0x3e0293ee, v52
	s_waitcnt vmcnt(4)
	s_waitcnt vmcnt(7)
	ds_write_b128 v221, v[54:57] offset:16384
	s_waitcnt vmcnt(6)
	ds_write_b128 v222, v[58:61] offset:16384
	s_waitcnt vmcnt(5)
	ds_write_b128 v219, v[62:65] offset:49152
	s_waitcnt vmcnt(4)
	ds_write_b128 v220, v[66:69] offset:49152
	v_exp_f32_e32 v66, v18
	v_fmamk_f32 v18, v19, 0x3e0293ee, v52
	v_exp_f32_e32 v67, v18
	v_fmamk_f32 v18, v20, 0x3e0293ee, v52
	v_exp_f32_e32 v68, v18
	v_fmamk_f32 v18, v21, 0x3e0293ee, v52
	v_exp_f32_e32 v69, v18
	v_fmamk_f32 v18, v22, 0x3e0293ee, v52
	v_exp_f32_e32 v70, v18
	v_fmamk_f32 v18, v23, 0x3e0293ee, v52
	v_exp_f32_e32 v71, v18
	v_fmamk_f32 v18, v24, 0x3e0293ee, v52
	v_exp_f32_e32 v72, v18
	v_fmamk_f32 v18, v25, 0x3e0293ee, v52
	v_exp_f32_e32 v73, v18
	v_fmamk_f32 v18, v26, 0x3e0293ee, v52
	v_mul_f32_e32 v53, 0x3e0293ee, v53
	v_exp_f32_e32 v74, v18
	v_fmamk_f32 v18, v27, 0x3e0293ee, v52
	v_exp_f32_e32 v53, v53
	v_exp_f32_e32 v75, v18
	v_fmamk_f32 v18, v28, 0x3e0293ee, v52
	v_mov_b64_e32 v[16:17], s[30:31]
	v_exp_f32_e32 v76, v18
	v_fmamk_f32 v18, v29, 0x3e0293ee, v52
	s_lshr_b32 s16, s48, 1
	v_exp_f32_e32 v77, v18
	v_fmamk_f32 v18, v30, 0x3e0293ee, v52
	s_addk_i32 s4, 0x4000
	s_lshl_b64 s[16:17], s[16:17], 8
	v_exp_f32_e32 v78, v18
	v_fmamk_f32 v18, v31, 0x3e0293ee, v52
	v_add_u32_e32 v216, s4, v99
	s_add_u32 s4, s33, s16
	v_pk_fma_f32 v[96:97], v[48:49], s[12:13], v[52:53] op_sel_hi:[1,0,0]
	v_pk_fma_f32 v[94:95], v[46:47], s[12:13], v[52:53] op_sel_hi:[1,0,0]
	v_pk_fma_f32 v[92:93], v[44:45], s[12:13], v[52:53] op_sel_hi:[1,0,0]
	v_pk_fma_f32 v[90:91], v[42:43], s[12:13], v[52:53] op_sel_hi:[1,0,0]
	v_pk_fma_f32 v[88:89], v[40:41], s[12:13], v[52:53] op_sel_hi:[1,0,0]
	v_pk_fma_f32 v[86:87], v[38:39], s[12:13], v[52:53] op_sel_hi:[1,0,0]
	v_pk_fma_f32 v[84:85], v[36:37], s[12:13], v[52:53] op_sel_hi:[1,0,0]
	v_pk_fma_f32 v[82:83], v[34:35], s[12:13], v[52:53] op_sel_hi:[1,0,0]
	v_exp_f32_e32 v79, v18
	v_fmamk_f32 v18, v32, 0x3e0293ee, v52
	v_fmac_f32_e32 v52, 0x3e0293ee, v33
	s_addc_u32 s5, s97, s17
	v_exp_f32_e32 v80, v18
	v_exp_f32_e32 v81, v52
	s_add_u32 s16, s13, s4
	s_addc_u32 s17, s50, s5
	v_cndmask_b32_e64 v234, v53, 1.0, vcc
	v_lshl_add_u64 v[212:213], s[16:17], 0, v[50:51]
	v_mov_b64_e32 v[32:33], v[16:17]
	v_mov_b64_e32 v[48:49], v[16:17]
	v_mov_b64_e32 v[64:65], v[16:17]
	v_mov_b64_e32 v[30:31], v[14:15]
	v_mov_b64_e32 v[28:29], v[12:13]
	v_mov_b64_e32 v[26:27], v[10:11]
	v_mov_b64_e32 v[24:25], v[8:9]
	v_mov_b64_e32 v[22:23], v[6:7]
	v_mov_b64_e32 v[20:21], v[4:5]
	v_mov_b64_e32 v[18:19], v[2:3]
	v_mov_b64_e32 v[46:47], v[14:15]
	v_mov_b64_e32 v[44:45], v[12:13]
	v_mov_b64_e32 v[42:43], v[10:11]
	v_mov_b64_e32 v[40:41], v[8:9]
	v_mov_b64_e32 v[38:39], v[6:7]
	v_mov_b64_e32 v[36:37], v[4:5]
	v_mov_b64_e32 v[34:35], v[2:3]
	v_mov_b64_e32 v[62:63], v[14:15]
	v_mov_b64_e32 v[60:61], v[12:13]
	v_mov_b64_e32 v[58:59], v[10:11]
	v_mov_b64_e32 v[56:57], v[8:9]
	v_mov_b64_e32 v[54:55], v[6:7]
	v_mov_b64_e32 v[52:53], v[4:5]
	v_mov_b64_e32 v[50:51], v[2:3]
	s_waitcnt lgkmcnt(0)
	s_barrier
; #define SBAR() __builtin_amdgcn_sched_barrier(0)
; #define SLOAD(i, k0) do { const long to_ = (long)(k0) * ldk * 2; const char* vt_ = (const char*)Vh + to_; const char* kt_ = (const char*)Kh + to_; \
;     sr_[i].vs0 = *(const bf16x8*)(vt_ + toff); sr_[i].vs1 = *(const bf16x8*)(vt_ + h32 + toff); \
;     sr_[i].ks0 = *(const bf16x8*)(kt_ + toff); sr_[i].ks1 = *(const bf16x8*)(kt_ + h32 + toff); } while (0)
; __device__ __forceinline__ void finishSM(f32x16& p0, f32x16& p1, float alpha, float& l_reg, bf16x8& pa0, bf16x8& pa1, bf16x8& pa2, bf16x8& pa3) {
;   for (int r = 0; r < 16; ++r) p1[r] = __builtin_amdgcn_exp2f(p1[r]);
;   float ps = 0; for (int r = 0; r < 16; ++r) ps += p0[r]; for (int r = 0; r < 16; ++r) ps += p1[r];
;   { auto rr = __builtin_amdgcn_permlane32_swap(__float_as_uint(ps), __float_as_uint(ps), false, false);
;     ps = __uint_as_float(rr[0]) + __uint_as_float(rr[1]); }
;   l_reg = l_reg * alpha + ps;
;     ...
;   PK4(p0, 0, pa0); PK4(p0, 8, pa1); PK4(p1, 0, pa2); PK4(p1, 8, pa3);
;     ...
; }
; template <int MODE, int QMODE> ...
;     ...
;   for (int j = 1; j + 1 < NT; j += 2) {
;     SBAR(); qkt(pB0, pB1, (bf16*)((char*)K_lds + SHM_K), qr, r32, hi);
;     finishSM(pA0, pA1, alA, l_reg, pa0, pa1, pa2, pa3); SBAR();
;     SLOAD(SO, (j + SDEPTH) * KVBLK); SBAR();
;     PVSM(vb0, pB0, pB1, j * KVBLK, mnB, alB);
.LBB0_171:
	ds_read_b128 v[98:101], v218 offset:49152
	ds_read_b128 v[102:105], v218 offset:57344
	ds_read_b128 v[178:181], v223 offset:49152
	ds_read_b128 v[182:185], v223 offset:57344
	ds_read_b128 v[186:189], v227 offset:49152
	ds_read_b128 v[190:193], v227 offset:57344
	v_exp_f32_e32 v82, v82
	v_exp_f32_e32 v83, v83
	s_waitcnt lgkmcnt(5)
	v_mfma_f32_32x32x16_bf16 v[114:129], v[98:101], v[134:137], 0
	v_exp_f32_e32 v84, v84
	v_exp_f32_e32 v85, v85
	v_exp_f32_e32 v86, v86
	v_exp_f32_e32 v87, v87
	v_exp_f32_e32 v88, v88
	v_exp_f32_e32 v89, v89
	v_exp_f32_e32 v90, v90
	s_waitcnt lgkmcnt(4)
	v_mfma_f32_32x32x16_bf16 v[98:113], v[102:105], v[134:137], 0
	v_exp_f32_e32 v91, v91
	v_exp_f32_e32 v92, v92
	v_exp_f32_e32 v93, v93
	v_exp_f32_e32 v94, v94
	v_exp_f32_e32 v95, v95
	v_exp_f32_e32 v96, v96
	v_exp_f32_e32 v97, v97
	s_waitcnt lgkmcnt(2)
	v_mfma_f32_32x32x16_bf16 v[98:113], v[182:185], v[142:145], v[98:113]
	v_mfma_f32_32x32x16_bf16 v[114:129], v[178:181], v[142:145], v[114:129]
	ds_read_b128 v[178:181], v228 offset:49152
	ds_read_b128 v[194:197], v228 offset:57344
	ds_read_b128 v[198:201], v229 offset:49152
	ds_read_b128 v[202:205], v229 offset:57344
	ds_read_b128 v[206:209], v231 offset:49152
	ds_read_b128 v[238:241], v231 offset:57344
	ds_read_b128 v[242:245], v230 offset:49152
	ds_read_b128 v[246:249], v230 offset:57344
	ds_read_b128 v[182:185], v232 offset:49152
	ds_read_b128 v[250:253], v232 offset:57344
	s_waitcnt lgkmcnt(10)
	v_mfma_f32_32x32x16_bf16 v[98:113], v[190:193], v[130:133], v[98:113]
	v_mfma_f32_32x32x16_bf16 v[114:129], v[186:189], v[130:133], v[114:129]
	v_add_f32_e32 v186, 0, v66
	v_add_f32_e32 v186, v67, v186
	v_add_f32_e32 v186, v68, v186
	s_waitcnt lgkmcnt(8)
	v_mfma_f32_32x32x16_bf16 v[98:113], v[194:197], v[138:141], v[98:113]
	v_cvt_pk_bf16_f32 v194, v66, v67
	v_cvt_pk_bf16_f32 v195, v68, v69
	v_cvt_pk_bf16_f32 v196, v70, v71
	v_cvt_pk_bf16_f32 v197, v72, v73
	s_nop 0
	v_permlane32_swap_b32_e32 v194, v196
	v_mfma_f32_32x32x16_bf16 v[114:129], v[178:181], v[138:141], v[114:129]
	v_add_f32_e32 v178, v69, v186
	v_add_f32_e32 v178, v70, v178
	v_add_f32_e32 v178, v71, v178
	v_add_f32_e32 v178, v72, v178
	v_add_f32_e32 v178, v73, v178
	v_add_f32_e32 v178, v74, v178
	v_add_f32_e32 v178, v75, v178
	s_waitcnt lgkmcnt(6)
	v_mfma_f32_32x32x16_bf16 v[98:113], v[202:205], v[150:153], v[98:113]
	v_add_f32_e32 v178, v76, v178
	v_add_f32_e32 v178, v77, v178
	v_add_f32_e32 v178, v78, v178
	v_add_f32_e32 v178, v79, v178
	v_add_f32_e32 v178, v80, v178
	v_add_f32_e32 v178, v81, v178
	v_add_f32_e32 v178, v82, v178
	v_mfma_f32_32x32x16_bf16 v[114:129], v[198:201], v[150:153], v[114:129]
	v_add_f32_e32 v178, v83, v178
	v_add_f32_e32 v178, v84, v178
	v_add_f32_e32 v178, v85, v178
	v_add_f32_e32 v178, v86, v178
	v_add_f32_e32 v178, v87, v178
	v_add_f32_e32 v178, v88, v178
	v_add_f32_e32 v178, v89, v178
	s_waitcnt lgkmcnt(4)
	v_mfma_f32_32x32x16_bf16 v[98:113], v[238:241], v[158:161], v[98:113]
	v_add_f32_e32 v178, v90, v178
	v_add_f32_e32 v178, v91, v178
	v_add_f32_e32 v178, v92, v178
	v_add_f32_e32 v178, v93, v178
	v_add_f32_e32 v178, v94, v178
	v_add_f32_e32 v178, v95, v178
	v_add_f32_e32 v178, v96, v178
	v_mfma_f32_32x32x16_bf16 v[114:129], v[206:209], v[158:161], v[114:129]
	v_add_f32_e32 v233, v97, v178
	v_mov_b32_e32 v235, v233
	s_nop 1
	v_permlane32_swap_b32_e32 v233, v235
	v_cvt_pk_bf16_f32 v198, v74, v75
	v_cvt_pk_bf16_f32 v199, v76, v77
	v_cvt_pk_bf16_f32 v200, v78, v79
	s_waitcnt lgkmcnt(2)
	v_mfma_f32_32x32x16_bf16 v[98:113], v[246:249], v[146:149], v[98:113]
	v_cvt_pk_bf16_f32 v201, v80, v81
	v_cvt_pk_bf16_f32 v206, v82, v83
	v_cvt_pk_bf16_f32 v207, v84, v85
	v_cvt_pk_bf16_f32 v208, v86, v87
	v_cvt_pk_bf16_f32 v209, v88, v89
	v_cvt_pk_bf16_f32 v202, v90, v91
	v_cvt_pk_bf16_f32 v203, v92, v93
	v_mfma_f32_32x32x16_bf16 v[114:129], v[242:245], v[146:149], v[114:129]
	v_cvt_pk_bf16_f32 v204, v94, v95
	v_cvt_pk_bf16_f32 v205, v96, v97
	v_permlane32_swap_b32_e32 v195, v197
	v_permlane32_swap_b32_e32 v198, v200
	v_permlane32_swap_b32_e32 v199, v201
	s_waitcnt lgkmcnt(0)
	v_mfma_f32_32x32x16_bf16 v[98:113], v[250:253], v[154:157], v[98:113]
	v_permlane32_swap_b32_e32 v206, v208
	v_permlane32_swap_b32_e32 v207, v209
	v_permlane32_swap_b32_e32 v202, v204
	v_permlane32_swap_b32_e32 v203, v205
	v_mfma_f32_32x32x16_bf16 v[114:129], v[182:185], v[154:157], v[114:129]
	v_add_co_u32_e32 v66, vcc, s67, v212
	s_nop 1
	v_addc_co_u32_e32 v67, vcc, -1, v213, vcc
	v_add_co_u32_e32 v68, vcc, s80, v212
	s_nop 1
	v_addc_co_u32_e32 v69, vcc, -1, v213, vcc
	global_load_dwordx4 v[178:181], v[66:67], off
	global_load_dwordx4 v[182:185], v[66:67], off offset:-512
	global_load_dwordx4 v[190:193], v[68:69], off
	global_load_dwordx4 v[186:189], v[68:69], off offset:-512
	ds_read_b64_tr_b16 v[66:67], v217 offset:0
	ds_read_b64_tr_b16 v[68:69], v217 offset:0x800
	ds_read_b64_tr_b16 v[70:71], v217 offset:0x1000
	ds_read_b64_tr_b16 v[72:73], v217 offset:0x1800
	ds_read_b64_tr_b16 v[74:75], v217 offset:0x2000
	ds_read_b64_tr_b16 v[76:77], v217 offset:0x2800
	ds_read_b64_tr_b16 v[78:79], v217 offset:0x3000
	ds_read_b64_tr_b16 v[80:81], v217 offset:0x3800
	s_waitcnt lgkmcnt(0)
	s_nop 0
	v_mfma_f32_32x32x16_bf16 v[50:65], v[194:197], v[66:69], v[50:65]
	v_max_f32_e32 v66, v115, v115
	v_max_f32_e32 v67, v114, v114
	v_max_f32_e32 v66, v67, v66
	v_max3_f32 v66, v66, v116, v117
	v_max3_f32 v66, v66, v118, v119
	v_max3_f32 v66, v66, v120, v121
	v_max3_f32 v66, v66, v122, v123
	v_mfma_f32_32x32x16_bf16 v[50:65], v[198:201], v[70:73], v[50:65]
	v_max3_f32 v66, v66, v124, v125
	v_max3_f32 v68, v66, v126, v127
	ds_read_b64_tr_b16 v[66:67], v217 offset:0x200
	v_max3_f32 v86, v68, v128, v129
	ds_read_b64_tr_b16 v[68:69], v217 offset:0xa00
	ds_read_b64_tr_b16 v[70:71], v217 offset:0x1200
	ds_read_b64_tr_b16 v[72:73], v217 offset:0x1a00
	v_mfma_f32_32x32x16_bf16 v[50:65], v[206:209], v[74:77], v[50:65]
	ds_read_b64_tr_b16 v[74:75], v217 offset:0x2200
	ds_read_b64_tr_b16 v[76:77], v217 offset:0x2a00
	ds_read_b64_tr_b16 v[82:83], v217 offset:0x3200
	ds_read_b64_tr_b16 v[84:85], v217 offset:0x3a00
	s_waitcnt lgkmcnt(0)
; #define SBAR() __builtin_amdgcn_sched_barrier(0)
; #define SLOAD(i, k0) do { const long to_ = (long)(k0) * ldk * 2; const char* vt_ = (const char*)Vh + to_; const char* kt_ = (const char*)Kh + to_; \
;     sr_[i].vs0 = *(const bf16x8*)(vt_ + toff); sr_[i].vs1 = *(const bf16x8*)(vt_ + h32 + toff); \
;     sr_[i].ks0 = *(const bf16x8*)(kt_ + toff); sr_[i].ks1 = *(const bf16x8*)(kt_ + h32 + toff); } while (0)
; #define SWAIT() do { if constexpr (SDEPTH == 2) asm volatile("s_waitcnt vmcnt(4)" ::: "memory"); else asm volatile("s_waitcnt vmcnt(0)" ::: "memory"); } while (0)
; #define RESC(a) do { if (__any((a) < 1.f)) { if (hi == 0) al_l[r32] = (a); asm volatile("s_waitcnt lgkmcnt(0)" ::: "memory"); \
;     for (int d = 0; d < 4; ++d) for (int r = 0; r < 16; ++r) o[d][r] *= al_l[crow(r, hi)]; } } while (0)
; #define MASK(P0, P1, k0) do { if constexpr (MODE == 1) { const int k0_ = (k0); \
;     if ((k0_ + 63 - qw0 > 128) || (k0_ - (qw0 + 31) < -128)) maskwin(P0, P1, k0_ - (qw0 + r32) + 128 + 4 * hi); } } while (0)
; template <int MODE, int QMODE> ...
;     ...
;   if (wid >= 4) __builtin_amdgcn_s_setprio(1);
;   f32x16 pA0, pA1, pB0, pB1; float mnA, mnB, alA, alB; bf16x8 pa0, pa1, pa2, pa3; const int NT = seq / KVBLK;
;   constexpr int SE = 0, SO = SDEPTH - 1;
;   SLOAD(SE, 0); asm volatile("s_waitcnt vmcnt(0)" ::: "memory"); SWRITE(0, SE); __syncthreads();
;   qkt(pA0, pA1, K_lds, qr, r32, hi); MASK(pA0, pA1, 0); partialSM(pA0, pA1, m_reg, mnA, alA);
;   SLOAD(SO, KVBLK); if constexpr (SDEPTH == 2) { if (2 < NT) SLOAD(SE, 2 * KVBLK); }
;   SWAIT(); SWRITE(1, SO); __syncthreads();
;   for (int j = 1; j + 1 < NT; j += 2) {
;     SBAR(); qkt(pB0, pB1, (bf16*)((char*)K_lds + SHM_K), qr, r32, hi);
;     finishSM(pA0, pA1, alA, l_reg, pa0, pa1, pa2, pa3); SBAR();
;     SLOAD(SO, (j + SDEPTH) * KVBLK); SBAR();
;     PVSM(vb0, pB0, pB1, j * KVBLK, mnB, alB);
;     __syncthreads(); SWAIT(); SWRITE(0, SE);
;     RESC(alB); __syncthreads();
	v_mfma_f32_32x32x16_bf16 v[50:65], v[202:205], v[78:81], v[50:65]
	v_mfma_f32_32x32x16_bf16 v[34:49], v[194:197], v[66:69], v[34:49]
	v_max3_f32 v78, v86, v98, v99
	v_max3_f32 v78, v78, v100, v101
	v_max3_f32 v78, v78, v102, v103
	v_max3_f32 v78, v78, v104, v105
	v_max3_f32 v78, v78, v106, v107
	v_max3_f32 v78, v78, v108, v109
	v_max3_f32 v66, v78, v110, v111
	v_max3_f32 v66, v66, v112, v113
	v_mfma_f32_32x32x16_bf16 v[34:49], v[198:201], v[70:73], v[34:49]
	v_mov_b32_e32 v67, v66
	s_nop 1
	v_permlane32_swap_b32_e32 v66, v67
	v_max_f32_e32 v67, v67, v67
	v_max_f32_e32 v66, v66, v66
	v_max_f32_e32 v66, v66, v67
	v_sub_f32_e32 v67, v66, v237
	v_cmp_ge_f32_e32 vcc, s62, v67
	v_max_f32_e32 v67, v237, v237
	v_max_f32_e32 v66, v67, v66
	v_sub_f32_e32 v67, v237, v66
	v_mfma_f32_32x32x16_bf16 v[34:49], v[206:209], v[74:77], v[34:49]
	v_mul_f32_e32 v67, 0x3e0293ee, v67
	v_exp_f32_e32 v67, v67
	s_cmp_eq_u64 vcc, exec
	s_cselect_b64 vcc, -1, 0
	v_cndmask_b32_e32 v236, v66, v237, vcc
	v_cndmask_b32_e64 v238, v67, 1.0, vcc
	ds_read_b64_tr_b16 v[66:67], v217 offset:0x400
	ds_read_b64_tr_b16 v[68:69], v217 offset:0xc00
	v_mfma_f32_32x32x16_bf16 v[34:49], v[202:205], v[82:85], v[34:49]
	ds_read_b64_tr_b16 v[82:83], v217 offset:0x1400
	ds_read_b64_tr_b16 v[84:85], v217 offset:0x1c00
	ds_read_b64_tr_b16 v[240:241], v217 offset:0x2400
	ds_read_b64_tr_b16 v[242:243], v217 offset:0x2c00
	ds_read_b64_tr_b16 v[244:245], v217 offset:0x3400
	ds_read_b64_tr_b16 v[246:247], v217 offset:0x3c00
	s_waitcnt lgkmcnt(0)
	v_mfma_f32_32x32x16_bf16 v[18:33], v[194:197], v[66:69], v[18:33]
	v_mul_f32_e32 v248, 0xbe0293ee, v236
	v_fma_f32 v80, v128, s12, v248
	v_fma_f32 v81, v129, s12, v248
	v_fma_f32 v78, v126, s12, v248
	v_fma_f32 v79, v127, s12, v248
	v_pk_fma_f32 v[76:77], v[124:125], s[12:13], v[248:249] op_sel_hi:[1,0,0]
	v_pk_fma_f32 v[74:75], v[122:123], s[12:13], v[248:249] op_sel_hi:[1,0,0]
	v_pk_fma_f32 v[72:73], v[120:121], s[12:13], v[248:249] op_sel_hi:[1,0,0]
	v_pk_fma_f32 v[70:71], v[118:119], s[12:13], v[248:249] op_sel_hi:[1,0,0]
	v_mfma_f32_32x32x16_bf16 v[18:33], v[198:201], v[82:85], v[18:33]
	v_fma_f32 v68, v116, s12, v248
	v_fma_f32 v69, v117, s12, v248
	v_fma_f32 v66, v114, s12, v248
	v_fma_f32 v67, v115, s12, v248
	v_fma_f32 v96, v112, s12, v248
	v_fma_f32 v97, v113, s12, v248
	v_pk_fma_f32 v[94:95], v[110:111], s[12:13], v[248:249] op_sel_hi:[1,0,0]
	v_pk_fma_f32 v[92:93], v[108:109], s[12:13], v[248:249] op_sel_hi:[1,0,0]
	v_pk_fma_f32 v[90:91], v[106:107], s[12:13], v[248:249] op_sel_hi:[1,0,0]
	v_pk_fma_f32 v[88:89], v[104:105], s[12:13], v[248:249] op_sel_hi:[1,0,0]
	v_mfma_f32_32x32x16_bf16 v[18:33], v[206:209], v[240:243], v[18:33]
	v_fma_f32 v86, v102, s12, v248
	v_fma_f32 v87, v103, s12, v248
	v_fma_f32 v84, v100, s12, v248
	v_fma_f32 v85, v101, s12, v248
	v_fma_f32 v82, v98, s12, v248
	v_fma_f32 v83, v99, s12, v248
	ds_read_b64_tr_b16 v[98:99], v217 offset:0x600
	ds_read_b64_tr_b16 v[100:101], v217 offset:0xe00
	ds_read_b64_tr_b16 v[102:103], v217 offset:0x1600
	ds_read_b64_tr_b16 v[104:105], v217 offset:0x1e00
	v_mfma_f32_32x32x16_bf16 v[18:33], v[202:205], v[244:247], v[18:33]
	ds_read_b64_tr_b16 v[108:109], v217 offset:0x2600
	ds_read_b64_tr_b16 v[110:111], v217 offset:0x2e00
	ds_read_b64_tr_b16 v[114:115], v217 offset:0x3600
	ds_read_b64_tr_b16 v[116:117], v217 offset:0x3e00
	s_waitcnt lgkmcnt(0)
	v_mfma_f32_32x32x16_bf16 v[2:17], v[194:197], v[98:101], v[2:17]
	v_exp_f32_e32 v98, v66
	v_exp_f32_e32 v99, v67
	v_exp_f32_e32 v100, v68
	v_exp_f32_e32 v101, v69
	v_exp_f32_e32 v106, v74
	v_exp_f32_e32 v107, v75
	v_exp_f32_e32 v112, v80
	v_mfma_f32_32x32x16_bf16 v[2:17], v[198:201], v[102:105], v[2:17]
	v_exp_f32_e32 v102, v70
	v_exp_f32_e32 v103, v71
	v_exp_f32_e32 v104, v72
	v_exp_f32_e32 v105, v73
	v_exp_f32_e32 v113, v81
	v_mfma_f32_32x32x16_bf16 v[2:17], v[206:209], v[108:111], v[2:17]
	v_exp_f32_e32 v108, v76
	v_exp_f32_e32 v109, v77
	v_exp_f32_e32 v110, v78
	v_exp_f32_e32 v111, v79
	v_mfma_f32_32x32x16_bf16 v[2:17], v[202:205], v[114:117], v[2:17]
	s_waitcnt vmcnt(4)
	v_cmp_gt_f32_e32 vcc, 1.0, v238
	ds_write_b128 v219, v[174:177] offset:32768
	ds_write_b128 v220, v[162:165] offset:32768
	s_cbranch_vccz .LBB0_175
	s_and_saveexec_b64 s[16:17], s[2:3]
	ds_write_b32 v214, v238 offset:128
	s_or_b64 exec, exec, s[16:17]
	s_waitcnt lgkmcnt(0)
	v_add_u32_e32 v78, s95, v210
	ds_read_b128 v[66:69], v78 offset:224
	ds_read_b128 v[70:73], v78 offset:192
	ds_read_b128 v[74:77], v78 offset:160
	ds_read_b128 v[78:81], v78 offset:128
	s_waitcnt lgkmcnt(3)
	v_pk_mul_f32 v[62:63], v[62:63], v[66:67]
	s_waitcnt lgkmcnt(2)
	v_pk_mul_f32 v[58:59], v[58:59], v[70:71]
	s_waitcnt lgkmcnt(1)
	v_pk_mul_f32 v[54:55], v[54:55], v[74:75]
	v_pk_mul_f32 v[64:65], v[64:65], v[68:69]
	v_pk_mul_f32 v[60:61], v[60:61], v[72:73]
	v_pk_mul_f32 v[56:57], v[56:57], v[76:77]
	s_waitcnt lgkmcnt(0)
	v_pk_mul_f32 v[52:53], v[52:53], v[80:81]
	v_pk_mul_f32 v[50:51], v[50:51], v[78:79]
	v_pk_mul_f32 v[46:47], v[46:47], v[66:67]
	v_pk_mul_f32 v[42:43], v[42:43], v[70:71]
	v_pk_mul_f32 v[38:39], v[38:39], v[74:75]
	v_pk_mul_f32 v[48:49], v[48:49], v[68:69]
	v_pk_mul_f32 v[44:45], v[44:45], v[72:73]
	v_pk_mul_f32 v[40:41], v[40:41], v[76:77]
	v_pk_mul_f32 v[36:37], v[36:37], v[80:81]
	v_pk_mul_f32 v[34:35], v[34:35], v[78:79]
	v_pk_mul_f32 v[30:31], v[30:31], v[66:67]
	v_pk_mul_f32 v[26:27], v[26:27], v[70:71]
	v_pk_mul_f32 v[22:23], v[22:23], v[74:75]
	v_pk_mul_f32 v[32:33], v[32:33], v[68:69]
	v_pk_mul_f32 v[28:29], v[28:29], v[72:73]
	v_pk_mul_f32 v[24:25], v[24:25], v[76:77]
	v_pk_mul_f32 v[20:21], v[20:21], v[80:81]
	v_pk_mul_f32 v[18:19], v[18:19], v[78:79]
	v_pk_mul_f32 v[14:15], v[14:15], v[66:67]
	v_pk_mul_f32 v[10:11], v[10:11], v[70:71]
	v_pk_mul_f32 v[6:7], v[6:7], v[74:75]
	v_pk_mul_f32 v[16:17], v[16:17], v[68:69]
	v_pk_mul_f32 v[12:13], v[12:13], v[72:73]
	v_pk_mul_f32 v[8:9], v[8:9], v[76:77]
	v_pk_mul_f32 v[4:5], v[4:5], v[80:81]
	v_pk_mul_f32 v[2:3], v[2:3], v[78:79]
; #define SBAR() __builtin_amdgcn_sched_barrier(0)
; #define SLOAD(i, k0) do { const long to_ = (long)(k0) * ldk * 2; const char* vt_ = (const char*)Vh + to_; const char* kt_ = (const char*)Kh + to_; \
;     sr_[i].vs0 = *(const bf16x8*)(vt_ + toff); sr_[i].vs1 = *(const bf16x8*)(vt_ + h32 + toff); \
;     sr_[i].ks0 = *(const bf16x8*)(kt_ + toff); sr_[i].ks1 = *(const bf16x8*)(kt_ + h32 + toff); } while (0)
; #define RESC(a) do { if (__any((a) < 1.f)) { if (hi == 0) al_l[r32] = (a); asm volatile("s_waitcnt lgkmcnt(0)" ::: "memory"); \
;     for (int d = 0; d < 4; ++d) for (int r = 0; r < 16; ++r) o[d][r] *= al_l[crow(r, hi)]; } } while (0)
; __device__ __forceinline__ void finishSM(f32x16& p0, f32x16& p1, float alpha, float& l_reg, bf16x8& pa0, bf16x8& pa1, bf16x8& pa2, bf16x8& pa3) {
;   for (int r = 0; r < 16; ++r) p1[r] = __builtin_amdgcn_exp2f(p1[r]);
;   float ps = 0; for (int r = 0; r < 16; ++r) ps += p0[r]; for (int r = 0; r < 16; ++r) ps += p1[r];
;   { auto rr = __builtin_amdgcn_permlane32_swap(__float_as_uint(ps), __float_as_uint(ps), false, false);
;     ps = __uint_as_float(rr[0]) + __uint_as_float(rr[1]); }
;   l_reg = l_reg * alpha + ps;
;     ...
;   PK4(p0, 0, pa0); PK4(p0, 8, pa1); PK4(p1, 0, pa2); PK4(p1, 8, pa3);
;     ...
; }
; template <int MODE, int QMODE> ...
;     ...
;     RESC(alB); __syncthreads();
;     SBAR(); qkt(pA0, pA1, K_lds, qr, r32, hi);
;     finishSM(pB0, pB1, alB, l_reg, pa0, pa1, pa2, pa3); SBAR();
;     if (SDEPTH == 1 || j + 3 < NT) SLOAD(SE, (j + 1 + SDEPTH) * KVBLK); SBAR();
.LBB0_175:
	s_waitcnt lgkmcnt(0)
	s_barrier
	ds_write_b128 v221, v[166:169]
	ds_write_b128 v222, v[170:173]
	ds_read_b128 v[66:69], v218 offset:32768
	ds_read_b128 v[70:73], v218 offset:40960
	ds_read_b128 v[194:197], v223 offset:32768
	ds_read_b128 v[198:201], v223 offset:40960
	ds_read_b128 v[162:165], v227 offset:32768
	ds_read_b128 v[166:169], v227 offset:40960
	ds_read_b128 v[170:173], v228 offset:32768
	ds_read_b128 v[174:177], v228 offset:40960
	v_exp_f32_e32 v82, v82
	v_exp_f32_e32 v83, v83
	s_waitcnt lgkmcnt(7)
	v_mfma_f32_32x32x16_bf16 v[114:129], v[66:69], v[134:137], 0
	v_exp_f32_e32 v84, v84
	v_exp_f32_e32 v85, v85
	v_exp_f32_e32 v86, v86
	v_exp_f32_e32 v87, v87
	v_exp_f32_e32 v88, v88
	v_exp_f32_e32 v89, v89
	v_exp_f32_e32 v90, v90
	s_waitcnt lgkmcnt(6)
	v_mfma_f32_32x32x16_bf16 v[66:81], v[70:73], v[134:137], 0
	v_exp_f32_e32 v91, v91
	v_exp_f32_e32 v92, v92
	v_exp_f32_e32 v93, v93
	v_exp_f32_e32 v94, v94
	v_exp_f32_e32 v95, v95
	v_exp_f32_e32 v96, v96
	v_exp_f32_e32 v97, v97
	ds_read_b128 v[242:245], v229 offset:32768
	ds_read_b128 v[246:249], v229 offset:40960
	ds_read_b128 v[250:253], v231 offset:32768
	s_waitcnt lgkmcnt(8)
	v_mfma_f32_32x32x16_bf16 v[114:129], v[194:197], v[142:145], v[114:129]
	s_waitcnt lgkmcnt(7)
	v_mfma_f32_32x32x16_bf16 v[66:81], v[198:201], v[142:145], v[66:81]
	ds_read_b128 v[194:197], v231 offset:40960
	ds_read_b128 v[198:201], v230 offset:32768
	s_waitcnt lgkmcnt(8)
	v_mfma_f32_32x32x16_bf16 v[114:129], v[162:165], v[130:133], v[114:129]
	s_waitcnt lgkmcnt(7)
	v_mfma_f32_32x32x16_bf16 v[66:81], v[166:169], v[130:133], v[66:81]
	ds_read_b128 v[162:165], v230 offset:40960
	ds_read_b128 v[166:169], v232 offset:32768
	s_waitcnt lgkmcnt(8)
	v_mfma_f32_32x32x16_bf16 v[114:129], v[170:173], v[138:141], v[114:129]
	s_waitcnt lgkmcnt(7)
	v_mfma_f32_32x32x16_bf16 v[66:81], v[174:177], v[138:141], v[66:81]
	ds_read_b128 v[170:173], v232 offset:40960
	s_waitcnt lgkmcnt(7)
	v_mfma_f32_32x32x16_bf16 v[114:129], v[242:245], v[150:153], v[114:129]
	s_waitcnt lgkmcnt(6)
	v_mfma_f32_32x32x16_bf16 v[66:81], v[246:249], v[150:153], v[66:81]
	s_waitcnt lgkmcnt(5)
	v_mfma_f32_32x32x16_bf16 v[114:129], v[250:253], v[158:161], v[114:129]
	s_waitcnt lgkmcnt(4)
	v_mfma_f32_32x32x16_bf16 v[66:81], v[194:197], v[158:161], v[66:81]
	s_waitcnt lgkmcnt(3)
	v_mfma_f32_32x32x16_bf16 v[114:129], v[198:201], v[146:149], v[114:129]
	s_waitcnt lgkmcnt(2)
	v_mfma_f32_32x32x16_bf16 v[66:81], v[162:165], v[146:149], v[66:81]
	v_cvt_pk_bf16_f32 v206, v98, v99
	v_cvt_pk_bf16_f32 v207, v100, v101
	v_cvt_pk_bf16_f32 v208, v102, v103
	v_cvt_pk_bf16_f32 v209, v104, v105
	s_nop 0
	v_permlane32_swap_b32_e32 v206, v208
	s_waitcnt lgkmcnt(1)
	v_mfma_f32_32x32x16_bf16 v[114:129], v[166:169], v[154:157], v[114:129]
	v_add_f32_e32 v194, 0, v98
	v_add_f32_e32 v194, v99, v194
	v_add_f32_e32 v194, v100, v194
	v_add_f32_e32 v194, v101, v194
	v_add_f32_e32 v194, v102, v194
	v_add_f32_e32 v194, v103, v194
	v_add_f32_e32 v194, v104, v194
	v_add_f32_e32 v194, v105, v194
	v_add_f32_e32 v194, v106, v194
	v_add_f32_e32 v194, v107, v194
	v_add_f32_e32 v194, v108, v194
	v_add_f32_e32 v194, v109, v194
	v_add_f32_e32 v194, v110, v194
	v_add_f32_e32 v194, v111, v194
	v_add_f32_e32 v194, v112, v194
	v_add_f32_e32 v194, v113, v194
	v_add_f32_e32 v194, v82, v194
	v_add_f32_e32 v194, v83, v194
	v_add_f32_e32 v194, v84, v194
	v_add_f32_e32 v194, v85, v194
	v_add_f32_e32 v194, v86, v194
	v_add_f32_e32 v194, v87, v194
	v_add_f32_e32 v194, v88, v194
	v_add_f32_e32 v194, v89, v194
	v_add_f32_e32 v194, v90, v194
	v_add_f32_e32 v194, v91, v194
	s_waitcnt lgkmcnt(0)
	v_mfma_f32_32x32x16_bf16 v[66:81], v[170:173], v[154:157], v[66:81]
	v_add_f32_e32 v194, v92, v194
	v_add_f32_e32 v194, v93, v194
	v_add_f32_e32 v194, v94, v194
	v_add_f32_e32 v194, v95, v194
	v_add_f32_e32 v194, v96, v194
	v_add_f32_e32 v239, v97, v194
	v_mov_b32_e32 v240, v239
	v_cvt_pk_bf16_f32 v198, v106, v107
	v_cvt_pk_bf16_f32 v199, v108, v109
	v_cvt_pk_bf16_f32 v200, v110, v111
	v_cvt_pk_bf16_f32 v201, v112, v113
	v_cvt_pk_bf16_f32 v202, v82, v83
	v_cvt_pk_bf16_f32 v203, v84, v85
	v_cvt_pk_bf16_f32 v204, v86, v87
	v_cvt_pk_bf16_f32 v205, v88, v89
	v_cvt_pk_bf16_f32 v194, v90, v91
	v_cvt_pk_bf16_f32 v195, v92, v93
	v_cvt_pk_bf16_f32 v196, v94, v95
	v_cvt_pk_bf16_f32 v197, v96, v97
	s_nop 1
	v_permlane32_swap_b32_e32 v239, v240
	v_permlane32_swap_b32_e32 v207, v209
	v_permlane32_swap_b32_e32 v198, v200
	v_permlane32_swap_b32_e32 v199, v201
	v_permlane32_swap_b32_e32 v202, v204
	v_permlane32_swap_b32_e32 v203, v205
	v_permlane32_swap_b32_e32 v194, v196
	v_permlane32_swap_b32_e32 v195, v197
	s_add_i32 s96, s96, 2
	s_cmp_ge_u32 s96, s94
	s_cselect_b64 s[16:17], -1, 0
	s_and_b64 vcc, exec, s[16:17]
	s_cbranch_vccnz .LBB0_177
	v_add_co_u32_e32 v82, vcc, 0xfffd0000, v212
	s_nop 1
	v_addc_co_u32_e32 v83, vcc, -1, v213, vcc
	global_load_dwordx4 v[166:169], v[82:83], off
	global_load_dwordx4 v[174:177], v[82:83], off offset:-512
	global_load_dwordx4 v[170:173], v[212:213], off
	global_load_dwordx4 v[162:165], v[212:213], off offset:-512
; #define SWAIT() do { if constexpr (SDEPTH == 2) asm volatile("s_waitcnt vmcnt(4)" ::: "memory"); else asm volatile("s_waitcnt vmcnt(0)" ::: "memory"); } while (0)
; template <int MODE, int QMODE> ...
;     ...
;     PVSM(vb0 + (int)SHM_V, pA0, pA1, (j + 1) * KVBLK, mnA, alA);
;     __syncthreads(); SWAIT(); SWRITE(1, SO);
.LBB0_177:
	ds_read_b64_tr_b16 v[82:83], v216 offset:0
	ds_read_b64_tr_b16 v[84:85], v216 offset:0x800
	ds_read_b64_tr_b16 v[86:87], v216 offset:0x1000
	ds_read_b64_tr_b16 v[88:89], v216 offset:0x1800
	ds_read_b64_tr_b16 v[90:91], v216 offset:0x2000
	ds_read_b64_tr_b16 v[92:93], v216 offset:0x2800
	ds_read_b64_tr_b16 v[94:95], v216 offset:0x3000
	ds_read_b64_tr_b16 v[96:97], v216 offset:0x3800
	s_waitcnt lgkmcnt(0)
	s_nop 0
	v_mfma_f32_32x32x16_bf16 v[50:65], v[206:209], v[82:85], v[50:65]
	v_max_f32_e32 v82, v115, v115
	v_max_f32_e32 v83, v114, v114
	v_max_f32_e32 v82, v83, v82
	v_max3_f32 v82, v82, v116, v117
	v_max3_f32 v82, v82, v118, v119
	v_max3_f32 v82, v82, v120, v121
	v_max3_f32 v82, v82, v122, v123
	v_mfma_f32_32x32x16_bf16 v[50:65], v[198:201], v[86:89], v[50:65]
	v_max3_f32 v82, v82, v124, v125
	v_max3_f32 v84, v82, v126, v127
	ds_read_b64_tr_b16 v[82:83], v216 offset:0x200
	v_max3_f32 v102, v84, v128, v129
	ds_read_b64_tr_b16 v[84:85], v216 offset:0xa00
	ds_read_b64_tr_b16 v[86:87], v216 offset:0x1200
	ds_read_b64_tr_b16 v[88:89], v216 offset:0x1a00
	v_mfma_f32_32x32x16_bf16 v[50:65], v[202:205], v[90:93], v[50:65]
	ds_read_b64_tr_b16 v[90:91], v216 offset:0x2200
	ds_read_b64_tr_b16 v[92:93], v216 offset:0x2a00
	ds_read_b64_tr_b16 v[98:99], v216 offset:0x3200
	ds_read_b64_tr_b16 v[100:101], v216 offset:0x3a00
	s_waitcnt lgkmcnt(0)
	v_mfma_f32_32x32x16_bf16 v[50:65], v[194:197], v[94:97], v[50:65]
	v_max3_f32 v94, v102, v66, v67
	v_mfma_f32_32x32x16_bf16 v[34:49], v[206:209], v[82:85], v[34:49]
	v_max3_f32 v94, v94, v68, v69
	v_max3_f32 v94, v94, v70, v71
	v_max3_f32 v94, v94, v72, v73
	v_max3_f32 v94, v94, v74, v75
	v_max3_f32 v94, v94, v76, v77
	v_max3_f32 v82, v94, v78, v79
	v_max3_f32 v82, v82, v80, v81
	v_mov_b32_e32 v83, v82
	v_mfma_f32_32x32x16_bf16 v[34:49], v[198:201], v[86:89], v[34:49]
	s_nop 0
	v_permlane32_swap_b32_e32 v82, v83
	v_max_f32_e32 v83, v83, v83
	v_max_f32_e32 v82, v82, v82
	v_max_f32_e32 v82, v82, v83
	v_sub_f32_e32 v83, v82, v236
	v_cmp_ge_f32_e32 vcc, s62, v83
	v_max_f32_e32 v83, v236, v236
	v_max_f32_e32 v82, v83, v82
	v_sub_f32_e32 v83, v236, v82
	v_mul_f32_e32 v83, 0x3e0293ee, v83
	v_mfma_f32_32x32x16_bf16 v[34:49], v[202:205], v[90:93], v[34:49]
	v_exp_f32_e32 v83, v83
	s_cmp_eq_u64 vcc, exec
	s_cselect_b64 vcc, -1, 0
	v_cndmask_b32_e32 v237, v82, v236, vcc
	v_cndmask_b32_e64 v236, v83, 1.0, vcc
	ds_read_b64_tr_b16 v[82:83], v216 offset:0x400
	ds_read_b64_tr_b16 v[84:85], v216 offset:0xc00
	ds_read_b64_tr_b16 v[86:87], v216 offset:0x1400
	v_mfma_f32_32x32x16_bf16 v[34:49], v[194:197], v[98:101], v[34:49]
	ds_read_b64_tr_b16 v[88:89], v216 offset:0x1c00
	ds_read_b64_tr_b16 v[242:243], v216 offset:0x2400
	ds_read_b64_tr_b16 v[244:245], v216 offset:0x2c00
	ds_read_b64_tr_b16 v[246:247], v216 offset:0x3400
	ds_read_b64_tr_b16 v[248:249], v216 offset:0x3c00
	s_waitcnt lgkmcnt(0)
	v_mfma_f32_32x32x16_bf16 v[18:33], v[206:209], v[82:85], v[18:33]
	v_mul_f32_e32 v250, 0xbe0293ee, v237
	v_fma_f32 v112, v128, s12, v250
	v_fma_f32 v113, v129, s12, v250
	v_fma_f32 v110, v126, s12, v250
	v_fma_f32 v111, v127, s12, v250
	v_pk_fma_f32 v[108:109], v[124:125], s[12:13], v[250:251] op_sel_hi:[1,0,0]
	v_pk_fma_f32 v[106:107], v[122:123], s[12:13], v[250:251] op_sel_hi:[1,0,0]
	v_pk_fma_f32 v[104:105], v[120:121], s[12:13], v[250:251] op_sel_hi:[1,0,0]
	v_pk_fma_f32 v[102:103], v[118:119], s[12:13], v[250:251] op_sel_hi:[1,0,0]
	v_mfma_f32_32x32x16_bf16 v[18:33], v[198:201], v[86:89], v[18:33]
	v_fma_f32 v100, v116, s12, v250
	v_fma_f32 v101, v117, s12, v250
	v_fma_f32 v98, v114, s12, v250
	v_fma_f32 v99, v115, s12, v250
	v_fma_f32 v96, v80, s12, v250
	v_fma_f32 v97, v81, s12, v250
	v_pk_fma_f32 v[94:95], v[78:79], s[12:13], v[250:251] op_sel_hi:[1,0,0]
	v_pk_fma_f32 v[92:93], v[76:77], s[12:13], v[250:251] op_sel_hi:[1,0,0]
	v_pk_fma_f32 v[90:91], v[74:75], s[12:13], v[250:251] op_sel_hi:[1,0,0]
	v_pk_fma_f32 v[88:89], v[72:73], s[12:13], v[250:251] op_sel_hi:[1,0,0]
	v_mfma_f32_32x32x16_bf16 v[18:33], v[202:205], v[242:245], v[18:33]
	v_fma_f32 v86, v70, s12, v250
	v_fma_f32 v87, v71, s12, v250
	v_fma_f32 v84, v68, s12, v250
	v_fma_f32 v85, v69, s12, v250
	v_fma_f32 v82, v66, s12, v250
	v_fma_f32 v83, v67, s12, v250
	ds_read_b64_tr_b16 v[66:67], v216 offset:0x600
	ds_read_b64_tr_b16 v[68:69], v216 offset:0xe00
	ds_read_b64_tr_b16 v[70:71], v216 offset:0x1600
	ds_read_b64_tr_b16 v[72:73], v216 offset:0x1e00
	v_mfma_f32_32x32x16_bf16 v[18:33], v[194:197], v[246:249], v[18:33]
	ds_read_b64_tr_b16 v[76:77], v216 offset:0x2600
	ds_read_b64_tr_b16 v[78:79], v216 offset:0x2e00
	ds_read_b64_tr_b16 v[114:115], v216 offset:0x3600
	ds_read_b64_tr_b16 v[116:117], v216 offset:0x3e00
	s_waitcnt lgkmcnt(0)
	v_mfma_f32_32x32x16_bf16 v[2:17], v[206:209], v[66:69], v[2:17]
	v_exp_f32_e32 v66, v98
	v_exp_f32_e32 v67, v99
	v_exp_f32_e32 v68, v100
	v_exp_f32_e32 v69, v101
	v_exp_f32_e32 v74, v106
	v_exp_f32_e32 v75, v107
	v_exp_f32_e32 v80, v112
	v_mfma_f32_32x32x16_bf16 v[2:17], v[198:201], v[70:73], v[2:17]
	v_exp_f32_e32 v70, v102
	v_exp_f32_e32 v71, v103
	v_exp_f32_e32 v72, v104
	v_exp_f32_e32 v73, v105
	v_exp_f32_e32 v81, v113
	v_mfma_f32_32x32x16_bf16 v[2:17], v[202:205], v[76:79], v[2:17]
	v_exp_f32_e32 v76, v108
	v_exp_f32_e32 v77, v109
	v_exp_f32_e32 v78, v110
	v_exp_f32_e32 v79, v111
	v_mfma_f32_32x32x16_bf16 v[2:17], v[194:197], v[114:117], v[2:17]
	s_waitcnt vmcnt(4)
	s_cmp_ge_u32 s96, s94
	s_cbranch_scc0 .Lb_nodrain
	s_waitcnt vmcnt(0)
; #define SWAIT() do { if constexpr (SDEPTH == 2) asm volatile("s_waitcnt vmcnt(4)" ::: "memory"); else asm volatile("s_waitcnt vmcnt(0)" ::: "memory"); } while (0)
; #define RESC(a) do { if (__any((a) < 1.f)) { if (hi == 0) al_l[r32] = (a); asm volatile("s_waitcnt lgkmcnt(0)" ::: "memory"); \
;     for (int d = 0; d < 4; ++d) for (int r = 0; r < 16; ++r) o[d][r] *= al_l[crow(r, hi)]; } } while (0)
; template <int MODE, int QMODE> ...
;     ...
;     __syncthreads(); SWAIT(); SWRITE(1, SO);
;     RESC(alA); __syncthreads();
.Lb_nodrain:
	v_cmp_gt_f32_e32 vcc, 1.0, v236
	ds_write_b128 v219, v[182:185] offset:49152
	ds_write_b128 v220, v[186:189] offset:49152
	s_cbranch_vccz .LBB0_181
	s_and_saveexec_b64 s[18:19], s[2:3]
	ds_write_b32 v214, v236 offset:128
	s_or_b64 exec, exec, s[18:19]
	s_waitcnt lgkmcnt(0)
	v_add_u32_e32 v110, s95, v210
	ds_read_b128 v[98:101], v110 offset:224
	ds_read_b128 v[102:105], v110 offset:192
	ds_read_b128 v[106:109], v110 offset:160
	ds_read_b128 v[110:113], v110 offset:128
	s_waitcnt lgkmcnt(3)
	v_pk_mul_f32 v[62:63], v[62:63], v[98:99]
	s_waitcnt lgkmcnt(2)
	v_pk_mul_f32 v[58:59], v[58:59], v[102:103]
	s_waitcnt lgkmcnt(1)
	v_pk_mul_f32 v[54:55], v[54:55], v[106:107]
	v_pk_mul_f32 v[64:65], v[64:65], v[100:101]
	v_pk_mul_f32 v[60:61], v[60:61], v[104:105]
	v_pk_mul_f32 v[56:57], v[56:57], v[108:109]
	s_waitcnt lgkmcnt(0)
	v_pk_mul_f32 v[52:53], v[52:53], v[112:113]
	v_pk_mul_f32 v[50:51], v[50:51], v[110:111]
	v_pk_mul_f32 v[46:47], v[46:47], v[98:99]
	v_pk_mul_f32 v[42:43], v[42:43], v[102:103]
	v_pk_mul_f32 v[38:39], v[38:39], v[106:107]
	v_pk_mul_f32 v[48:49], v[48:49], v[100:101]
	v_pk_mul_f32 v[44:45], v[44:45], v[104:105]
	v_pk_mul_f32 v[40:41], v[40:41], v[108:109]
	v_pk_mul_f32 v[36:37], v[36:37], v[112:113]
	v_pk_mul_f32 v[34:35], v[34:35], v[110:111]
	v_pk_mul_f32 v[30:31], v[30:31], v[98:99]
	v_pk_mul_f32 v[26:27], v[26:27], v[102:103]
	v_pk_mul_f32 v[22:23], v[22:23], v[106:107]
	v_pk_mul_f32 v[32:33], v[32:33], v[100:101]
	v_pk_mul_f32 v[28:29], v[28:29], v[104:105]
	v_pk_mul_f32 v[24:25], v[24:25], v[108:109]
	v_pk_mul_f32 v[20:21], v[20:21], v[112:113]
	v_pk_mul_f32 v[18:19], v[18:19], v[110:111]
	v_pk_mul_f32 v[14:15], v[14:15], v[98:99]
	v_pk_mul_f32 v[10:11], v[10:11], v[102:103]
	v_pk_mul_f32 v[6:7], v[6:7], v[106:107]
	v_pk_mul_f32 v[16:17], v[16:17], v[100:101]
	v_pk_mul_f32 v[12:13], v[12:13], v[104:105]
	v_pk_mul_f32 v[8:9], v[8:9], v[108:109]
	v_pk_mul_f32 v[4:5], v[4:5], v[112:113]
	v_pk_mul_f32 v[2:3], v[2:3], v[110:111]
.LBB0_181:
	v_add_f32_e32 v98, v233, v235
	v_fmac_f32_e32 v98, v234, v215
	v_add_f32_e32 v215, v239, v240
	v_fmac_f32_e32 v215, v98, v238
	v_lshl_add_u64 v[212:213], v[212:213], 0, s[44:45]
	s_and_b64 vcc, exec, s[16:17]
	s_waitcnt lgkmcnt(0)
	s_barrier
	ds_write_b128 v221, v[178:181] offset:16384
	ds_write_b128 v222, v[190:193] offset:16384
	s_cbranch_vccnz .LBB0_183
	v_mov_b32_e32 v234, v236
	s_branch .LBB0_171

; __device__ __forceinline__ int v_st(int k, int c) { const int kk = (k & ~0xC) | ((k & 4) << 1) | ((k & 8) >> 1); return ((kk >> 3) * 4 + (c >> 5)) * 512 + ((kk & 7) * 32 + (c & 31)) * 2; }
; __device__ __forceinline__ int v_rd_base(int lane) { return ((lane & 3) << 3) | (((lane >> 2) & 3) << 6) | (((lane >> 4) & 1) << 5) | (((lane >> 5) & 1) << 8); }
; #define SLOAD(i, k0) do { const long to_ = (long)(k0) * ldk * 2; const char* vt_ = (const char*)Vh + to_; const char* kt_ = (const char*)Kh + to_; \
;     sr_[i].vs0 = *(const bf16x8*)(vt_ + toff); sr_[i].vs1 = *(const bf16x8*)(vt_ + h32 + toff); \
;     sr_[i].ks0 = *(const bf16x8*)(kt_ + toff); sr_[i].ks1 = *(const bf16x8*)(kt_ + h32 + toff); } while (0)
; #define MASK(P0, P1, k0) do { if constexpr (MODE == 1) { const int k0_ = (k0); \
;     if ((k0_ + 63 - qw0 > 128) || (k0_ - (qw0 + 31) < -128)) maskwin(P0, P1, k0_ - (qw0 + r32) + 128 + 4 * hi); } } while (0)
; template <int MODE, int QMODE> ...
;     ...
;   const int sr = tid >> 4, sc = (tid & 15) * 8, vst0 = v_st(sr, sc), vst1 = v_st(32 + sr, sc);
;   const int vb0 = (int)(uintptr_t)V_lds + v_rd_base(lane);
;   const unsigned toff = (unsigned)(sr * ldk + sc) * 2u; const long h32 = (long)ldk * 64;
;   constexpr int SDEPTH = (MODE == 0 && QMODE == 2) ? 2 : 1;
;   struct { typename St::T vs0, vs1, ks0, ks1; } sr_[SDEPTH];
;     ...
;   const int qw0 = qrel + wrow;
;     ...
;   if (wid >= 4) __builtin_amdgcn_s_setprio(1);
;   f32x16 pA0, pA1, pB0, pB1; float mnA, mnB, alA, alB; bf16x8 pa0, pa1, pa2, pa3; const int NT = seq / KVBLK;
;   constexpr int SE = 0, SO = SDEPTH - 1;
;   SLOAD(SE, 0); asm volatile("s_waitcnt vmcnt(0)" ::: "memory"); SWRITE(0, SE); __syncthreads();
;   qkt(pA0, pA1, K_lds, qr, r32, hi); MASK(pA0, pA1, 0); partialSM(pA0, pA1, m_reg, mnA, alA);
.LBB0_226:
	s_addk_i32 s80, 0x2000
	s_and_b64 s[2:3], s[2:3], exec
	s_cselect_b32 s2, 0x4000, s80
	s_add_i32 s3, s20, 0xffffff80
	s_max_i32 s3, s3, s84
	s_mul_i32 s5, s3, 0x1800
	s_mul_hi_u32 s4, s3, 0x1800
	s_add_u32 s5, s40, s5
	s_addc_u32 s4, s41, s4
	s_lshl_b32 s22, s67, 7
	s_and_b32 s22, s22, 0x100
	s_add_u32 s22, s5, s22
	s_addc_u32 s23, s4, 0
	s_add_u32 s80, s22, 0x800
	v_ashrrev_i32_e32 v18, 4, v40
	v_lshlrev_b32_e32 v19, 3, v40
	s_addc_u32 s81, s23, 0
	v_and_b32_e32 v20, 0x78, v19
	v_mul_lo_u32 v2, v18, s27
	s_add_u32 s82, s22, 0xa00
	v_or_b32_e32 v2, v2, v20
	s_addc_u32 s83, s23, 0
	v_lshlrev_b32_e32 v178, 1, v2
	v_lshl_add_u64 v[36:37], s[82:83], 0, v[178:179]
	v_add_co_u32_e32 v2, vcc, s29, v36
	v_lshl_add_u64 v[34:35], s[80:81], 0, v[178:179]
	s_nop 0
	v_addc_co_u32_e32 v3, vcc, 0, v37, vcc
	global_load_dwordx4 v[2:5], v[2:3], off
	s_nop 0
	global_load_dwordx4 v[6:9], v178, s[22:23] offset:2560
	global_load_dwordx4 v[10:13], v178, s[22:23] offset:2048
	v_add_co_u32_e32 v14, vcc, s29, v34
	v_lshlrev_b32_e32 v22, 4, v38
	s_nop 0
	v_addc_co_u32_e32 v15, vcc, 0, v35, vcc
	global_load_dwordx4 v[14:17], v[14:15], off
	v_and_b32_e32 v23, 0xfffff0, v18
	v_lshlrev_b32_e32 v24, 1, v18
	v_lshrrev_b32_e32 v25, 1, v18
	v_and_b32_e32 v26, 3, v18
	v_add_u32_e32 v27, 32, v18
	v_and_b32_e32 v50, 0xf0, v22
	v_and_or_b32 v22, v24, 8, v23
	v_and_or_b32 v23, v25, 4, v26
	v_and_b32_e32 v24, 0xfffff0, v27
	v_lshlrev_b32_e32 v25, 1, v27
	v_and_b32_e32 v21, 0xf0, v40
	v_bfe_u32 v19, v19, 5, 2
	v_lshlrev_b32_e32 v18, 8, v18
	v_lshlrev_b32_e32 v20, 1, v20
	v_lshlrev_b32_e32 v26, 8, v27
	v_lshrrev_b32_e32 v22, 1, v22
	v_and_or_b32 v24, v25, 8, v24
	v_and_b32_e32 v28, 48, v20
	v_bitop3_b32 v18, v20, v18, v21 bitop3:0xde
	v_bitop3_b32 v20, v20, v26, v21 bitop3:0xde
	v_or_b32_e32 v21, v22, v19
	v_lshrrev_b32_e32 v22, 1, v24
	v_lshlrev_b32_e32 v41, 8, v38
	v_lshlrev_b32_e32 v23, 6, v23
	v_add_u32_e32 v199, 0, v18
	v_lshlrev_b32_e32 v18, 9, v21
	v_or_b32_e32 v19, v22, v19
	v_bitop3_b32 v27, v180, v41, v50 bitop3:0xde
	v_or3_b32 v18, v18, v23, v28
	v_lshlrev_b32_e32 v19, 9, v19
	v_add_u32_e32 v191, 0, v27
	v_or3_b32 v19, v19, v23, v28
	v_add_u32_e32 v201, 0, v18
	v_add_u32_e32 v200, 0, v20
	v_add_u32_e32 v202, 0, v19
	s_waitcnt vmcnt(0)
	s_sub_i32 s4, s20, s3
	s_or_b32 s81, s66, s4
	s_add_i32 s4, s81, 0xffffff9e
	s_cmp_gt_u32 s4, 0xffffff5c
	v_lshlrev_b32_e32 v189, 2, v184
	v_or_b32_e32 v190, s81, v38
	s_waitcnt vmcnt(2)
	ds_write_b128 v201, v[6:9]
	ds_write_b128 v202, v[2:5]
	s_waitcnt vmcnt(1)
	ds_write_b128 v199, v[10:13] offset:32768
	s_waitcnt vmcnt(0)
	ds_write_b128 v200, v[14:17] offset:32768
	s_waitcnt lgkmcnt(0)
	s_barrier
	ds_read_b128 v[2:5], v191 offset:32768
	ds_read_b128 v[6:9], v191 offset:40960
	s_waitcnt lgkmcnt(1)
	v_mfma_f32_32x32x16_bf16 v[18:33], v[2:5], v[134:137], 0
	v_or_b32_e32 v2, 32, v180
	v_bitop3_b32 v2, v2, v41, v50 bitop3:0xde
	v_add_u32_e32 v192, 0, v2
	ds_read_b128 v[42:45], v192 offset:32768
	ds_read_b128 v[46:49], v192 offset:40960
	s_waitcnt lgkmcnt(2)
	v_mfma_f32_32x32x16_bf16 v[2:17], v[6:9], v[134:137], 0
	s_waitcnt lgkmcnt(1)
	v_mfma_f32_32x32x16_bf16 v[18:33], v[42:45], v[142:145], v[18:33]
	v_or_b32_e32 v42, 64, v180
	v_bitop3_b32 v42, v42, v41, v50 bitop3:0xde
	v_add_u32_e32 v193, 0, v42
	s_waitcnt lgkmcnt(0)
	v_mfma_f32_32x32x16_bf16 v[2:17], v[46:49], v[142:145], v[2:17]
	ds_read_b128 v[42:45], v193 offset:32768
	ds_read_b128 v[46:49], v193 offset:40960
	s_waitcnt lgkmcnt(1)
	v_mfma_f32_32x32x16_bf16 v[18:33], v[42:45], v[150:153], v[18:33]
	v_or_b32_e32 v42, 0x60, v180
	v_bitop3_b32 v42, v42, v41, v50 bitop3:0xde
	v_add_u32_e32 v194, 0, v42
	s_waitcnt lgkmcnt(0)
	v_mfma_f32_32x32x16_bf16 v[2:17], v[46:49], v[150:153], v[2:17]
	ds_read_b128 v[42:45], v194 offset:32768
	ds_read_b128 v[46:49], v194 offset:40960
	s_waitcnt lgkmcnt(1)
	v_mfma_f32_32x32x16_bf16 v[18:33], v[42:45], v[158:161], v[18:33]
	v_or_b32_e32 v42, 0x80, v180
	v_bitop3_b32 v42, v42, v41, v50 bitop3:0xde
	v_add_u32_e32 v195, 0, v42
	s_waitcnt lgkmcnt(0)
	v_mfma_f32_32x32x16_bf16 v[2:17], v[46:49], v[158:161], v[2:17]
	ds_read_b128 v[42:45], v195 offset:32768
	ds_read_b128 v[46:49], v195 offset:40960
	s_waitcnt lgkmcnt(1)
	v_mfma_f32_32x32x16_bf16 v[18:33], v[42:45], v[130:133], v[18:33]
	v_or_b32_e32 v42, 0xa0, v180
	v_bitop3_b32 v42, v42, v41, v50 bitop3:0xde
	v_add_u32_e32 v196, 0, v42
	s_waitcnt lgkmcnt(0)
	v_mfma_f32_32x32x16_bf16 v[2:17], v[46:49], v[130:133], v[2:17]
	ds_read_b128 v[42:45], v196 offset:32768
	ds_read_b128 v[46:49], v196 offset:40960
	s_waitcnt lgkmcnt(1)
	v_mfma_f32_32x32x16_bf16 v[18:33], v[42:45], v[138:141], v[18:33]
	v_or_b32_e32 v42, 0xc0, v180
	v_bitop3_b32 v42, v42, v41, v50 bitop3:0xde
	v_add_u32_e32 v197, 0, v42
	s_waitcnt lgkmcnt(0)
	v_mfma_f32_32x32x16_bf16 v[2:17], v[46:49], v[138:141], v[2:17]
	ds_read_b128 v[42:45], v197 offset:32768
	ds_read_b128 v[46:49], v197 offset:40960
	s_waitcnt lgkmcnt(1)
	v_mfma_f32_32x32x16_bf16 v[18:33], v[42:45], v[146:149], v[18:33]
	v_or_b32_e32 v42, 0xe0, v180
	v_bitop3_b32 v41, v42, v41, v50 bitop3:0xde
	v_add_u32_e32 v198, 0, v41
	s_waitcnt lgkmcnt(0)
	v_mfma_f32_32x32x16_bf16 v[2:17], v[46:49], v[146:149], v[2:17]
	ds_read_b128 v[42:45], v198 offset:32768
	ds_read_b128 v[46:49], v198 offset:40960
	s_waitcnt lgkmcnt(1)
	v_mfma_f32_32x32x16_bf16 v[18:33], v[42:45], v[154:157], v[18:33]
	s_waitcnt lgkmcnt(0)
	v_mfma_f32_32x32x16_bf16 v[2:17], v[46:49], v[154:157], v[2:17]
	s_cbranch_scc1 .LBB0_228
; __device__ __forceinline__ void maskwin(f32x16& p0, f32x16& p1, int mb) {
; #pragma unroll
;   for (int r = 0; r < 16; ++r) { const int dk = mb + (r & 3) + 8 * (r >> 2);
;     if ((unsigned)dk > 256u) p0[r] = -INFINITY; if ((unsigned)(dk + 32) > 256u) p1[r] = -INFINITY; }
; }
	v_sub_u32_e32 v41, v189, v190
	v_add_u32_e32 v42, 0xffffff7f, v41
	v_cmp_lt_u32_e32 vcc, s30, v42
	v_add_u32_e32 v42, 0xffffff9f, v41
	s_nop 4
	v_cndmask_b32_e32 v18, v1, v18, vcc
	v_cmp_lt_u32_e32 vcc, s30, v42
	v_add_u32_e32 v42, 0xffffff80, v41
	s_nop 0
	v_cndmask_b32_e32 v2, v1, v2, vcc
	v_cmp_lt_u32_e32 vcc, s30, v42
	v_add_u32_e32 v42, 0xffffffa0, v41
	s_nop 0
	v_cndmask_b32_e32 v19, v1, v19, vcc
	v_cmp_lt_u32_e32 vcc, s30, v42
	v_add_u32_e32 v42, 0xffffff81, v41
	s_nop 0
	v_cndmask_b32_e32 v3, v1, v3, vcc
	v_cmp_lt_u32_e32 vcc, s30, v42
	v_add_u32_e32 v42, 0xffffffa1, v41
	s_nop 0
	v_cndmask_b32_e32 v20, v1, v20, vcc
	v_cmp_lt_u32_e32 vcc, s30, v42
	v_add_u32_e32 v42, 0xffffff82, v41
	s_nop 0
	v_cndmask_b32_e32 v4, v1, v4, vcc
	v_cmp_lt_u32_e32 vcc, s30, v42
	v_add_u32_e32 v42, 0xffffffa2, v41
	s_nop 0
	v_cndmask_b32_e32 v21, v1, v21, vcc
	v_cmp_lt_u32_e32 vcc, s30, v42
	v_add_u32_e32 v42, 0xffffff87, v41
	s_nop 0
	v_cndmask_b32_e32 v5, v1, v5, vcc
	v_cmp_lt_u32_e32 vcc, s30, v42
	v_add_u32_e32 v42, 0xffffffa7, v41
	s_nop 0
	v_cndmask_b32_e32 v22, v1, v22, vcc
	v_cmp_lt_u32_e32 vcc, s30, v42
	v_add_u32_e32 v42, 0xffffff88, v41
	s_nop 0
	v_cndmask_b32_e32 v6, v1, v6, vcc
	v_cmp_lt_u32_e32 vcc, s30, v42
	v_add_u32_e32 v42, 0xffffffa8, v41
	s_nop 0
	v_cndmask_b32_e32 v23, v1, v23, vcc
	v_cmp_lt_u32_e32 vcc, s30, v42
	v_add_u32_e32 v42, 0xffffff89, v41
	s_nop 0
	v_cndmask_b32_e32 v7, v1, v7, vcc
	v_cmp_lt_u32_e32 vcc, s30, v42
	v_add_u32_e32 v42, 0xffffffa9, v41
	s_nop 0
	v_cndmask_b32_e32 v24, v1, v24, vcc
	v_cmp_lt_u32_e32 vcc, s30, v42
	v_add_u32_e32 v42, 0xffffff8a, v41
	s_nop 0
	v_cndmask_b32_e32 v8, v1, v8, vcc
	v_cmp_lt_u32_e32 vcc, s30, v42
	v_add_u32_e32 v42, 0xffffffaa, v41
	s_nop 0
	v_cndmask_b32_e32 v25, v1, v25, vcc
	v_cmp_lt_u32_e32 vcc, s30, v42
	v_add_u32_e32 v42, 0xffffff8f, v41
	s_nop 0
	v_cndmask_b32_e32 v9, v1, v9, vcc
	v_cmp_lt_u32_e32 vcc, s30, v42
	v_add_u32_e32 v42, 0xffffffaf, v41
	s_nop 0
	v_cndmask_b32_e32 v26, v1, v26, vcc
	v_cmp_lt_u32_e32 vcc, s30, v42
	v_add_u32_e32 v42, 0xffffff90, v41
	s_nop 0
	v_cndmask_b32_e32 v10, v1, v10, vcc
	v_cmp_lt_u32_e32 vcc, s30, v42
	v_add_u32_e32 v42, 0xffffffb0, v41
	s_nop 0
	v_cndmask_b32_e32 v27, v1, v27, vcc
	v_cmp_lt_u32_e32 vcc, s30, v42
	v_add_u32_e32 v42, 0xffffff91, v41
	s_nop 0
	v_cndmask_b32_e32 v11, v1, v11, vcc
	v_cmp_lt_u32_e32 vcc, s30, v42
	v_add_u32_e32 v42, 0xffffffb1, v41
	s_nop 0
	v_cndmask_b32_e32 v28, v1, v28, vcc
	v_cmp_lt_u32_e32 vcc, s30, v42
	v_add_u32_e32 v42, 0xffffff92, v41
	s_nop 0
	v_cndmask_b32_e32 v12, v1, v12, vcc
	v_cmp_lt_u32_e32 vcc, s30, v42
	v_add_u32_e32 v42, 0xffffffb2, v41
	s_nop 0
	v_cndmask_b32_e32 v29, v1, v29, vcc
	v_cmp_lt_u32_e32 vcc, s30, v42
	v_add_u32_e32 v42, 0xffffff97, v41
	s_nop 0
	v_cndmask_b32_e32 v13, v1, v13, vcc
	v_cmp_lt_u32_e32 vcc, s30, v42
	v_add_u32_e32 v42, 0xffffffb7, v41
	s_nop 0
	v_cndmask_b32_e32 v30, v1, v30, vcc
	v_cmp_lt_u32_e32 vcc, s30, v42
	v_add_u32_e32 v42, 0xffffff98, v41
	s_nop 0
	v_cndmask_b32_e32 v14, v1, v14, vcc
	v_cmp_lt_u32_e32 vcc, s30, v42
	v_add_u32_e32 v42, 0xffffffb8, v41
	s_nop 0
	v_cndmask_b32_e32 v31, v1, v31, vcc
	v_cmp_lt_u32_e32 vcc, s30, v42
	v_add_u32_e32 v42, 0xffffff99, v41
	s_nop 0
	v_cndmask_b32_e32 v15, v1, v15, vcc
	v_cmp_lt_u32_e32 vcc, s30, v42
	v_add_u32_e32 v42, 0xffffffb9, v41
	s_nop 0
	v_cndmask_b32_e32 v32, v1, v32, vcc
	v_cmp_lt_u32_e32 vcc, s30, v42
	v_add_u32_e32 v42, 0xffffff9a, v41
	v_add_u32_e32 v41, 0xffffffba, v41
	v_cndmask_b32_e32 v16, v1, v16, vcc
	v_cmp_lt_u32_e32 vcc, s30, v42
	s_nop 1
	v_cndmask_b32_e32 v33, v1, v33, vcc
	v_cmp_lt_u32_e32 vcc, s30, v41
	s_nop 1
	v_cndmask_b32_e32 v17, v1, v17, vcc

; __device__ __forceinline__ int v_st(int k, int c) { const int kk = (k & ~0xC) | ((k & 4) << 1) | ((k & 8) >> 1); return ((kk >> 3) * 4 + (c >> 5)) * 512 + ((kk & 7) * 32 + (c & 31)) * 2; }
; __device__ __forceinline__ int v_rd_base(int lane) { return ((lane & 3) << 3) | (((lane >> 2) & 3) << 6) | (((lane >> 4) & 1) << 5) | (((lane >> 5) & 1) << 8); }
; #define SLOAD(i, k0) do { const long to_ = (long)(k0) * ldk * 2; const char* vt_ = (const char*)Vh + to_; const char* kt_ = (const char*)Kh + to_; \
;     sr_[i].vs0 = *(const bf16x8*)(vt_ + toff); sr_[i].vs1 = *(const bf16x8*)(vt_ + h32 + toff); \
;     sr_[i].ks0 = *(const bf16x8*)(kt_ + toff); sr_[i].ks1 = *(const bf16x8*)(kt_ + h32 + toff); } while (0)
; #define MASK(P0, P1, k0) do { if constexpr (MODE == 1) { const int k0_ = (k0); \
;     if ((k0_ + 63 - qw0 > 128) || (k0_ - (qw0 + 31) < -128)) maskwin(P0, P1, k0_ - (qw0 + r32) + 128 + 4 * hi); } } while (0)
; template <int MODE, int QMODE> ...
;     ...
;   const int sr = tid >> 4, sc = (tid & 15) * 8, vst0 = v_st(sr, sc), vst1 = v_st(32 + sr, sc);
;   const int vb0 = (int)(uintptr_t)V_lds + v_rd_base(lane);
;   const unsigned toff = (unsigned)(sr * ldk + sc) * 2u; const long h32 = (long)ldk * 64;
;   constexpr int SDEPTH = (MODE == 0 && QMODE == 2) ? 2 : 1;
;   struct { typename St::T vs0, vs1, ks0, ks1; } sr_[SDEPTH];
;     ...
;   const int qw0 = qrel + wrow;
;     ...
;   if (wid >= 4) __builtin_amdgcn_s_setprio(1);
;   f32x16 pA0, pA1, pB0, pB1; float mnA, mnB, alA, alB; bf16x8 pa0, pa1, pa2, pa3; const int NT = seq / KVBLK;
;   constexpr int SE = 0, SO = SDEPTH - 1;
;   SLOAD(SE, 0); asm volatile("s_waitcnt vmcnt(0)" ::: "memory"); SWRITE(0, SE); __syncthreads();
;   qkt(pA0, pA1, K_lds, qr, r32, hi); MASK(pA0, pA1, 0); partialSM(pA0, pA1, m_reg, mnA, alA);
.LBB0_292:
	s_add_i32 s4, s13, 0xffffc000
	s_lshr_b32 s4, s4, 5
	s_and_b32 s4, s4, 0x7ffff00
	s_add_i32 s8, s4, 0x100
	s_lshl_b64 s[4:5], s[8:9], 10
	s_cmpk_gt_i32 s18, 0x3fff
	s_cselect_b32 s5, s5, 0
	s_cselect_b32 s4, s4, 0
	s_lshl_b64 s[4:5], s[4:5], 1
	s_add_u32 s4, s42, s4
	s_addc_u32 s5, s43, s5
	s_lshl_b32 s8, s3, 1
	s_add_u32 s4, s4, s8
	v_lshlrev_b32_e32 v19, 3, v35
	s_addc_u32 s5, s5, 0
	v_and_b32_e32 v2, 0x78, v19
	s_add_u32 s20, s4, 0x400
	v_ashrrev_i32_e32 v18, 4, v35
	v_lshlrev_b32_e32 v20, 1, v2
	s_addc_u32 s21, s5, 0
	v_lshl_or_b32 v10, v18, 11, v20
	v_mov_b32_e32 v11, v195
	v_lshl_add_u64 v[178:179], s[20:21], 0, v[10:11]
	v_add_co_u32_e32 v2, vcc, s24, v178
	v_lshl_add_u64 v[186:187], s[4:5], 0, v[10:11]
	s_nop 0
	v_addc_co_u32_e32 v3, vcc, 0, v179, vcc
	global_load_dwordx4 v[2:5], v[2:3], off
	s_nop 0
	global_load_dwordx4 v[6:9], v10, s[4:5] offset:1024
	s_nop 0
	global_load_dwordx4 v[10:13], v10, s[4:5]
	v_add_co_u32_e32 v14, vcc, s24, v186
	v_lshlrev_b32_e32 v22, 4, v34
	s_nop 0
	v_addc_co_u32_e32 v15, vcc, 0, v187, vcc
	global_load_dwordx4 v[14:17], v[14:15], off
	v_and_b32_e32 v23, 0xfffff0, v18
	v_lshlrev_b32_e32 v24, 1, v18
	v_lshrrev_b32_e32 v25, 1, v18
	v_and_b32_e32 v26, 3, v18
	v_add_u32_e32 v27, 32, v18
	v_and_b32_e32 v45, 0xf0, v22
	v_and_or_b32 v22, v24, 8, v23
	v_and_or_b32 v23, v25, 4, v26
	v_and_b32_e32 v24, 0xfffff0, v27
	v_lshlrev_b32_e32 v25, 1, v27
	v_and_b32_e32 v21, 0xf0, v35
	v_bfe_u32 v19, v19, 5, 2
	v_lshlrev_b32_e32 v18, 8, v18
	v_lshlrev_b32_e32 v26, 8, v27
	v_lshrrev_b32_e32 v22, 1, v22
	v_and_or_b32 v24, v25, 8, v24
	v_and_b32_e32 v28, 48, v20
	v_bitop3_b32 v18, v20, v18, v21 bitop3:0xde
	v_bitop3_b32 v20, v20, v26, v21 bitop3:0xde
	v_or_b32_e32 v21, v22, v19
	v_lshrrev_b32_e32 v22, 1, v24
	v_lshlrev_b32_e32 v44, 8, v34
	v_lshlrev_b32_e32 v23, 6, v23
	v_add_u32_e32 v214, 0, v18
	v_lshlrev_b32_e32 v18, 9, v21
	v_or_b32_e32 v19, v22, v19
	v_bitop3_b32 v27, v194, v44, v45 bitop3:0xde
	v_or3_b32 v18, v18, v23, v28
	v_lshlrev_b32_e32 v19, 9, v19
	v_add_u32_e32 v203, 0, v27
	v_or3_b32 v19, v19, v23, v28
	v_add_u32_e32 v216, 0, v18
	v_add_u32_e32 v215, 0, v20
	v_add_u32_e32 v217, 0, v19
	s_waitcnt vmcnt(0)
	v_and_b32_e32 v35, 63, v35
	v_or_b32_e32 v46, 0xc0, v194
	v_or_b32_e32 v47, 0xe0, v194
	v_lshlrev_b32_e32 v48, 3, v35
	v_and_b32_e32 v51, 0x100, v48
	s_and_b32 s2, s2, 0x3fffffc0
	s_lshl_b32 s2, s2, 2
	s_add_i32 s59, s2, 0
	s_add_i32 s59, s59, 0x10000
	s_cmp_lg_u32 0, -1
	s_cselect_b32 s2, 0, 0
	v_cmp_gt_u32_e64 s[4:5], 32, v35
	v_lshl_add_u32 v197, v34, 2, s59
	s_waitcnt vmcnt(2)
	ds_write_b128 v216, v[6:9]
	ds_write_b128 v217, v[2:5]
	s_waitcnt vmcnt(1)
	ds_write_b128 v214, v[10:13] offset:32768
	s_waitcnt vmcnt(0)
	ds_write_b128 v215, v[14:17] offset:32768
	s_waitcnt lgkmcnt(0)
	s_barrier
	ds_read_b128 v[2:5], v203 offset:32768
	ds_read_b128 v[6:9], v203 offset:40960
	s_waitcnt lgkmcnt(1)
	v_mfma_f32_32x32x16_bf16 v[18:33], v[2:5], v[158:161], 0
	v_or_b32_e32 v2, 32, v194
	v_bitop3_b32 v2, v2, v44, v45 bitop3:0xde
	v_add_u32_e32 v204, 0, v2
	ds_read_b128 v[36:39], v204 offset:32768
	ds_read_b128 v[40:43], v204 offset:40960
	s_waitcnt lgkmcnt(2)
	v_mfma_f32_32x32x16_bf16 v[2:17], v[6:9], v[158:161], 0
	s_waitcnt lgkmcnt(1)
	v_mfma_f32_32x32x16_bf16 v[18:33], v[36:39], v[154:157], v[18:33]
	v_or_b32_e32 v36, 64, v194
	v_bitop3_b32 v36, v36, v44, v45 bitop3:0xde
	v_add_u32_e32 v205, 0, v36
	s_waitcnt lgkmcnt(0)
	v_mfma_f32_32x32x16_bf16 v[2:17], v[40:43], v[154:157], v[2:17]
	ds_read_b128 v[36:39], v205 offset:32768
	ds_read_b128 v[40:43], v205 offset:40960
	s_waitcnt lgkmcnt(1)
	v_mfma_f32_32x32x16_bf16 v[18:33], v[36:39], v[150:153], v[18:33]
	v_or_b32_e32 v36, 0x60, v194
	v_bitop3_b32 v36, v36, v44, v45 bitop3:0xde
	v_add_u32_e32 v206, 0, v36
	s_waitcnt lgkmcnt(0)
	v_mfma_f32_32x32x16_bf16 v[2:17], v[40:43], v[150:153], v[2:17]
	ds_read_b128 v[36:39], v206 offset:32768
	ds_read_b128 v[40:43], v206 offset:40960
	s_waitcnt lgkmcnt(1)
	v_mfma_f32_32x32x16_bf16 v[18:33], v[36:39], v[146:149], v[18:33]
	v_or_b32_e32 v36, 0x80, v194
	v_bitop3_b32 v36, v36, v44, v45 bitop3:0xde
	v_add_u32_e32 v207, 0, v36
	s_waitcnt lgkmcnt(0)
	v_mfma_f32_32x32x16_bf16 v[2:17], v[40:43], v[146:149], v[2:17]
	ds_read_b128 v[36:39], v207 offset:32768
	ds_read_b128 v[40:43], v207 offset:40960
	s_waitcnt lgkmcnt(1)
	v_mfma_f32_32x32x16_bf16 v[18:33], v[36:39], v[142:145], v[18:33]
	v_or_b32_e32 v36, 0xa0, v194
	v_bitop3_b32 v36, v36, v44, v45 bitop3:0xde
	v_add_u32_e32 v209, 0, v36
	ds_read_b128 v[36:39], v209 offset:32768
	s_waitcnt lgkmcnt(1)
	v_mfma_f32_32x32x16_bf16 v[2:17], v[40:43], v[142:145], v[2:17]
	v_lshlrev_b32_e32 v40, 4, v35
	v_lshlrev_b32_e32 v41, 1, v35
	v_and_b32_e32 v49, 0xc0, v40
	v_and_b32_e32 v50, 32, v41
	ds_read_b128 v[40:43], v209 offset:40960
	s_waitcnt lgkmcnt(1)
	v_mfma_f32_32x32x16_bf16 v[18:33], v[36:39], v[138:141], v[18:33]
	v_bitop3_b32 v36, v46, v44, v45 bitop3:0xde
	v_bitop3_b32 v37, v47, v44, v45 bitop3:0xde
	v_add_u32_e32 v211, 0, v36
	v_add_u32_e32 v210, 0, v37
	ds_read_b128 v[36:39], v211 offset:32768
	v_and_or_b32 v44, v48, 24, v49
	v_add_co_u32_e32 v48, vcc, s26, v186
	s_waitcnt lgkmcnt(1)
	v_mfma_f32_32x32x16_bf16 v[2:17], v[40:43], v[138:141], v[2:17]
	ds_read_b128 v[40:43], v211 offset:40960
	v_addc_co_u32_e32 v49, vcc, 0, v187, vcc
	v_add_co_u32_e32 v52, vcc, s27, v186
	v_or3_b32 v162, v44, v50, v51
	s_nop 0
	v_addc_co_u32_e32 v53, vcc, 0, v187, vcc
	s_waitcnt lgkmcnt(1)
	v_mfma_f32_32x32x16_bf16 v[18:33], v[36:39], v[134:137], v[18:33]
	ds_read_b128 v[36:39], v210 offset:32768
	v_add_co_u32_e32 v44, vcc, s26, v178
	v_add_u32_e32 v201, s2, v162
	s_nop 0
	v_addc_co_u32_e32 v45, vcc, 0, v179, vcc
	v_add_co_u32_e32 v46, vcc, s27, v178
	s_waitcnt lgkmcnt(1)
; #define SBAR() __builtin_amdgcn_sched_barrier(0)
; #define SLOAD(i, k0) do { const long to_ = (long)(k0) * ldk * 2; const char* vt_ = (const char*)Vh + to_; const char* kt_ = (const char*)Kh + to_; \
;     sr_[i].vs0 = *(const bf16x8*)(vt_ + toff); sr_[i].vs1 = *(const bf16x8*)(vt_ + h32 + toff); \
;     sr_[i].ks0 = *(const bf16x8*)(kt_ + toff); sr_[i].ks1 = *(const bf16x8*)(kt_ + h32 + toff); } while (0)
; #define SWAIT() do { if constexpr (SDEPTH == 2) asm volatile("s_waitcnt vmcnt(4)" ::: "memory"); else asm volatile("s_waitcnt vmcnt(0)" ::: "memory"); } while (0)
; __device__ __forceinline__ void partialSM(f32x16& p0, f32x16& p1, float& m_reg, float& mn, float& alpha) {
;   constexpr float C = SCALE * 1.4426950408889634f;
;   float pmax = p0[0]; for (int r = 1; r < 16; ++r) pmax = fmaxf(pmax, p0[r]); for (int r = 0; r < 16; ++r) pmax = fmaxf(pmax, p1[r]);
;   { auto rr = __builtin_amdgcn_permlane32_swap(__float_as_uint(pmax), __float_as_uint(pmax), false, false);
;     pmax = fmaxf(__uint_as_float(rr[0]), __uint_as_float(rr[1])); }
;   if (__builtin_expect(__all(pmax - m_reg <= THR / SCALE), 1)) { mn = m_reg; alpha = 1.f; }
;   else { mn = fmaxf(m_reg, pmax); alpha = __builtin_amdgcn_exp2f((m_reg - mn) * C); m_reg = mn; }
;   float mnC = -mn * C;
;   for (int r = 0; r < 16; ++r) p0[r] = fmaf(p0[r], C, mnC); for (int r = 0; r < 16; ++r) p1[r] = fmaf(p1[r], C, mnC);
;   for (int r = 0; r < 16; ++r) p0[r] = __builtin_amdgcn_exp2f(p0[r]);
; }
; template <int MODE, int QMODE> ...
;     ...
;   SLOAD(SO, KVBLK); if constexpr (SDEPTH == 2) { if (2 < NT) SLOAD(SE, 2 * KVBLK); }
;   SWAIT(); SWRITE(1, SO); __syncthreads();
;   for (int j = 1; j + 1 < NT; j += 2) {
;     SBAR(); qkt(pB0, pB1, (bf16*)((char*)K_lds + SHM_K), qr, r32, hi);
;     finishSM(pA0, pA1, alA, l_reg, pa0, pa1, pa2, pa3); SBAR();
	v_mfma_f32_32x32x16_bf16 v[2:17], v[40:43], v[134:137], v[2:17]
	v_addc_co_u32_e32 v47, vcc, 0, v179, vcc
	ds_read_b128 v[40:43], v210 offset:40960
	s_waitcnt lgkmcnt(1)
	v_mfma_f32_32x32x16_bf16 v[18:33], v[36:39], v[130:133], v[18:33]
	global_load_dwordx4 v[36:39], v[44:45], off
	s_nop 0
	global_load_dwordx4 v[44:47], v[46:47], off
	s_nop 0
	global_load_dwordx4 v[48:51], v[48:49], off
	s_nop 0
	global_load_dwordx4 v[52:55], v[52:53], off
	s_waitcnt vmcnt(0)
	s_waitcnt vmcnt(3)
	ds_write_b128 v216, v[36:39] offset:16384
	s_waitcnt vmcnt(2)
	ds_write_b128 v217, v[44:47] offset:16384
	s_waitcnt vmcnt(1)
	ds_write_b128 v214, v[48:51] offset:49152
	s_waitcnt vmcnt(0)
	ds_write_b128 v215, v[52:55] offset:49152
	s_waitcnt lgkmcnt(4)
	v_mfma_f32_32x32x16_bf16 v[2:17], v[40:43], v[130:133], v[2:17]
	v_max_f32_e32 v40, v19, v19
	v_max_f32_e32 v41, v18, v18
	v_max_f32_e32 v40, v41, v40
	v_max3_f32 v40, v40, v20, v21
	v_max3_f32 v40, v40, v22, v23
	v_max3_f32 v40, v40, v24, v25
	v_max3_f32 v40, v40, v26, v27
	v_max3_f32 v40, v40, v28, v29
	v_max3_f32 v40, v40, v30, v31
	v_max3_f32 v40, v40, v32, v33
	s_nop 1
	v_max3_f32 v40, v40, v2, v3
	v_max3_f32 v40, v40, v4, v5
	v_max3_f32 v40, v40, v6, v7
	v_max3_f32 v40, v40, v8, v9
	v_max3_f32 v40, v40, v10, v11
	v_max3_f32 v40, v40, v12, v13
	v_max3_f32 v40, v40, v14, v15
	v_max3_f32 v40, v40, v16, v17
	v_mov_b32_e32 v41, v40
	s_nop 1
	v_permlane32_swap_b32_e32 v40, v41
	v_max_f32_e32 v41, v41, v41
	v_max_f32_e32 v40, v40, v40
	v_max_f32_e32 v40, v40, v41
	v_add_f32_e32 v41, 0x7149f2ca, v40
	v_cmp_ge_f32_e32 vcc, s25, v41
	s_cmp_eq_u64 vcc, exec
	v_max_f32_e32 v163, 0xf149f2ca, v40
	s_cselect_b64 s[2:3], -1, 0
	v_cndmask_b32_e64 v82, v163, v1, s[2:3]
	v_mul_f32_e32 v83, 0xbe0293ee, v82
	v_fmamk_f32 v18, v18, 0x3e0293ee, v83
	v_fmamk_f32 v19, v19, 0x3e0293ee, v83
	v_fmamk_f32 v20, v20, 0x3e0293ee, v83
	v_fmamk_f32 v21, v21, 0x3e0293ee, v83
	v_fmamk_f32 v22, v22, 0x3e0293ee, v83
	v_fmamk_f32 v23, v23, 0x3e0293ee, v83
	v_fmamk_f32 v24, v24, 0x3e0293ee, v83
	v_fmamk_f32 v25, v25, 0x3e0293ee, v83
	v_fmamk_f32 v26, v26, 0x3e0293ee, v83
	v_fmamk_f32 v27, v27, 0x3e0293ee, v83
	v_fmamk_f32 v28, v28, 0x3e0293ee, v83
	v_fmamk_f32 v29, v29, 0x3e0293ee, v83
	v_fmamk_f32 v30, v30, 0x3e0293ee, v83
	v_fmamk_f32 v31, v31, 0x3e0293ee, v83
	v_fmamk_f32 v32, v32, 0x3e0293ee, v83
	v_fmamk_f32 v33, v33, 0x3e0293ee, v83
	v_fmamk_f32 v84, v2, 0x3e0293ee, v83
	v_fmamk_f32 v85, v3, 0x3e0293ee, v83
	v_fmamk_f32 v86, v4, 0x3e0293ee, v83
	v_fmamk_f32 v87, v5, 0x3e0293ee, v83
	v_fmamk_f32 v88, v6, 0x3e0293ee, v83
	v_fmamk_f32 v89, v7, 0x3e0293ee, v83
	v_fmamk_f32 v90, v8, 0x3e0293ee, v83
	v_fmamk_f32 v91, v9, 0x3e0293ee, v83
	v_fmamk_f32 v92, v10, 0x3e0293ee, v83
	v_fmamk_f32 v93, v11, 0x3e0293ee, v83
	v_fmamk_f32 v94, v12, 0x3e0293ee, v83
	v_fmamk_f32 v95, v13, 0x3e0293ee, v83
	v_fmamk_f32 v96, v14, 0x3e0293ee, v83
	v_fmamk_f32 v97, v15, 0x3e0293ee, v83
	v_fmamk_f32 v98, v16, 0x3e0293ee, v83
	v_fmac_f32_e32 v83, 0x3e0293ee, v17
	v_exp_f32_e32 v99, v18
	v_exp_f32_e32 v100, v19
	v_exp_f32_e32 v101, v20
	v_exp_f32_e32 v102, v21
	v_exp_f32_e32 v103, v22
	v_exp_f32_e32 v104, v23
	v_exp_f32_e32 v105, v24
	v_exp_f32_e32 v109, v25
	v_exp_f32_e32 v110, v26
	v_exp_f32_e32 v111, v27
	v_exp_f32_e32 v112, v28
	v_exp_f32_e32 v113, v29
	v_exp_f32_e32 v114, v30
	v_exp_f32_e32 v115, v31
	v_exp_f32_e32 v116, v32
	v_exp_f32_e32 v117, v33
	s_waitcnt lgkmcnt(0)
	s_barrier
	ds_read_b128 v[2:5], v203 offset:49152
	ds_read_b128 v[6:9], v203 offset:57344
	v_exp_f32_e32 v84, v84
	v_exp_f32_e32 v85, v85
	v_exp_f32_e32 v86, v86
	s_waitcnt lgkmcnt(1)
	v_mfma_f32_32x32x16_bf16 v[66:81], v[2:5], v[158:161], 0
	v_exp_f32_e32 v87, v87
	v_exp_f32_e32 v88, v88
	s_waitcnt lgkmcnt(0)
	v_mfma_f32_32x32x16_bf16 v[50:65], v[6:9], v[158:161], 0
	ds_read_b128 v[2:5], v204 offset:49152
	ds_read_b128 v[6:9], v204 offset:57344
	ds_read_b128 v[10:13], v205 offset:49152
	ds_read_b128 v[14:17], v205 offset:57344
	s_waitcnt lgkmcnt(3)
	v_mfma_f32_32x32x16_bf16 v[66:81], v[2:5], v[154:157], v[66:81]
	ds_read_b128 v[2:5], v206 offset:49152
	ds_read_b128 v[18:21], v206 offset:57344
	ds_read_b128 v[22:25], v207 offset:49152
	ds_read_b128 v[26:29], v207 offset:57344
	ds_read_b128 v[30:33], v209 offset:49152
	ds_read_b128 v[34:37], v209 offset:57344
	ds_read_b128 v[38:41], v211 offset:49152
	ds_read_b128 v[42:45], v211 offset:57344
	s_waitcnt lgkmcnt(10)
	v_mfma_f32_32x32x16_bf16 v[50:65], v[6:9], v[154:157], v[50:65]
	ds_read_b128 v[6:9], v210 offset:49152
	ds_read_b128 v[46:49], v210 offset:57344
	v_cvt_pk_bf16_f32 v106, v99, v100
	v_cvt_pk_bf16_f32 v107, v101, v102
	v_cvt_pk_bf16_f32 v108, v103, v104
	s_nop 0
	v_permlane32_swap_b32_e32 v106, v108
	s_waitcnt lgkmcnt(11)
	v_mfma_f32_32x32x16_bf16 v[66:81], v[10:13], v[150:153], v[66:81]
	v_exp_f32_e32 v10, v89
	v_exp_f32_e32 v11, v90
	v_exp_f32_e32 v12, v91
	v_exp_f32_e32 v13, v92
	v_exp_f32_e32 v89, v93
	v_exp_f32_e32 v90, v94
	v_exp_f32_e32 v91, v95
	s_waitcnt lgkmcnt(10)
	v_mfma_f32_32x32x16_bf16 v[50:65], v[14:17], v[150:153], v[50:65]
	v_exp_f32_e32 v17, v83
	v_add_f32_e32 v83, 0, v99
	v_add_f32_e32 v83, v100, v83
	v_add_f32_e32 v83, v101, v83
	v_exp_f32_e32 v14, v96
	v_exp_f32_e32 v15, v97
	v_exp_f32_e32 v16, v98
	s_waitcnt lgkmcnt(9)
	v_mfma_f32_32x32x16_bf16 v[66:81], v[2:5], v[146:149], v[66:81]
	v_add_f32_e32 v2, v102, v83
	v_add_f32_e32 v2, v103, v2
	v_add_f32_e32 v2, v104, v2
	v_add_f32_e32 v2, v105, v2
	v_add_f32_e32 v2, v109, v2
	v_add_f32_e32 v2, v110, v2
	v_add_f32_e32 v2, v111, v2
	s_waitcnt lgkmcnt(8)
; #define SBAR() __builtin_amdgcn_sched_barrier(0)
; #define SLOAD(i, k0) do { const long to_ = (long)(k0) * ldk * 2; const char* vt_ = (const char*)Vh + to_; const char* kt_ = (const char*)Kh + to_; \
;     sr_[i].vs0 = *(const bf16x8*)(vt_ + toff); sr_[i].vs1 = *(const bf16x8*)(vt_ + h32 + toff); \
;     sr_[i].ks0 = *(const bf16x8*)(kt_ + toff); sr_[i].ks1 = *(const bf16x8*)(kt_ + h32 + toff); } while (0)
; #define SWAIT() do { if constexpr (SDEPTH == 2) asm volatile("s_waitcnt vmcnt(4)" ::: "memory"); else asm volatile("s_waitcnt vmcnt(0)" ::: "memory"); } while (0)
; #define MASK(P0, P1, k0) do { if constexpr (MODE == 1) { const int k0_ = (k0); \
;     if ((k0_ + 63 - qw0 > 128) || (k0_ - (qw0 + 31) < -128)) maskwin(P0, P1, k0_ - (qw0 + r32) + 128 + 4 * hi); } } while (0)
; template <int MODE, int QMODE> ...
;     ...
;   if (wid >= 4) __builtin_amdgcn_s_setprio(1);
;   f32x16 pA0, pA1, pB0, pB1; float mnA, mnB, alA, alB; bf16x8 pa0, pa1, pa2, pa3; const int NT = seq / KVBLK;
;   constexpr int SE = 0, SO = SDEPTH - 1;
;   SLOAD(SE, 0); asm volatile("s_waitcnt vmcnt(0)" ::: "memory"); SWRITE(0, SE); __syncthreads();
;   qkt(pA0, pA1, K_lds, qr, r32, hi); MASK(pA0, pA1, 0); partialSM(pA0, pA1, m_reg, mnA, alA);
;   SLOAD(SO, KVBLK); if constexpr (SDEPTH == 2) { if (2 < NT) SLOAD(SE, 2 * KVBLK); }
;   SWAIT(); SWRITE(1, SO); __syncthreads();
;   for (int j = 1; j + 1 < NT; j += 2) {
;     SBAR(); qkt(pB0, pB1, (bf16*)((char*)K_lds + SHM_K), qr, r32, hi);
;     finishSM(pA0, pA1, alA, l_reg, pa0, pa1, pa2, pa3); SBAR();
;     SLOAD(SO, (j + SDEPTH) * KVBLK); SBAR();
;     PVSM(vb0, pB0, pB1, j * KVBLK, mnB, alB);
	v_mfma_f32_32x32x16_bf16 v[50:65], v[18:21], v[146:149], v[50:65]
	v_add_f32_e32 v2, v112, v2
	v_add_f32_e32 v2, v113, v2
	v_add_f32_e32 v2, v114, v2
	v_add_f32_e32 v2, v115, v2
	v_add_f32_e32 v2, v116, v2
	v_add_f32_e32 v2, v117, v2
	v_add_f32_e32 v2, v84, v2
	s_waitcnt lgkmcnt(7)
	v_mfma_f32_32x32x16_bf16 v[66:81], v[22:25], v[142:145], v[66:81]
	v_add_f32_e32 v2, v85, v2
	v_add_f32_e32 v2, v86, v2
	v_add_f32_e32 v2, v87, v2
	v_add_f32_e32 v2, v88, v2
	v_add_f32_e32 v2, v10, v2
	v_add_f32_e32 v2, v11, v2
	v_add_f32_e32 v2, v12, v2
	s_waitcnt lgkmcnt(6)
	v_mfma_f32_32x32x16_bf16 v[50:65], v[26:29], v[142:145], v[50:65]
	v_add_f32_e32 v2, v13, v2
	v_add_f32_e32 v2, v89, v2
	v_add_f32_e32 v2, v90, v2
	v_add_f32_e32 v2, v91, v2
	v_add_f32_e32 v2, v14, v2
	v_add_f32_e32 v2, v15, v2
	v_add_f32_e32 v2, v16, v2
	s_waitcnt lgkmcnt(5)
	v_mfma_f32_32x32x16_bf16 v[66:81], v[30:33], v[138:141], v[66:81]
	v_add_f32_e32 v198, v17, v2
	v_mov_b32_e32 v199, v198
	s_nop 1
	v_permlane32_swap_b32_e32 v198, v199
	v_cvt_pk_bf16_f32 v109, v105, v109
	v_cvt_pk_bf16_f32 v102, v110, v111
	v_cvt_pk_bf16_f32 v103, v112, v113
	s_waitcnt lgkmcnt(4)
	v_mfma_f32_32x32x16_bf16 v[50:65], v[34:37], v[138:141], v[50:65]
	v_cvt_pk_bf16_f32 v104, v114, v115
	v_cvt_pk_bf16_f32 v105, v116, v117
	v_cvt_pk_bf16_f32 v110, v84, v85
	v_cvt_pk_bf16_f32 v111, v86, v87
	v_cvt_pk_bf16_f32 v112, v88, v10
	v_cvt_pk_bf16_f32 v113, v11, v12
	v_cvt_pk_bf16_f32 v98, v13, v89
	s_waitcnt lgkmcnt(3)
	v_mfma_f32_32x32x16_bf16 v[66:81], v[38:41], v[134:137], v[66:81]
	v_cvt_pk_bf16_f32 v99, v90, v91
	v_cvt_pk_bf16_f32 v100, v14, v15
	v_cvt_pk_bf16_f32 v101, v16, v17
	v_permlane32_swap_b32_e32 v107, v109
	v_permlane32_swap_b32_e32 v102, v104
	s_waitcnt lgkmcnt(2)
	v_mfma_f32_32x32x16_bf16 v[50:65], v[42:45], v[134:137], v[50:65]
	v_permlane32_swap_b32_e32 v103, v105
	v_permlane32_swap_b32_e32 v110, v112
	v_permlane32_swap_b32_e32 v111, v113
	v_permlane32_swap_b32_e32 v98, v100
	s_waitcnt lgkmcnt(1)
	v_mfma_f32_32x32x16_bf16 v[66:81], v[6:9], v[130:133], v[66:81]
	v_permlane32_swap_b32_e32 v99, v101
	s_waitcnt lgkmcnt(0)
	v_mfma_f32_32x32x16_bf16 v[50:65], v[46:49], v[130:133], v[50:65]
	v_add_co_u32_e32 v2, vcc, s28, v178
	s_nop 1
	v_addc_co_u32_e32 v3, vcc, 0, v179, vcc
	v_add_co_u32_e32 v4, vcc, s29, v178
	s_nop 1
	v_addc_co_u32_e32 v5, vcc, 0, v179, vcc
	global_load_dwordx4 v[114:117], v[2:3], off
	global_load_dwordx4 v[118:121], v[4:5], off
	v_add_co_u32_e32 v2, vcc, s28, v186
	s_nop 1
	v_addc_co_u32_e32 v3, vcc, 0, v187, vcc
	v_add_co_u32_e32 v4, vcc, s29, v186
	s_nop 1
	v_addc_co_u32_e32 v5, vcc, 0, v187, vcc
	global_load_dwordx4 v[122:125], v[2:3], off
	global_load_dwordx4 v[126:129], v[4:5], off
	ds_read_b64_tr_b16 v[2:3], v201 offset:0
	ds_read_b64_tr_b16 v[4:5], v201 offset:0x800
	ds_read_b64_tr_b16 v[18:19], v201 offset:0x1000
	ds_read_b64_tr_b16 v[20:21], v201 offset:0x1800
	ds_read_b64_tr_b16 v[22:23], v201 offset:0x2000
	ds_read_b64_tr_b16 v[24:25], v201 offset:0x2800
	ds_read_b64_tr_b16 v[26:27], v201 offset:0x3000
	ds_read_b64_tr_b16 v[28:29], v201 offset:0x3800
	s_waitcnt lgkmcnt(0)
	s_nop 0
	v_mfma_f32_32x32x16_bf16 v[2:17], v[106:109], v[2:5], 0
	v_max_f32_e32 v30, v67, v67
	v_max_f32_e32 v31, v66, v66
	v_max_f32_e32 v30, v31, v30
	v_max3_f32 v30, v30, v68, v69
	v_mfma_f32_32x32x16_bf16 v[2:17], v[102:105], v[18:21], v[2:17]
	v_max3_f32 v18, v30, v70, v71
	v_max3_f32 v18, v18, v72, v73
	v_max3_f32 v18, v18, v74, v75
	v_max3_f32 v18, v18, v76, v77
	v_max3_f32 v20, v18, v78, v79
	ds_read_b64_tr_b16 v[18:19], v201 offset:0x200
	v_max3_f32 v30, v20, v80, v81
	v_mfma_f32_32x32x16_bf16 v[2:17], v[110:113], v[22:25], v[2:17]
	ds_read_b64_tr_b16 v[20:21], v201 offset:0xa00
	ds_read_b64_tr_b16 v[34:35], v201 offset:0x1200
	ds_read_b64_tr_b16 v[36:37], v201 offset:0x1a00
	ds_read_b64_tr_b16 v[38:39], v201 offset:0x2200
	ds_read_b64_tr_b16 v[40:41], v201 offset:0x2a00
	ds_read_b64_tr_b16 v[42:43], v201 offset:0x3200
	ds_read_b64_tr_b16 v[44:45], v201 offset:0x3a00
	v_mfma_f32_32x32x16_bf16 v[2:17], v[98:101], v[26:29], v[2:17]
	s_waitcnt lgkmcnt(0)
	v_max3_f32 v22, v30, v50, v51
	v_max3_f32 v22, v22, v52, v53
	v_max3_f32 v22, v22, v54, v55
	v_max3_f32 v22, v22, v56, v57
	v_max3_f32 v22, v22, v58, v59
	v_max3_f32 v46, v22, v60, v61
	v_mfma_f32_32x32x16_bf16 v[18:33], v[106:109], v[18:21], 0
	v_max3_f32 v46, v46, v62, v63
	v_max3_f32 v46, v46, v64, v65
	v_mov_b32_e32 v47, v46
	s_nop 1
	v_permlane32_swap_b32_e32 v46, v47
	v_max_f32_e32 v47, v47, v47
	v_max_f32_e32 v46, v46, v46
	v_mfma_f32_32x32x16_bf16 v[18:33], v[102:105], v[34:37], v[18:33]
	v_max_f32_e32 v34, v46, v47
	v_sub_f32_e32 v35, v34, v82
	v_max_f32_e32 v34, v82, v34
	v_cmp_ge_f32_e32 vcc, s25, v35
	v_sub_f32_e32 v35, v82, v34
	v_mul_f32_e32 v35, 0x3e0293ee, v35
	v_exp_f32_e32 v35, v35
	v_mfma_f32_32x32x16_bf16 v[18:33], v[110:113], v[38:41], v[18:33]
	s_cmp_eq_u64 vcc, exec
	s_cselect_b64 vcc, -1, 0
	v_cndmask_b32_e32 v218, v34, v82, vcc
	v_cndmask_b32_e64 v200, v35, 1.0, vcc
	ds_read_b64_tr_b16 v[34:35], v201 offset:0x400
	ds_read_b64_tr_b16 v[36:37], v201 offset:0xc00
	ds_read_b64_tr_b16 v[164:165], v201 offset:0x1400
	v_mfma_f32_32x32x16_bf16 v[18:33], v[98:101], v[42:45], v[18:33]
	ds_read_b64_tr_b16 v[166:167], v201 offset:0x1c00
	ds_read_b64_tr_b16 v[168:169], v201 offset:0x2400
	ds_read_b64_tr_b16 v[170:171], v201 offset:0x2c00
	ds_read_b64_tr_b16 v[172:173], v201 offset:0x3400
	ds_read_b64_tr_b16 v[174:175], v201 offset:0x3c00
	s_waitcnt lgkmcnt(0)
; #define SBAR() __builtin_amdgcn_sched_barrier(0)
; #define SLOAD(i, k0) do { const long to_ = (long)(k0) * ldk * 2; const char* vt_ = (const char*)Vh + to_; const char* kt_ = (const char*)Kh + to_; \
;     sr_[i].vs0 = *(const bf16x8*)(vt_ + toff); sr_[i].vs1 = *(const bf16x8*)(vt_ + h32 + toff); \
;     sr_[i].ks0 = *(const bf16x8*)(kt_ + toff); sr_[i].ks1 = *(const bf16x8*)(kt_ + h32 + toff); } while (0)
; #define SWAIT() do { if constexpr (SDEPTH == 2) asm volatile("s_waitcnt vmcnt(4)" ::: "memory"); else asm volatile("s_waitcnt vmcnt(0)" ::: "memory"); } while (0)
; #define RESC(a) do { if (__any((a) < 1.f)) { if (hi == 0) al_l[r32] = (a); asm volatile("s_waitcnt lgkmcnt(0)" ::: "memory"); \
;     for (int d = 0; d < 4; ++d) for (int r = 0; r < 16; ++r) o[d][r] *= al_l[crow(r, hi)]; } } while (0)
; #define MASK(P0, P1, k0) do { if constexpr (MODE == 1) { const int k0_ = (k0); \
;     if ((k0_ + 63 - qw0 > 128) || (k0_ - (qw0 + 31) < -128)) maskwin(P0, P1, k0_ - (qw0 + r32) + 128 + 4 * hi); } } while (0)
; template <int MODE, int QMODE> ...
;     ...
;   if (wid >= 4) __builtin_amdgcn_s_setprio(1);
;   f32x16 pA0, pA1, pB0, pB1; float mnA, mnB, alA, alB; bf16x8 pa0, pa1, pa2, pa3; const int NT = seq / KVBLK;
;   constexpr int SE = 0, SO = SDEPTH - 1;
;   SLOAD(SE, 0); asm volatile("s_waitcnt vmcnt(0)" ::: "memory"); SWRITE(0, SE); __syncthreads();
;   qkt(pA0, pA1, K_lds, qr, r32, hi); MASK(pA0, pA1, 0); partialSM(pA0, pA1, m_reg, mnA, alA);
;   SLOAD(SO, KVBLK); if constexpr (SDEPTH == 2) { if (2 < NT) SLOAD(SE, 2 * KVBLK); }
;   SWAIT(); SWRITE(1, SO); __syncthreads();
;   for (int j = 1; j + 1 < NT; j += 2) {
;     SBAR(); qkt(pB0, pB1, (bf16*)((char*)K_lds + SHM_K), qr, r32, hi);
;     finishSM(pA0, pA1, alA, l_reg, pa0, pa1, pa2, pa3); SBAR();
;     SLOAD(SO, (j + SDEPTH) * KVBLK); SBAR();
;     PVSM(vb0, pB0, pB1, j * KVBLK, mnB, alB);
;     __syncthreads(); SWAIT(); SWRITE(0, SE);
;     RESC(alB); __syncthreads();
	v_mfma_f32_32x32x16_bf16 v[34:49], v[106:109], v[34:37], 0
	v_mul_f32_e32 v176, 0xbe0293ee, v218
	v_fma_f32 v96, v80, s12, v176
	v_fma_f32 v97, v81, s12, v176
	v_fma_f32 v94, v78, s12, v176
	v_fma_f32 v95, v79, s12, v176
	v_pk_fma_f32 v[92:93], v[76:77], s[12:13], v[176:177] op_sel_hi:[1,0,0]
	v_pk_fma_f32 v[90:91], v[74:75], s[12:13], v[176:177] op_sel_hi:[1,0,0]
	v_pk_fma_f32 v[88:89], v[72:73], s[12:13], v[176:177] op_sel_hi:[1,0,0]
	v_pk_fma_f32 v[86:87], v[70:71], s[12:13], v[176:177] op_sel_hi:[1,0,0]
	v_mfma_f32_32x32x16_bf16 v[34:49], v[102:105], v[164:167], v[34:49]
	v_fma_f32 v84, v68, s12, v176
	v_fma_f32 v85, v69, s12, v176
	v_fma_f32 v82, v66, s12, v176
	v_fma_f32 v83, v67, s12, v176
	v_fma_f32 v80, v64, s12, v176
	v_fma_f32 v81, v65, s12, v176
	v_pk_fma_f32 v[78:79], v[62:63], s[12:13], v[176:177] op_sel_hi:[1,0,0]
	v_pk_fma_f32 v[76:77], v[60:61], s[12:13], v[176:177] op_sel_hi:[1,0,0]
	v_pk_fma_f32 v[74:75], v[58:59], s[12:13], v[176:177] op_sel_hi:[1,0,0]
	v_pk_fma_f32 v[72:73], v[56:57], s[12:13], v[176:177] op_sel_hi:[1,0,0]
	v_mfma_f32_32x32x16_bf16 v[34:49], v[110:113], v[168:171], v[34:49]
	v_fma_f32 v70, v54, s12, v176
	v_fma_f32 v71, v55, s12, v176
	v_fma_f32 v68, v52, s12, v176
	v_fma_f32 v69, v53, s12, v176
	v_fma_f32 v66, v50, s12, v176
	v_fma_f32 v67, v51, s12, v176
	ds_read_b64_tr_b16 v[50:51], v201 offset:0x600
	ds_read_b64_tr_b16 v[52:53], v201 offset:0xe00
	ds_read_b64_tr_b16 v[164:165], v201 offset:0x1600
	ds_read_b64_tr_b16 v[166:167], v201 offset:0x1e00
	v_mfma_f32_32x32x16_bf16 v[34:49], v[98:101], v[172:175], v[34:49]
	ds_read_b64_tr_b16 v[168:169], v201 offset:0x2600
	ds_read_b64_tr_b16 v[170:171], v201 offset:0x2e00
	ds_read_b64_tr_b16 v[180:181], v201 offset:0x3600
	ds_read_b64_tr_b16 v[182:183], v201 offset:0x3e00
	s_waitcnt lgkmcnt(0)
	v_mfma_f32_32x32x16_bf16 v[50:65], v[106:109], v[50:53], 0
	v_exp_f32_e32 v82, v82
	v_exp_f32_e32 v83, v83
	v_exp_f32_e32 v84, v84
	v_exp_f32_e32 v85, v85
	v_exp_f32_e32 v86, v86
	v_exp_f32_e32 v87, v87
	v_exp_f32_e32 v88, v88
	v_mfma_f32_32x32x16_bf16 v[50:65], v[102:105], v[164:167], v[50:65]
	v_exp_f32_e32 v89, v89
	v_exp_f32_e32 v90, v90
	v_exp_f32_e32 v91, v91
	v_exp_f32_e32 v92, v92
	v_exp_f32_e32 v93, v93
	v_exp_f32_e32 v94, v94
	v_exp_f32_e32 v95, v95
	v_mfma_f32_32x32x16_bf16 v[50:65], v[110:113], v[168:171], v[50:65]
	v_exp_f32_e32 v96, v96
	v_exp_f32_e32 v97, v97
	v_mfma_f32_32x32x16_bf16 v[50:65], v[98:101], v[180:183], v[50:65]
	s_barrier
	s_waitcnt vmcnt(0)
	v_cmp_gt_f32_e32 vcc, 1.0, v200
	s_waitcnt vmcnt(3)
	ds_write_b128 v216, v[114:117]
	s_waitcnt vmcnt(2)
	ds_write_b128 v217, v[118:121]
	s_waitcnt vmcnt(1)
	ds_write_b128 v214, v[122:125] offset:32768
	s_waitcnt vmcnt(0)
	ds_write_b128 v215, v[126:129] offset:32768
	s_cbranch_vccz .LBB0_296
	s_and_saveexec_b64 s[20:21], s[4:5]
	ds_write_b32 v197, v200 offset:128
	s_or_b64 exec, exec, s[20:21]
	s_waitcnt lgkmcnt(0)
	v_add_u32_e32 v110, s59, v194
	ds_read_b128 v[98:101], v110 offset:224
	ds_read_b128 v[102:105], v110 offset:192
	ds_read_b128 v[106:109], v110 offset:160
	ds_read_b128 v[110:113], v110 offset:128
	s_waitcnt lgkmcnt(3)
	v_pk_mul_f32 v[14:15], v[14:15], v[98:99]
	s_waitcnt lgkmcnt(2)
	v_pk_mul_f32 v[10:11], v[10:11], v[102:103]
	s_waitcnt lgkmcnt(1)
	v_pk_mul_f32 v[6:7], v[6:7], v[106:107]
	v_pk_mul_f32 v[16:17], v[16:17], v[100:101]
	v_pk_mul_f32 v[12:13], v[12:13], v[104:105]
	v_pk_mul_f32 v[8:9], v[8:9], v[108:109]
	s_waitcnt lgkmcnt(0)
	v_pk_mul_f32 v[4:5], v[4:5], v[112:113]
	v_pk_mul_f32 v[2:3], v[2:3], v[110:111]
	v_pk_mul_f32 v[30:31], v[30:31], v[98:99]
	v_pk_mul_f32 v[26:27], v[26:27], v[102:103]
	v_pk_mul_f32 v[22:23], v[22:23], v[106:107]
	v_pk_mul_f32 v[32:33], v[32:33], v[100:101]
	v_pk_mul_f32 v[28:29], v[28:29], v[104:105]
	v_pk_mul_f32 v[24:25], v[24:25], v[108:109]
	v_pk_mul_f32 v[20:21], v[20:21], v[112:113]
	v_pk_mul_f32 v[18:19], v[18:19], v[110:111]
	v_pk_mul_f32 v[46:47], v[46:47], v[98:99]
	v_pk_mul_f32 v[42:43], v[42:43], v[102:103]
	v_pk_mul_f32 v[38:39], v[38:39], v[106:107]
	v_pk_mul_f32 v[48:49], v[48:49], v[100:101]
	v_pk_mul_f32 v[44:45], v[44:45], v[104:105]
	v_pk_mul_f32 v[40:41], v[40:41], v[108:109]
	v_pk_mul_f32 v[36:37], v[36:37], v[112:113]
	v_pk_mul_f32 v[34:35], v[34:35], v[110:111]
	v_pk_mul_f32 v[62:63], v[62:63], v[98:99]
	v_pk_mul_f32 v[58:59], v[58:59], v[102:103]
	v_pk_mul_f32 v[54:55], v[54:55], v[106:107]
	v_pk_mul_f32 v[64:65], v[64:65], v[100:101]
	v_pk_mul_f32 v[60:61], v[60:61], v[104:105]
	v_pk_mul_f32 v[56:57], v[56:57], v[108:109]
	v_pk_mul_f32 v[52:53], v[52:53], v[112:113]
	v_pk_mul_f32 v[50:51], v[50:51], v[110:111]

; #define SEAM(k) do { if (IN(k) && IN((k) + 1)) grid.sync(); } while (0)
; __global__ void __launch_bounds__(NWAVES * 64, 2) hymba_fwd(Params P) {
;     ...
;     SEAM(3);
;     SEAM(4);
.LBB0_350:
	s_cmp_lt_i32 s70, 5
	s_cselect_b64 s[4:5], -1, 0
	s_cmp_gt_i32 s71, 5
	s_cselect_b64 s[2:3], -1, 0
	s_and_b64 s[4:5], s[4:5], s[2:3]
	s_andn2_b64 vcc, exec, s[4:5]
	s_branch .LBB0_362

; #define PG8_STAGE(bufoff, gbase, voff) do { _Pragma("unroll") for (int _i = 0; _i < 2; ++_i) \
;         __builtin_amdgcn_global_load_lds((const unsigned*)((const char*)(gbase) + (voff)[_i]), (PG8_LAS unsigned*)(lds + (bufoff) + ldsw + _i * 8192), 16, 0, 0); } while (0)
; #define PG8_LDA(dst, b, h) do { _Pragma("unroll") for (int m = 0; m < 4; ++m) _Pragma("unroll") for (int k = 0; k < 2; ++k) dst[m][k] = *(const PG8_LAS bf16x8*)(lds + PG8_SA(b, h) + aoff + m * 2048 + k * 1024); } while (0)
; #define PG8_LDB(dst, b, h) do { _Pragma("unroll") for (int n = 0; n < 2; ++n) _Pragma("unroll") for (int k = 0; k < 2; ++k) dst[n][k] = *(const PG8_LAS bf16x8*)(lds + PG8_SB(b, h) + boff + n * 2048 + k * 1024); } while (0)
; #define PG8_MMA(ai, bj, At, Bt) do { __builtin_amdgcn_s_setprio(1); _Pragma("unroll") for (int m = 0; m < 4; ++m) _Pragma("unroll") for (int n = 0; n < 2; ++n) _Pragma("unroll") for (int k = 0; k < 2; ++k) \
;         acc[ai][bj][m][n] = __builtin_amdgcn_mfma_f32_16x16x32_bf16(Bt[n][k], At[m][k], acc[ai][bj][m][n], 0, 0, 0); __builtin_amdgcn_s_setprio(0); } while (0)
; #define PG8_WAIT_V(n) asm volatile("s_waitcnt vmcnt(" #n ")" ::: "memory")
; #define PG8_WAIT_L(n) asm volatile("s_waitcnt lgkmcnt(" #n ")" ::: "memory")
; #define PG8_BAR __builtin_amdgcn_s_barrier()
; #define PG8_SCHED __builtin_amdgcn_sched_barrier(0)
; template <class Epi, class Sched, bool ALIGN_EPI = false, bool SP2 = false, bool KSEG = false>
; __device__ __forceinline__ void gemm_phase(PG8_LAS unsigned char* lds, const Gemm g, const Sched& S, const Epi& E) {
;     ...
;             const char* a2 = last ? nA : cA + (size_t)(t + 2) * kstep; const char* b2 = last ? nB : cB + (size_t)(t + 2) * kstep;
;             const char* a3 = a2 + kstep; const char* b3 = b2 + kstep;
;             if (last && has_next) S.a_ready(nxt);
;             if constexpr (SP2) {
;             PG8_LDB(B0, 0, 0); PG8_LDB(B1, 0, 1); PG8_SCHED; PG8_LDA(At, 0, 0); PG8_STAGE(PG8_SA(1, 1), a1 + hstep, voffA);
;             PG8_WAIT_V(8); PG8_WAIT_L(0); PG8_BAR; PG8_MMA(0, 0, At, B0); PG8_MMA(0, 1, At, B1); PG8_BAR; PG8_SCHED;
;             PG8_LDA(At, 0, 1); PG8_STAGE(PG8_SB(0, 0), b2, voffB); PG8_STAGE(PG8_SB(0, 1), b2 + hstep, voffB); PG8_STAGE(PG8_SA(0, 0), a2, voffA);
;             PG8_WAIT_V(8); PG8_WAIT_L(0); PG8_BAR; PG8_MMA(1, 0, At, B0); PG8_MMA(1, 1, At, B1); PG8_BAR; PG8_SCHED;
.LBB0_497:
	ds_read_b128 v[148:151], v168
	ds_read_b128 v[172:175], v168 offset:1024
	ds_read_b128 v[176:179], v168 offset:2048
	ds_read_b128 v[180:183], v168 offset:3072
	ds_read_b128 v[184:187], v169
	ds_read_b128 v[188:191], v169 offset:1024
	ds_read_b128 v[192:195], v169 offset:2048
	ds_read_b128 v[196:199], v169 offset:3072
	s_add_u32 s33, s36, 0xfff80080
	s_addc_u32 s38, s37, -1
	s_cmp_eq_u32 s62, 28
	s_cselect_b32 s41, s25, s38
	s_cselect_b32 s40, s58, s33
	s_cselect_b32 s39, s23, s61
	s_cselect_b32 s38, s59, s60
	s_add_u32 s98, s36, 0xfff80000
	s_addc_u32 s99, s37, -1
	v_lshl_add_u64 v[232:233], s[98:99], 0, v[132:133]
	s_mov_b32 m0, s52
	s_nop 0
	global_load_lds_dwordx4 v[232:233], off
	v_lshl_add_u64 v[232:233], s[98:99], 0, v[136:137]
	s_mov_b32 m0, s53
	s_nop 0
	global_load_lds_dwordx4 v[232:233], off
	v_lshl_add_u64 v[232:233], s[36:37], 0, v[140:141]
	s_add_i32 m0, s31, 0xc000
	ds_read_b128 v[200:203], v170
	ds_read_b128 v[204:207], v170 offset:1024
	ds_read_b128 v[208:211], v170 offset:2048
	ds_read_b128 v[212:215], v170 offset:3072
	ds_read_b128 v[216:219], v170 offset:4096
	ds_read_b128 v[220:223], v170 offset:5120
	ds_read_b128 v[224:227], v170 offset:6144
	ds_read_b128 v[228:231], v170 offset:7168
	global_load_lds_dwordx4 v[232:233], off
	v_lshl_add_u64 v[232:233], s[36:37], 0, v[142:143]
	s_add_i32 m0, s31, 0xe000
	s_nop 0
	global_load_lds_dwordx4 v[232:233], off
	s_waitcnt vmcnt(8)
	s_waitcnt lgkmcnt(0)
	s_barrier
	s_setprio 1
	s_waitcnt lgkmcnt(0)
	v_mfma_f32_16x16x32_bf16 v[126:129], v[148:151], v[200:203], v[126:129]
	v_mfma_f32_16x16x32_bf16 v[122:125], v[176:179], v[200:203], v[122:125]
	v_mfma_f32_16x16x32_bf16 v[110:113], v[148:151], v[208:211], v[110:113]
	v_mfma_f32_16x16x32_bf16 v[106:109], v[176:179], v[208:211], v[106:109]
	v_mfma_f32_16x16x32_bf16 v[94:97], v[148:151], v[216:219], v[94:97]
	v_mfma_f32_16x16x32_bf16 v[90:93], v[176:179], v[216:219], v[90:93]
	v_mfma_f32_16x16x32_bf16 v[78:81], v[148:151], v[224:227], v[78:81]
	v_mfma_f32_16x16x32_bf16 v[74:77], v[176:179], v[224:227], v[74:77]
	v_mfma_f32_16x16x32_bf16 v[126:129], v[172:175], v[204:207], v[126:129]
	v_mfma_f32_16x16x32_bf16 v[122:125], v[180:183], v[204:207], v[122:125]
	v_mfma_f32_16x16x32_bf16 v[110:113], v[172:175], v[212:215], v[110:113]
	v_mfma_f32_16x16x32_bf16 v[106:109], v[180:183], v[212:215], v[106:109]
	v_mfma_f32_16x16x32_bf16 v[94:97], v[172:175], v[220:223], v[94:97]
	v_mfma_f32_16x16x32_bf16 v[90:93], v[180:183], v[220:223], v[90:93]
	v_mfma_f32_16x16x32_bf16 v[78:81], v[172:175], v[228:231], v[78:81]
	v_mfma_f32_16x16x32_bf16 v[74:77], v[180:183], v[228:231], v[74:77]
	s_setprio 0
	s_setprio 1
	v_mfma_f32_16x16x32_bf16 v[118:121], v[184:187], v[200:203], v[118:121]
	v_mfma_f32_16x16x32_bf16 v[114:117], v[192:195], v[200:203], v[114:117]
	v_mfma_f32_16x16x32_bf16 v[102:105], v[184:187], v[208:211], v[102:105]
	v_mfma_f32_16x16x32_bf16 v[98:101], v[192:195], v[208:211], v[98:101]
	v_mfma_f32_16x16x32_bf16 v[86:89], v[184:187], v[216:219], v[86:89]
	v_mfma_f32_16x16x32_bf16 v[82:85], v[192:195], v[216:219], v[82:85]
	v_mfma_f32_16x16x32_bf16 v[70:73], v[184:187], v[224:227], v[70:73]
	v_mfma_f32_16x16x32_bf16 v[66:69], v[192:195], v[224:227], v[66:69]
	v_mfma_f32_16x16x32_bf16 v[118:121], v[188:191], v[204:207], v[118:121]
	v_mfma_f32_16x16x32_bf16 v[114:117], v[196:199], v[204:207], v[114:117]
	v_mfma_f32_16x16x32_bf16 v[102:105], v[188:191], v[212:215], v[102:105]
	v_mfma_f32_16x16x32_bf16 v[98:101], v[196:199], v[212:215], v[98:101]
	v_mfma_f32_16x16x32_bf16 v[86:89], v[188:191], v[220:223], v[86:89]
	v_mfma_f32_16x16x32_bf16 v[82:85], v[196:199], v[220:223], v[82:85]
	v_mfma_f32_16x16x32_bf16 v[70:73], v[188:191], v[228:231], v[70:73]
	v_mfma_f32_16x16x32_bf16 v[66:69], v[196:199], v[228:231], v[66:69]
	s_setprio 0
	s_barrier
	s_add_i32 s33, s54, s43
	v_lshl_add_u64 v[232:233], s[38:39], 0, v[134:135]
	s_mov_b32 m0, s33
	ds_read_b128 v[200:203], v170 offset:16384
	ds_read_b128 v[204:207], v170 offset:17408
	ds_read_b128 v[208:211], v170 offset:18432
	ds_read_b128 v[212:215], v170 offset:19456
	ds_read_b128 v[216:219], v170 offset:20480
	ds_read_b128 v[220:223], v170 offset:21504
	ds_read_b128 v[224:227], v170 offset:22528
	ds_read_b128 v[228:231], v170 offset:23552
	global_load_lds_dwordx4 v[232:233], off
	s_add_i32 m0, s33, 0x2000
	s_add_u32 s64, s38, 0x80000
	v_lshl_add_u64 v[234:235], s[38:39], 0, v[138:139]
	s_addc_u32 s65, s39, 0
	s_add_i32 s33, s55, s43
	global_load_lds_dwordx4 v[234:235], off
	v_lshl_add_u64 v[236:237], s[64:65], 0, v[134:135]
	s_mov_b32 m0, s33
	s_nop 0
	global_load_lds_dwordx4 v[236:237], off
	v_lshl_add_u64 v[236:237], s[64:65], 0, v[138:139]
	s_add_i32 m0, s33, 0x2000
	s_nop 0
	global_load_lds_dwordx4 v[236:237], off
	s_waitcnt vmcnt(6)
	s_waitcnt lgkmcnt(0)
	s_barrier
; #define PG8_STAGE(bufoff, gbase, voff) do { _Pragma("unroll") for (int _i = 0; _i < 2; ++_i) \
;         __builtin_amdgcn_global_load_lds((const unsigned*)((const char*)(gbase) + (voff)[_i]), (PG8_LAS unsigned*)(lds + (bufoff) + ldsw + _i * 8192), 16, 0, 0); } while (0)
; #define PG8_LDA(dst, b, h) do { _Pragma("unroll") for (int m = 0; m < 4; ++m) _Pragma("unroll") for (int k = 0; k < 2; ++k) dst[m][k] = *(const PG8_LAS bf16x8*)(lds + PG8_SA(b, h) + aoff + m * 2048 + k * 1024); } while (0)
; #define PG8_LDB(dst, b, h) do { _Pragma("unroll") for (int n = 0; n < 2; ++n) _Pragma("unroll") for (int k = 0; k < 2; ++k) dst[n][k] = *(const PG8_LAS bf16x8*)(lds + PG8_SB(b, h) + boff + n * 2048 + k * 1024); } while (0)
; #define PG8_MMA(ai, bj, At, Bt) do { __builtin_amdgcn_s_setprio(1); _Pragma("unroll") for (int m = 0; m < 4; ++m) _Pragma("unroll") for (int n = 0; n < 2; ++n) _Pragma("unroll") for (int k = 0; k < 2; ++k) \
;         acc[ai][bj][m][n] = __builtin_amdgcn_mfma_f32_16x16x32_bf16(Bt[n][k], At[m][k], acc[ai][bj][m][n], 0, 0, 0); __builtin_amdgcn_s_setprio(0); } while (0)
; #define PG8_WAIT_V(n) asm volatile("s_waitcnt vmcnt(" #n ")" ::: "memory")
; #define PG8_WAIT_L(n) asm volatile("s_waitcnt lgkmcnt(" #n ")" ::: "memory")
; #define PG8_BAR __builtin_amdgcn_s_barrier()
; #define PG8_SCHED __builtin_amdgcn_sched_barrier(0)
; template <class Epi, class Sched, bool ALIGN_EPI = false, bool SP2 = false, bool KSEG = false>
; __device__ __forceinline__ void gemm_phase(PG8_LAS unsigned char* lds, const Gemm g, const Sched& S, const Epi& E) {
;     ...
;             PG8_WAIT_V(8); PG8_WAIT_L(0); PG8_BAR; PG8_MMA(1, 0, At, B0); PG8_MMA(1, 1, At, B1); PG8_BAR; PG8_SCHED;
;             PG8_LDB(B0, 1, 0); PG8_LDB(B1, 1, 1); PG8_SCHED; PG8_LDA(At, 1, 0); PG8_STAGE(PG8_SA(0, 1), a2 + hstep, voffA);
;             PG8_WAIT_V(8); PG8_WAIT_L(0); PG8_BAR; PG8_MMA(0, 0, At, B0); PG8_MMA(0, 1, At, B1); PG8_BAR; PG8_SCHED;
	s_setprio 1
	s_waitcnt lgkmcnt(0)
	v_mfma_f32_16x16x32_bf16 v[62:65], v[148:151], v[200:203], v[62:65]
	v_mfma_f32_16x16x32_bf16 v[58:61], v[176:179], v[200:203], v[58:61]
	v_mfma_f32_16x16x32_bf16 v[46:49], v[148:151], v[208:211], v[46:49]
	v_mfma_f32_16x16x32_bf16 v[42:45], v[176:179], v[208:211], v[42:45]
	v_mfma_f32_16x16x32_bf16 v[30:33], v[148:151], v[216:219], v[30:33]
	v_mfma_f32_16x16x32_bf16 v[26:29], v[176:179], v[216:219], v[26:29]
	v_mfma_f32_16x16x32_bf16 v[14:17], v[148:151], v[224:227], v[14:17]
	v_mfma_f32_16x16x32_bf16 v[10:13], v[176:179], v[224:227], v[10:13]
	v_mfma_f32_16x16x32_bf16 v[62:65], v[172:175], v[204:207], v[62:65]
	v_mfma_f32_16x16x32_bf16 v[58:61], v[180:183], v[204:207], v[58:61]
	v_mfma_f32_16x16x32_bf16 v[46:49], v[172:175], v[212:215], v[46:49]
	v_mfma_f32_16x16x32_bf16 v[42:45], v[180:183], v[212:215], v[42:45]
	v_mfma_f32_16x16x32_bf16 v[30:33], v[172:175], v[220:223], v[30:33]
	v_mfma_f32_16x16x32_bf16 v[26:29], v[180:183], v[220:223], v[26:29]
	v_mfma_f32_16x16x32_bf16 v[14:17], v[172:175], v[228:231], v[14:17]
	v_mfma_f32_16x16x32_bf16 v[10:13], v[180:183], v[228:231], v[10:13]
	s_setprio 0
	s_setprio 1
	v_mfma_f32_16x16x32_bf16 v[54:57], v[184:187], v[200:203], v[54:57]
	v_mfma_f32_16x16x32_bf16 v[50:53], v[192:195], v[200:203], v[50:53]
	v_mfma_f32_16x16x32_bf16 v[38:41], v[184:187], v[208:211], v[38:41]
	v_mfma_f32_16x16x32_bf16 v[34:37], v[192:195], v[208:211], v[34:37]
	v_mfma_f32_16x16x32_bf16 v[22:25], v[184:187], v[216:219], v[22:25]
	v_mfma_f32_16x16x32_bf16 v[18:21], v[192:195], v[216:219], v[18:21]
	v_mfma_f32_16x16x32_bf16 v[6:9], v[184:187], v[224:227], v[6:9]
	v_mfma_f32_16x16x32_bf16 v[2:5], v[192:195], v[224:227], v[2:5]
	v_mfma_f32_16x16x32_bf16 v[54:57], v[188:191], v[204:207], v[54:57]
	v_mfma_f32_16x16x32_bf16 v[50:53], v[196:199], v[204:207], v[50:53]
	v_mfma_f32_16x16x32_bf16 v[38:41], v[188:191], v[212:215], v[38:41]
	v_mfma_f32_16x16x32_bf16 v[34:37], v[196:199], v[212:215], v[34:37]
	v_mfma_f32_16x16x32_bf16 v[22:25], v[188:191], v[220:223], v[22:25]
	v_mfma_f32_16x16x32_bf16 v[18:21], v[196:199], v[220:223], v[18:21]
	v_mfma_f32_16x16x32_bf16 v[6:9], v[188:191], v[228:231], v[6:9]
	v_mfma_f32_16x16x32_bf16 v[2:5], v[196:199], v[228:231], v[2:5]
	s_setprio 0
	s_barrier
	s_add_i32 s33, 0, 0x18000
	s_add_i32 s63, 0, 0x1c000
	v_add_u32_e32 v180, s33, v166
	v_add_u32_e32 v196, s63, v166
	ds_read_b128 v[148:151], v180
	ds_read_b128 v[172:175], v180 offset:1024
	ds_read_b128 v[176:179], v180 offset:2048
	ds_read_b128 v[180:183], v180 offset:3072
	ds_read_b128 v[184:187], v196
	ds_read_b128 v[188:191], v196 offset:1024
	ds_read_b128 v[192:195], v196 offset:2048
	ds_read_b128 v[196:199], v196 offset:3072
	v_lshl_add_u64 v[240:241], s[40:41], 0, v[132:133]
	s_mov_b32 m0, s31
	s_nop 0
	global_load_lds_dwordx4 v[240:241], off
	v_lshl_add_u64 v[240:241], s[40:41], 0, v[136:137]
	s_mov_b32 m0, s45
	s_nop 0
	global_load_lds_dwordx4 v[240:241], off
	s_add_u32 s40, s40, 0x80000
	s_addc_u32 s41, s41, 0
	s_mov_b32 m0, s49
	v_lshl_add_u64 v[240:241], s[40:41], 0, v[132:133]
	ds_read_b128 v[200:203], v170 offset:32768
	ds_read_b128 v[204:207], v170 offset:33792
	ds_read_b128 v[208:211], v170 offset:34816
	ds_read_b128 v[212:215], v170 offset:35840
	ds_read_b128 v[216:219], v170 offset:36864
	ds_read_b128 v[220:223], v170 offset:37888
	ds_read_b128 v[224:227], v170 offset:38912
	ds_read_b128 v[228:231], v170 offset:39936
	global_load_lds_dwordx4 v[240:241], off
	v_lshl_add_u64 v[240:241], s[40:41], 0, v[136:137]
	s_mov_b32 m0, s50
	s_nop 0
	global_load_lds_dwordx4 v[240:241], off
	s_waitcnt vmcnt(8)
	s_waitcnt lgkmcnt(0)
	s_barrier
; #define PG8_STAGE(bufoff, gbase, voff) do { _Pragma("unroll") for (int _i = 0; _i < 2; ++_i) \
;         __builtin_amdgcn_global_load_lds((const unsigned*)((const char*)(gbase) + (voff)[_i]), (PG8_LAS unsigned*)(lds + (bufoff) + ldsw + _i * 8192), 16, 0, 0); } while (0)
; #define PG8_LDA(dst, b, h) do { _Pragma("unroll") for (int m = 0; m < 4; ++m) _Pragma("unroll") for (int k = 0; k < 2; ++k) dst[m][k] = *(const PG8_LAS bf16x8*)(lds + PG8_SA(b, h) + aoff + m * 2048 + k * 1024); } while (0)
; #define PG8_MMA(ai, bj, At, Bt) do { __builtin_amdgcn_s_setprio(1); _Pragma("unroll") for (int m = 0; m < 4; ++m) _Pragma("unroll") for (int n = 0; n < 2; ++n) _Pragma("unroll") for (int k = 0; k < 2; ++k) \
;         acc[ai][bj][m][n] = __builtin_amdgcn_mfma_f32_16x16x32_bf16(Bt[n][k], At[m][k], acc[ai][bj][m][n], 0, 0, 0); __builtin_amdgcn_s_setprio(0); } while (0)
; #define PG8_WAIT_V(n) asm volatile("s_waitcnt vmcnt(" #n ")" ::: "memory")
; #define PG8_WAIT_L(n) asm volatile("s_waitcnt lgkmcnt(" #n ")" ::: "memory")
; #define PG8_BAR __builtin_amdgcn_s_barrier()
; #define PG8_SCHED __builtin_amdgcn_sched_barrier(0)
; template <class Epi, class Sched, bool ALIGN_EPI = false, bool SP2 = false, bool KSEG = false>
; __device__ __forceinline__ void gemm_phase(PG8_LAS unsigned char* lds, const Gemm g, const Sched& S, const Epi& E) {
;     ...
;             PG8_WAIT_V(8); PG8_WAIT_L(0); PG8_BAR; PG8_MMA(0, 0, At, B0); PG8_MMA(0, 1, At, B1); PG8_BAR; PG8_SCHED;
;             PG8_LDA(At, 1, 1); PG8_STAGE(PG8_SB(1, 0), b3, voffB); PG8_STAGE(PG8_SB(1, 1), b3 + hstep, voffB); PG8_STAGE(PG8_SA(1, 0), a3, voffA);
;             PG8_WAIT_V(8); PG8_WAIT_L(0); PG8_BAR; PG8_MMA(1, 0, At, B0); PG8_MMA(1, 1, At, B1); PG8_BAR; PG8_SCHED;
	s_setprio 1
	s_waitcnt lgkmcnt(0)
	v_mfma_f32_16x16x32_bf16 v[126:129], v[148:151], v[200:203], v[126:129]
	v_mfma_f32_16x16x32_bf16 v[122:125], v[176:179], v[200:203], v[122:125]
	v_mfma_f32_16x16x32_bf16 v[110:113], v[148:151], v[208:211], v[110:113]
	v_mfma_f32_16x16x32_bf16 v[106:109], v[176:179], v[208:211], v[106:109]
	v_mfma_f32_16x16x32_bf16 v[94:97], v[148:151], v[216:219], v[94:97]
	v_mfma_f32_16x16x32_bf16 v[90:93], v[176:179], v[216:219], v[90:93]
	v_mfma_f32_16x16x32_bf16 v[78:81], v[148:151], v[224:227], v[78:81]
	v_mfma_f32_16x16x32_bf16 v[74:77], v[176:179], v[224:227], v[74:77]
	v_mfma_f32_16x16x32_bf16 v[126:129], v[172:175], v[204:207], v[126:129]
	v_mfma_f32_16x16x32_bf16 v[122:125], v[180:183], v[204:207], v[122:125]
	v_mfma_f32_16x16x32_bf16 v[110:113], v[172:175], v[212:215], v[110:113]
	v_mfma_f32_16x16x32_bf16 v[106:109], v[180:183], v[212:215], v[106:109]
	v_mfma_f32_16x16x32_bf16 v[94:97], v[172:175], v[220:223], v[94:97]
	v_mfma_f32_16x16x32_bf16 v[90:93], v[180:183], v[220:223], v[90:93]
	v_mfma_f32_16x16x32_bf16 v[78:81], v[172:175], v[228:231], v[78:81]
	v_mfma_f32_16x16x32_bf16 v[74:77], v[180:183], v[228:231], v[74:77]
	s_setprio 0
	s_setprio 1
	v_mfma_f32_16x16x32_bf16 v[118:121], v[184:187], v[200:203], v[118:121]
	v_mfma_f32_16x16x32_bf16 v[114:117], v[192:195], v[200:203], v[114:117]
	v_mfma_f32_16x16x32_bf16 v[102:105], v[184:187], v[208:211], v[102:105]
	v_mfma_f32_16x16x32_bf16 v[98:101], v[192:195], v[208:211], v[98:101]
	v_mfma_f32_16x16x32_bf16 v[86:89], v[184:187], v[216:219], v[86:89]
	v_mfma_f32_16x16x32_bf16 v[82:85], v[192:195], v[216:219], v[82:85]
	v_mfma_f32_16x16x32_bf16 v[70:73], v[184:187], v[224:227], v[70:73]
	v_mfma_f32_16x16x32_bf16 v[66:69], v[192:195], v[224:227], v[66:69]
	v_mfma_f32_16x16x32_bf16 v[118:121], v[188:191], v[204:207], v[118:121]
	v_mfma_f32_16x16x32_bf16 v[114:117], v[196:199], v[204:207], v[114:117]
	v_mfma_f32_16x16x32_bf16 v[102:105], v[188:191], v[212:215], v[102:105]
	v_mfma_f32_16x16x32_bf16 v[98:101], v[196:199], v[212:215], v[98:101]
	v_mfma_f32_16x16x32_bf16 v[86:89], v[188:191], v[220:223], v[86:89]
	v_mfma_f32_16x16x32_bf16 v[82:85], v[196:199], v[220:223], v[82:85]
	v_mfma_f32_16x16x32_bf16 v[70:73], v[188:191], v[228:231], v[70:73]
	v_mfma_f32_16x16x32_bf16 v[66:69], v[196:199], v[228:231], v[66:69]
	s_setprio 0
	s_barrier
	s_add_i32 s33, s33, s43
	v_lshl_add_u64 v[232:233], v[232:233], 0, s[10:11]
	s_mov_b32 m0, s33
	ds_read_b128 v[200:203], v170 offset:49152
	ds_read_b128 v[204:207], v170 offset:50176
	ds_read_b128 v[208:211], v170 offset:51200
	ds_read_b128 v[212:215], v170 offset:52224
	ds_read_b128 v[216:219], v170 offset:53248
	ds_read_b128 v[220:223], v170 offset:54272
	ds_read_b128 v[224:227], v170 offset:55296
	ds_read_b128 v[228:231], v170 offset:56320
	global_load_lds_dwordx4 v[232:233], off
	s_add_i32 m0, s33, 0x2000
	s_add_u32 s38, s38, 0x80080
	v_lshl_add_u64 v[232:233], v[234:235], 0, s[10:11]
	s_addc_u32 s39, s39, 0
	s_add_i32 s33, s63, s43
	global_load_lds_dwordx4 v[232:233], off
	v_lshl_add_u64 v[232:233], s[38:39], 0, v[134:135]
	s_mov_b32 m0, s33
	s_nop 0
	global_load_lds_dwordx4 v[232:233], off
	v_lshl_add_u64 v[232:233], s[38:39], 0, v[138:139]
	s_add_i32 m0, s33, 0x2000
	s_nop 0
	global_load_lds_dwordx4 v[232:233], off
	s_waitcnt vmcnt(6)
	s_waitcnt lgkmcnt(0)
	s_barrier
	s_setprio 1
	s_waitcnt lgkmcnt(0)
	v_mfma_f32_16x16x32_bf16 v[62:65], v[148:151], v[200:203], v[62:65]
	v_mfma_f32_16x16x32_bf16 v[58:61], v[176:179], v[200:203], v[58:61]
	v_mfma_f32_16x16x32_bf16 v[46:49], v[148:151], v[208:211], v[46:49]
	v_mfma_f32_16x16x32_bf16 v[42:45], v[176:179], v[208:211], v[42:45]
	v_mfma_f32_16x16x32_bf16 v[30:33], v[148:151], v[216:219], v[30:33]
	v_mfma_f32_16x16x32_bf16 v[26:29], v[176:179], v[216:219], v[26:29]
	v_mfma_f32_16x16x32_bf16 v[14:17], v[148:151], v[224:227], v[14:17]
	v_mfma_f32_16x16x32_bf16 v[10:13], v[176:179], v[224:227], v[10:13]
	v_mfma_f32_16x16x32_bf16 v[62:65], v[172:175], v[204:207], v[62:65]
	v_mfma_f32_16x16x32_bf16 v[58:61], v[180:183], v[204:207], v[58:61]
	v_mfma_f32_16x16x32_bf16 v[46:49], v[172:175], v[212:215], v[46:49]
	v_mfma_f32_16x16x32_bf16 v[42:45], v[180:183], v[212:215], v[42:45]
	v_mfma_f32_16x16x32_bf16 v[30:33], v[172:175], v[220:223], v[30:33]
	v_mfma_f32_16x16x32_bf16 v[26:29], v[180:183], v[220:223], v[26:29]
	v_mfma_f32_16x16x32_bf16 v[14:17], v[172:175], v[228:231], v[14:17]
	v_mfma_f32_16x16x32_bf16 v[10:13], v[180:183], v[228:231], v[10:13]
	s_setprio 0
	s_setprio 1
	v_mfma_f32_16x16x32_bf16 v[54:57], v[184:187], v[200:203], v[54:57]
	v_mfma_f32_16x16x32_bf16 v[50:53], v[192:195], v[200:203], v[50:53]
	v_mfma_f32_16x16x32_bf16 v[38:41], v[184:187], v[208:211], v[38:41]
	v_mfma_f32_16x16x32_bf16 v[34:37], v[192:195], v[208:211], v[34:37]
	v_mfma_f32_16x16x32_bf16 v[22:25], v[184:187], v[216:219], v[22:25]
	v_mfma_f32_16x16x32_bf16 v[18:21], v[192:195], v[216:219], v[18:21]
	v_mfma_f32_16x16x32_bf16 v[6:9], v[184:187], v[224:227], v[6:9]
	v_mfma_f32_16x16x32_bf16 v[2:5], v[192:195], v[224:227], v[2:5]
	v_mfma_f32_16x16x32_bf16 v[54:57], v[188:191], v[204:207], v[54:57]
	v_mfma_f32_16x16x32_bf16 v[50:53], v[196:199], v[204:207], v[50:53]
	v_mfma_f32_16x16x32_bf16 v[38:41], v[188:191], v[212:215], v[38:41]
	v_mfma_f32_16x16x32_bf16 v[34:37], v[196:199], v[212:215], v[34:37]
	v_mfma_f32_16x16x32_bf16 v[22:25], v[188:191], v[220:223], v[22:25]
	v_mfma_f32_16x16x32_bf16 v[18:21], v[196:199], v[220:223], v[18:21]
	v_mfma_f32_16x16x32_bf16 v[6:9], v[188:191], v[228:231], v[6:9]
	v_mfma_f32_16x16x32_bf16 v[2:5], v[196:199], v[228:231], v[2:5]
	s_setprio 0
	s_barrier
	s_add_i32 s62, s62, 2
	s_add_u32 s36, s36, 0x100
	s_addc_u32 s37, s37, 0
	s_add_u32 s60, s60, 0x100
	s_addc_u32 s61, s61, 0
	s_cmp_gt_u32 s62, 29
	s_cbranch_scc0 .LBB0_497
	s_and_b64 vcc, exec, s[12:13]
	s_cbranch_vccz .LBB0_500
	s_barrier

; #define PG8_STAGE(bufoff, gbase, voff) do { _Pragma("unroll") for (int _i = 0; _i < 2; ++_i) \
;         __builtin_amdgcn_global_load_lds((const unsigned*)((const char*)(gbase) + (voff)[_i]), (PG8_LAS unsigned*)(lds + (bufoff) + ldsw + _i * 8192), 16, 0, 0); } while (0)
; #define PG8_LDA(dst, b, h) do { _Pragma("unroll") for (int m = 0; m < 4; ++m) _Pragma("unroll") for (int k = 0; k < 2; ++k) dst[m][k] = *(const PG8_LAS bf16x8*)(lds + PG8_SA(b, h) + aoff + m * 2048 + k * 1024); } while (0)
; #define PG8_LDB(dst, b, h) do { _Pragma("unroll") for (int n = 0; n < 2; ++n) _Pragma("unroll") for (int k = 0; k < 2; ++k) dst[n][k] = *(const PG8_LAS bf16x8*)(lds + PG8_SB(b, h) + boff + n * 2048 + k * 1024); } while (0)
; #define PG8_MMA(ai, bj, At, Bt) do { __builtin_amdgcn_s_setprio(1); _Pragma("unroll") for (int m = 0; m < 4; ++m) _Pragma("unroll") for (int n = 0; n < 2; ++n) _Pragma("unroll") for (int k = 0; k < 2; ++k) \
;         acc[ai][bj][m][n] = __builtin_amdgcn_mfma_f32_16x16x32_bf16(Bt[n][k], At[m][k], acc[ai][bj][m][n], 0, 0, 0); __builtin_amdgcn_s_setprio(0); } while (0)
; #define PG8_WAIT_V(n) asm volatile("s_waitcnt vmcnt(" #n ")" ::: "memory")
; #define PG8_WAIT_L(n) asm volatile("s_waitcnt lgkmcnt(" #n ")" ::: "memory")
; #define PG8_BAR __builtin_amdgcn_s_barrier()
; #define PG8_SCHED __builtin_amdgcn_sched_barrier(0)
; template <class Epi, class Sched, bool ALIGN_EPI = false, bool SP2 = false, bool KSEG = false>
; __device__ __forceinline__ void gemm_phase(PG8_LAS unsigned char* lds, const Gemm g, const Sched& S, const Epi& E) {
;     ...
;             const char* a2 = last ? nA : cA + (size_t)(t + 2) * kstep; const char* b2 = last ? nB : cB + (size_t)(t + 2) * kstep;
;             const char* a3 = a2 + kstep; const char* b3 = b2 + kstep;
;             if (last && has_next) S.a_ready(nxt);
;             if constexpr (SP2) {
;             PG8_LDB(B0, 0, 0); PG8_LDB(B1, 0, 1); PG8_SCHED; PG8_LDA(At, 0, 0); PG8_STAGE(PG8_SA(1, 1), a1 + hstep, voffA);
;             PG8_WAIT_V(8); PG8_WAIT_L(0); PG8_BAR; PG8_MMA(0, 0, At, B0); PG8_MMA(0, 1, At, B1); PG8_BAR; PG8_SCHED;
;             PG8_LDA(At, 0, 1); PG8_STAGE(PG8_SB(0, 0), b2, voffB); PG8_STAGE(PG8_SB(0, 1), b2 + hstep, voffB); PG8_STAGE(PG8_SA(0, 0), a2, voffA);
;             PG8_WAIT_V(8); PG8_WAIT_L(0); PG8_BAR; PG8_MMA(1, 0, At, B0); PG8_MMA(1, 1, At, B1); PG8_BAR; PG8_SCHED;
.LBB0_537:
	ds_read_b128 v[154:157], v173
	ds_read_b128 v[176:179], v173 offset:1024
	ds_read_b128 v[180:183], v173 offset:2048
	ds_read_b128 v[184:187], v173 offset:3072
	ds_read_b128 v[188:191], v174
	ds_read_b128 v[192:195], v174 offset:1024
	ds_read_b128 v[196:199], v174 offset:2048
	ds_read_b128 v[200:203], v174 offset:3072
	s_add_u32 s33, s36, 0xffea0080
	s_addc_u32 s38, s37, -1
	s_cmpk_eq_i32 s64, 0x54
	s_cselect_b32 s41, s13, s38
	s_cselect_b32 s40, s12, s33
	s_cselect_b32 s39, s31, s63
	s_cselect_b32 s38, s30, s62
	s_add_u32 s98, s36, 0xffea0000
	s_addc_u32 s99, s37, -1
	v_lshl_add_u64 v[236:237], s[98:99], 0, v[140:141]
	s_mov_b32 m0, s54
	s_nop 0
	global_load_lds_dwordx4 v[236:237], off
	v_lshl_add_u64 v[236:237], s[98:99], 0, v[142:143]
	s_mov_b32 m0, s55
	s_nop 0
	global_load_lds_dwordx4 v[236:237], off
	v_lshl_add_u64 v[236:237], s[36:37], 0, v[146:147]
	s_add_i32 m0, s44, 0xc000
	ds_read_b128 v[204:207], v175
	ds_read_b128 v[208:211], v175 offset:1024
	ds_read_b128 v[212:215], v175 offset:2048
	ds_read_b128 v[216:219], v175 offset:3072
	ds_read_b128 v[220:223], v175 offset:4096
	ds_read_b128 v[224:227], v175 offset:5120
	ds_read_b128 v[228:231], v175 offset:6144
	ds_read_b128 v[232:235], v175 offset:7168
	global_load_lds_dwordx4 v[236:237], off
	v_lshl_add_u64 v[236:237], s[36:37], 0, v[148:149]
	s_add_i32 m0, s44, 0xe000
	s_nop 0
	global_load_lds_dwordx4 v[236:237], off
	s_waitcnt vmcnt(8)
	s_waitcnt lgkmcnt(0)
	s_barrier
	s_setprio 1
	s_waitcnt lgkmcnt(0)
	v_mfma_f32_16x16x32_bf16 v[126:129], v[154:157], v[204:207], v[126:129]
	v_mfma_f32_16x16x32_bf16 v[122:125], v[180:183], v[204:207], v[122:125]
	v_mfma_f32_16x16x32_bf16 v[110:113], v[154:157], v[212:215], v[110:113]
	v_mfma_f32_16x16x32_bf16 v[106:109], v[180:183], v[212:215], v[106:109]
	v_mfma_f32_16x16x32_bf16 v[94:97], v[154:157], v[220:223], v[94:97]
	v_mfma_f32_16x16x32_bf16 v[90:93], v[180:183], v[220:223], v[90:93]
	v_mfma_f32_16x16x32_bf16 v[78:81], v[154:157], v[228:231], v[78:81]
	v_mfma_f32_16x16x32_bf16 v[74:77], v[180:183], v[228:231], v[74:77]
	v_mfma_f32_16x16x32_bf16 v[126:129], v[176:179], v[208:211], v[126:129]
	v_mfma_f32_16x16x32_bf16 v[122:125], v[184:187], v[208:211], v[122:125]
	v_mfma_f32_16x16x32_bf16 v[110:113], v[176:179], v[216:219], v[110:113]
	v_mfma_f32_16x16x32_bf16 v[106:109], v[184:187], v[216:219], v[106:109]
	v_mfma_f32_16x16x32_bf16 v[94:97], v[176:179], v[224:227], v[94:97]
	v_mfma_f32_16x16x32_bf16 v[90:93], v[184:187], v[224:227], v[90:93]
	v_mfma_f32_16x16x32_bf16 v[78:81], v[176:179], v[232:235], v[78:81]
	v_mfma_f32_16x16x32_bf16 v[74:77], v[184:187], v[232:235], v[74:77]
	s_setprio 0
	s_setprio 1
	v_mfma_f32_16x16x32_bf16 v[118:121], v[188:191], v[204:207], v[118:121]
	v_mfma_f32_16x16x32_bf16 v[114:117], v[196:199], v[204:207], v[114:117]
	v_mfma_f32_16x16x32_bf16 v[102:105], v[188:191], v[212:215], v[102:105]
	v_mfma_f32_16x16x32_bf16 v[98:101], v[196:199], v[212:215], v[98:101]
	v_mfma_f32_16x16x32_bf16 v[86:89], v[188:191], v[220:223], v[86:89]
	v_mfma_f32_16x16x32_bf16 v[82:85], v[196:199], v[220:223], v[82:85]
	v_mfma_f32_16x16x32_bf16 v[70:73], v[188:191], v[228:231], v[70:73]
	v_mfma_f32_16x16x32_bf16 v[66:69], v[196:199], v[228:231], v[66:69]
	v_mfma_f32_16x16x32_bf16 v[118:121], v[192:195], v[208:211], v[118:121]
	v_mfma_f32_16x16x32_bf16 v[114:117], v[200:203], v[208:211], v[114:117]
	v_mfma_f32_16x16x32_bf16 v[102:105], v[192:195], v[216:219], v[102:105]
	v_mfma_f32_16x16x32_bf16 v[98:101], v[200:203], v[216:219], v[98:101]
	v_mfma_f32_16x16x32_bf16 v[86:89], v[192:195], v[224:227], v[86:89]
	v_mfma_f32_16x16x32_bf16 v[82:85], v[200:203], v[224:227], v[82:85]
	v_mfma_f32_16x16x32_bf16 v[70:73], v[192:195], v[232:235], v[70:73]
	v_mfma_f32_16x16x32_bf16 v[66:69], v[200:203], v[232:235], v[66:69]
	s_setprio 0
	s_barrier
	s_add_i32 s33, s56, s43
	v_lshl_add_u64 v[236:237], s[38:39], 0, v[130:131]
	s_mov_b32 m0, s33
	ds_read_b128 v[204:207], v175 offset:16384
	ds_read_b128 v[208:211], v175 offset:17408
	ds_read_b128 v[212:215], v175 offset:18432
	ds_read_b128 v[216:219], v175 offset:19456
	ds_read_b128 v[220:223], v175 offset:20480
	ds_read_b128 v[224:227], v175 offset:21504
	ds_read_b128 v[228:231], v175 offset:22528
	ds_read_b128 v[232:235], v175 offset:23552
	global_load_lds_dwordx4 v[236:237], off
	s_add_i32 m0, s33, 0x2000
	s_add_u32 s66, s38, 0x160000
	v_lshl_add_u64 v[238:239], s[38:39], 0, v[144:145]
	s_addc_u32 s67, s39, 0
	s_add_i32 s33, s57, s43
	global_load_lds_dwordx4 v[238:239], off
	v_lshl_add_u64 v[240:241], s[66:67], 0, v[130:131]
	s_mov_b32 m0, s33
	s_nop 0
	global_load_lds_dwordx4 v[240:241], off
	v_lshl_add_u64 v[240:241], s[66:67], 0, v[144:145]
	s_add_i32 m0, s33, 0x2000
	s_nop 0
	global_load_lds_dwordx4 v[240:241], off
	s_waitcnt vmcnt(6)
	s_waitcnt lgkmcnt(0)
	s_barrier
; #define PG8_STAGE(bufoff, gbase, voff) do { _Pragma("unroll") for (int _i = 0; _i < 2; ++_i) \
;         __builtin_amdgcn_global_load_lds((const unsigned*)((const char*)(gbase) + (voff)[_i]), (PG8_LAS unsigned*)(lds + (bufoff) + ldsw + _i * 8192), 16, 0, 0); } while (0)
; #define PG8_LDA(dst, b, h) do { _Pragma("unroll") for (int m = 0; m < 4; ++m) _Pragma("unroll") for (int k = 0; k < 2; ++k) dst[m][k] = *(const PG8_LAS bf16x8*)(lds + PG8_SA(b, h) + aoff + m * 2048 + k * 1024); } while (0)
; #define PG8_LDB(dst, b, h) do { _Pragma("unroll") for (int n = 0; n < 2; ++n) _Pragma("unroll") for (int k = 0; k < 2; ++k) dst[n][k] = *(const PG8_LAS bf16x8*)(lds + PG8_SB(b, h) + boff + n * 2048 + k * 1024); } while (0)
; #define PG8_MMA(ai, bj, At, Bt) do { __builtin_amdgcn_s_setprio(1); _Pragma("unroll") for (int m = 0; m < 4; ++m) _Pragma("unroll") for (int n = 0; n < 2; ++n) _Pragma("unroll") for (int k = 0; k < 2; ++k) \
;         acc[ai][bj][m][n] = __builtin_amdgcn_mfma_f32_16x16x32_bf16(Bt[n][k], At[m][k], acc[ai][bj][m][n], 0, 0, 0); __builtin_amdgcn_s_setprio(0); } while (0)
; #define PG8_WAIT_V(n) asm volatile("s_waitcnt vmcnt(" #n ")" ::: "memory")
; #define PG8_WAIT_L(n) asm volatile("s_waitcnt lgkmcnt(" #n ")" ::: "memory")
; #define PG8_BAR __builtin_amdgcn_s_barrier()
; #define PG8_SCHED __builtin_amdgcn_sched_barrier(0)
; template <class Epi, class Sched, bool ALIGN_EPI = false, bool SP2 = false, bool KSEG = false>
; __device__ __forceinline__ void gemm_phase(PG8_LAS unsigned char* lds, const Gemm g, const Sched& S, const Epi& E) {
;     ...
;             PG8_WAIT_V(8); PG8_WAIT_L(0); PG8_BAR; PG8_MMA(1, 0, At, B0); PG8_MMA(1, 1, At, B1); PG8_BAR; PG8_SCHED;
;             PG8_LDB(B0, 1, 0); PG8_LDB(B1, 1, 1); PG8_SCHED; PG8_LDA(At, 1, 0); PG8_STAGE(PG8_SA(0, 1), a2 + hstep, voffA);
;             PG8_WAIT_V(8); PG8_WAIT_L(0); PG8_BAR; PG8_MMA(0, 0, At, B0); PG8_MMA(0, 1, At, B1); PG8_BAR; PG8_SCHED;
	s_setprio 1
	s_waitcnt lgkmcnt(0)
	v_mfma_f32_16x16x32_bf16 v[62:65], v[154:157], v[204:207], v[62:65]
	v_mfma_f32_16x16x32_bf16 v[58:61], v[180:183], v[204:207], v[58:61]
	v_mfma_f32_16x16x32_bf16 v[46:49], v[154:157], v[212:215], v[46:49]
	v_mfma_f32_16x16x32_bf16 v[42:45], v[180:183], v[212:215], v[42:45]
	v_mfma_f32_16x16x32_bf16 v[30:33], v[154:157], v[220:223], v[30:33]
	v_mfma_f32_16x16x32_bf16 v[26:29], v[180:183], v[220:223], v[26:29]
	v_mfma_f32_16x16x32_bf16 v[14:17], v[154:157], v[228:231], v[14:17]
	v_mfma_f32_16x16x32_bf16 v[10:13], v[180:183], v[228:231], v[10:13]
	v_mfma_f32_16x16x32_bf16 v[62:65], v[176:179], v[208:211], v[62:65]
	v_mfma_f32_16x16x32_bf16 v[58:61], v[184:187], v[208:211], v[58:61]
	v_mfma_f32_16x16x32_bf16 v[46:49], v[176:179], v[216:219], v[46:49]
	v_mfma_f32_16x16x32_bf16 v[42:45], v[184:187], v[216:219], v[42:45]
	v_mfma_f32_16x16x32_bf16 v[30:33], v[176:179], v[224:227], v[30:33]
	v_mfma_f32_16x16x32_bf16 v[26:29], v[184:187], v[224:227], v[26:29]
	v_mfma_f32_16x16x32_bf16 v[14:17], v[176:179], v[232:235], v[14:17]
	v_mfma_f32_16x16x32_bf16 v[10:13], v[184:187], v[232:235], v[10:13]
	s_setprio 0
	s_setprio 1
	v_mfma_f32_16x16x32_bf16 v[54:57], v[188:191], v[204:207], v[54:57]
	v_mfma_f32_16x16x32_bf16 v[50:53], v[196:199], v[204:207], v[50:53]
	v_mfma_f32_16x16x32_bf16 v[38:41], v[188:191], v[212:215], v[38:41]
	v_mfma_f32_16x16x32_bf16 v[34:37], v[196:199], v[212:215], v[34:37]
	v_mfma_f32_16x16x32_bf16 v[22:25], v[188:191], v[220:223], v[22:25]
	v_mfma_f32_16x16x32_bf16 v[18:21], v[196:199], v[220:223], v[18:21]
	v_mfma_f32_16x16x32_bf16 v[6:9], v[188:191], v[228:231], v[6:9]
	v_mfma_f32_16x16x32_bf16 v[2:5], v[196:199], v[228:231], v[2:5]
	v_mfma_f32_16x16x32_bf16 v[54:57], v[192:195], v[208:211], v[54:57]
	v_mfma_f32_16x16x32_bf16 v[50:53], v[200:203], v[208:211], v[50:53]
	v_mfma_f32_16x16x32_bf16 v[38:41], v[192:195], v[216:219], v[38:41]
	v_mfma_f32_16x16x32_bf16 v[34:37], v[200:203], v[216:219], v[34:37]
	v_mfma_f32_16x16x32_bf16 v[22:25], v[192:195], v[224:227], v[22:25]
	v_mfma_f32_16x16x32_bf16 v[18:21], v[200:203], v[224:227], v[18:21]
	v_mfma_f32_16x16x32_bf16 v[6:9], v[192:195], v[232:235], v[6:9]
	v_mfma_f32_16x16x32_bf16 v[2:5], v[200:203], v[232:235], v[2:5]
	s_setprio 0
	s_barrier
	s_add_i32 s33, 0, 0x18000
	s_add_i32 s65, 0, 0x1c000
	v_add_u32_e32 v184, s33, v171
	v_add_u32_e32 v200, s65, v171
	ds_read_b128 v[154:157], v184
	ds_read_b128 v[176:179], v184 offset:1024
	ds_read_b128 v[180:183], v184 offset:2048
	ds_read_b128 v[184:187], v184 offset:3072
	ds_read_b128 v[188:191], v200
	ds_read_b128 v[192:195], v200 offset:1024
	ds_read_b128 v[196:199], v200 offset:2048
	ds_read_b128 v[200:203], v200 offset:3072
	v_lshl_add_u64 v[244:245], s[40:41], 0, v[140:141]
	s_mov_b32 m0, s44
	s_nop 0
	global_load_lds_dwordx4 v[244:245], off
	v_lshl_add_u64 v[244:245], s[40:41], 0, v[142:143]
	s_mov_b32 m0, s45
	s_nop 0
	global_load_lds_dwordx4 v[244:245], off
	s_add_u32 s40, s40, 0x160000
	s_addc_u32 s41, s41, 0
	s_mov_b32 m0, s51
	v_lshl_add_u64 v[244:245], s[40:41], 0, v[140:141]
	ds_read_b128 v[204:207], v175 offset:32768
	ds_read_b128 v[208:211], v175 offset:33792
	ds_read_b128 v[212:215], v175 offset:34816
	ds_read_b128 v[216:219], v175 offset:35840
	ds_read_b128 v[220:223], v175 offset:36864
	ds_read_b128 v[224:227], v175 offset:37888
	ds_read_b128 v[228:231], v175 offset:38912
	ds_read_b128 v[232:235], v175 offset:39936
	global_load_lds_dwordx4 v[244:245], off
	v_lshl_add_u64 v[244:245], s[40:41], 0, v[142:143]
	s_mov_b32 m0, s52
	s_nop 0
	global_load_lds_dwordx4 v[244:245], off
	s_waitcnt vmcnt(8)
	s_waitcnt lgkmcnt(0)
	s_barrier
; #define PG8_STAGE(bufoff, gbase, voff) do { _Pragma("unroll") for (int _i = 0; _i < 2; ++_i) \
;         __builtin_amdgcn_global_load_lds((const unsigned*)((const char*)(gbase) + (voff)[_i]), (PG8_LAS unsigned*)(lds + (bufoff) + ldsw + _i * 8192), 16, 0, 0); } while (0)
; #define PG8_LDA(dst, b, h) do { _Pragma("unroll") for (int m = 0; m < 4; ++m) _Pragma("unroll") for (int k = 0; k < 2; ++k) dst[m][k] = *(const PG8_LAS bf16x8*)(lds + PG8_SA(b, h) + aoff + m * 2048 + k * 1024); } while (0)
; #define PG8_MMA(ai, bj, At, Bt) do { __builtin_amdgcn_s_setprio(1); _Pragma("unroll") for (int m = 0; m < 4; ++m) _Pragma("unroll") for (int n = 0; n < 2; ++n) _Pragma("unroll") for (int k = 0; k < 2; ++k) \
;         acc[ai][bj][m][n] = __builtin_amdgcn_mfma_f32_16x16x32_bf16(Bt[n][k], At[m][k], acc[ai][bj][m][n], 0, 0, 0); __builtin_amdgcn_s_setprio(0); } while (0)
; #define PG8_WAIT_V(n) asm volatile("s_waitcnt vmcnt(" #n ")" ::: "memory")
; #define PG8_WAIT_L(n) asm volatile("s_waitcnt lgkmcnt(" #n ")" ::: "memory")
; #define PG8_BAR __builtin_amdgcn_s_barrier()
; #define PG8_SCHED __builtin_amdgcn_sched_barrier(0)
; template <class Epi, class Sched, bool ALIGN_EPI = false, bool SP2 = false, bool KSEG = false>
; __device__ __forceinline__ void gemm_phase(PG8_LAS unsigned char* lds, const Gemm g, const Sched& S, const Epi& E) {
;     ...
;             PG8_WAIT_V(8); PG8_WAIT_L(0); PG8_BAR; PG8_MMA(0, 0, At, B0); PG8_MMA(0, 1, At, B1); PG8_BAR; PG8_SCHED;
;             PG8_LDA(At, 1, 1); PG8_STAGE(PG8_SB(1, 0), b3, voffB); PG8_STAGE(PG8_SB(1, 1), b3 + hstep, voffB); PG8_STAGE(PG8_SA(1, 0), a3, voffA);
;             PG8_WAIT_V(8); PG8_WAIT_L(0); PG8_BAR; PG8_MMA(1, 0, At, B0); PG8_MMA(1, 1, At, B1); PG8_BAR; PG8_SCHED;
	s_setprio 1
	s_waitcnt lgkmcnt(0)
	v_mfma_f32_16x16x32_bf16 v[126:129], v[154:157], v[204:207], v[126:129]
	v_mfma_f32_16x16x32_bf16 v[122:125], v[180:183], v[204:207], v[122:125]
	v_mfma_f32_16x16x32_bf16 v[110:113], v[154:157], v[212:215], v[110:113]
	v_mfma_f32_16x16x32_bf16 v[106:109], v[180:183], v[212:215], v[106:109]
	v_mfma_f32_16x16x32_bf16 v[94:97], v[154:157], v[220:223], v[94:97]
	v_mfma_f32_16x16x32_bf16 v[90:93], v[180:183], v[220:223], v[90:93]
	v_mfma_f32_16x16x32_bf16 v[78:81], v[154:157], v[228:231], v[78:81]
	v_mfma_f32_16x16x32_bf16 v[74:77], v[180:183], v[228:231], v[74:77]
	v_mfma_f32_16x16x32_bf16 v[126:129], v[176:179], v[208:211], v[126:129]
	v_mfma_f32_16x16x32_bf16 v[122:125], v[184:187], v[208:211], v[122:125]
	v_mfma_f32_16x16x32_bf16 v[110:113], v[176:179], v[216:219], v[110:113]
	v_mfma_f32_16x16x32_bf16 v[106:109], v[184:187], v[216:219], v[106:109]
	v_mfma_f32_16x16x32_bf16 v[94:97], v[176:179], v[224:227], v[94:97]
	v_mfma_f32_16x16x32_bf16 v[90:93], v[184:187], v[224:227], v[90:93]
	v_mfma_f32_16x16x32_bf16 v[78:81], v[176:179], v[232:235], v[78:81]
	v_mfma_f32_16x16x32_bf16 v[74:77], v[184:187], v[232:235], v[74:77]
	s_setprio 0
	s_setprio 1
	v_mfma_f32_16x16x32_bf16 v[118:121], v[188:191], v[204:207], v[118:121]
	v_mfma_f32_16x16x32_bf16 v[114:117], v[196:199], v[204:207], v[114:117]
	v_mfma_f32_16x16x32_bf16 v[102:105], v[188:191], v[212:215], v[102:105]
	v_mfma_f32_16x16x32_bf16 v[98:101], v[196:199], v[212:215], v[98:101]
	v_mfma_f32_16x16x32_bf16 v[86:89], v[188:191], v[220:223], v[86:89]
	v_mfma_f32_16x16x32_bf16 v[82:85], v[196:199], v[220:223], v[82:85]
	v_mfma_f32_16x16x32_bf16 v[70:73], v[188:191], v[228:231], v[70:73]
	v_mfma_f32_16x16x32_bf16 v[66:69], v[196:199], v[228:231], v[66:69]
	v_mfma_f32_16x16x32_bf16 v[118:121], v[192:195], v[208:211], v[118:121]
	v_mfma_f32_16x16x32_bf16 v[114:117], v[200:203], v[208:211], v[114:117]
	v_mfma_f32_16x16x32_bf16 v[102:105], v[192:195], v[216:219], v[102:105]
	v_mfma_f32_16x16x32_bf16 v[98:101], v[200:203], v[216:219], v[98:101]
	v_mfma_f32_16x16x32_bf16 v[86:89], v[192:195], v[224:227], v[86:89]
	v_mfma_f32_16x16x32_bf16 v[82:85], v[200:203], v[224:227], v[82:85]
	v_mfma_f32_16x16x32_bf16 v[70:73], v[192:195], v[232:235], v[70:73]
	v_mfma_f32_16x16x32_bf16 v[66:69], v[200:203], v[232:235], v[66:69]
	s_setprio 0
	s_barrier
	s_add_i32 s33, s33, s43
	v_lshl_add_u64 v[236:237], v[236:237], 0, s[26:27]
	s_mov_b32 m0, s33
	ds_read_b128 v[204:207], v175 offset:49152
	ds_read_b128 v[208:211], v175 offset:50176
	ds_read_b128 v[212:215], v175 offset:51200
	ds_read_b128 v[216:219], v175 offset:52224
	ds_read_b128 v[220:223], v175 offset:53248
	ds_read_b128 v[224:227], v175 offset:54272
	ds_read_b128 v[228:231], v175 offset:55296
	ds_read_b128 v[232:235], v175 offset:56320
	global_load_lds_dwordx4 v[236:237], off
	s_add_i32 m0, s33, 0x2000
	s_add_u32 s38, s38, 0x160080
	v_lshl_add_u64 v[236:237], v[238:239], 0, s[26:27]
	s_addc_u32 s39, s39, 0
	s_add_i32 s33, s65, s43
	global_load_lds_dwordx4 v[236:237], off
	v_lshl_add_u64 v[236:237], s[38:39], 0, v[130:131]
	s_mov_b32 m0, s33
	s_nop 0
	global_load_lds_dwordx4 v[236:237], off
	v_lshl_add_u64 v[236:237], s[38:39], 0, v[144:145]
	s_add_i32 m0, s33, 0x2000
	s_nop 0
	global_load_lds_dwordx4 v[236:237], off
	s_waitcnt vmcnt(6)
	s_waitcnt lgkmcnt(0)
	s_barrier
	s_setprio 1
	s_waitcnt lgkmcnt(0)
	v_mfma_f32_16x16x32_bf16 v[62:65], v[154:157], v[204:207], v[62:65]
	v_mfma_f32_16x16x32_bf16 v[58:61], v[180:183], v[204:207], v[58:61]
	v_mfma_f32_16x16x32_bf16 v[46:49], v[154:157], v[212:215], v[46:49]
	v_mfma_f32_16x16x32_bf16 v[42:45], v[180:183], v[212:215], v[42:45]
	v_mfma_f32_16x16x32_bf16 v[30:33], v[154:157], v[220:223], v[30:33]
	v_mfma_f32_16x16x32_bf16 v[26:29], v[180:183], v[220:223], v[26:29]
	v_mfma_f32_16x16x32_bf16 v[14:17], v[154:157], v[228:231], v[14:17]
	v_mfma_f32_16x16x32_bf16 v[10:13], v[180:183], v[228:231], v[10:13]
	v_mfma_f32_16x16x32_bf16 v[62:65], v[176:179], v[208:211], v[62:65]
	v_mfma_f32_16x16x32_bf16 v[58:61], v[184:187], v[208:211], v[58:61]
	v_mfma_f32_16x16x32_bf16 v[46:49], v[176:179], v[216:219], v[46:49]
	v_mfma_f32_16x16x32_bf16 v[42:45], v[184:187], v[216:219], v[42:45]
	v_mfma_f32_16x16x32_bf16 v[30:33], v[176:179], v[224:227], v[30:33]
	v_mfma_f32_16x16x32_bf16 v[26:29], v[184:187], v[224:227], v[26:29]
	v_mfma_f32_16x16x32_bf16 v[14:17], v[176:179], v[232:235], v[14:17]
	v_mfma_f32_16x16x32_bf16 v[10:13], v[184:187], v[232:235], v[10:13]
	s_setprio 0
	s_setprio 1
	v_mfma_f32_16x16x32_bf16 v[54:57], v[188:191], v[204:207], v[54:57]
	v_mfma_f32_16x16x32_bf16 v[50:53], v[196:199], v[204:207], v[50:53]
	v_mfma_f32_16x16x32_bf16 v[38:41], v[188:191], v[212:215], v[38:41]
	v_mfma_f32_16x16x32_bf16 v[34:37], v[196:199], v[212:215], v[34:37]
	v_mfma_f32_16x16x32_bf16 v[22:25], v[188:191], v[220:223], v[22:25]
	v_mfma_f32_16x16x32_bf16 v[18:21], v[196:199], v[220:223], v[18:21]
	v_mfma_f32_16x16x32_bf16 v[6:9], v[188:191], v[228:231], v[6:9]
	v_mfma_f32_16x16x32_bf16 v[2:5], v[196:199], v[228:231], v[2:5]
	v_mfma_f32_16x16x32_bf16 v[54:57], v[192:195], v[208:211], v[54:57]
	v_mfma_f32_16x16x32_bf16 v[50:53], v[200:203], v[208:211], v[50:53]
	v_mfma_f32_16x16x32_bf16 v[38:41], v[192:195], v[216:219], v[38:41]
	v_mfma_f32_16x16x32_bf16 v[34:37], v[200:203], v[216:219], v[34:37]
	v_mfma_f32_16x16x32_bf16 v[22:25], v[192:195], v[224:227], v[22:25]
	v_mfma_f32_16x16x32_bf16 v[18:21], v[200:203], v[224:227], v[18:21]
	v_mfma_f32_16x16x32_bf16 v[6:9], v[192:195], v[232:235], v[6:9]
	v_mfma_f32_16x16x32_bf16 v[2:5], v[200:203], v[232:235], v[2:5]
	s_setprio 0
	s_barrier
	s_add_i32 s64, s64, 2
	s_add_u32 s36, s36, 0x100
	s_addc_u32 s37, s37, 0
	s_add_u32 s62, s62, 0x100
	s_addc_u32 s63, s63, 0
	s_cmpk_gt_u32 s64, 0x55
	s_cbranch_scc0 .LBB0_537
	s_and_b64 vcc, exec, s[28:29]
	s_cbranch_vccz .LBB0_540
	s_barrier

; #define PG8_STAGE(bufoff, gbase, voff) do { _Pragma("unroll") for (int _i = 0; _i < 2; ++_i) \
;         __builtin_amdgcn_global_load_lds((const unsigned*)((const char*)(gbase) + (voff)[_i]), (PG8_LAS unsigned*)(lds + (bufoff) + ldsw + _i * 8192), 16, 0, 0); } while (0)
; #define PG8_LDA(dst, b, h) do { _Pragma("unroll") for (int m = 0; m < 4; ++m) _Pragma("unroll") for (int k = 0; k < 2; ++k) dst[m][k] = *(const PG8_LAS bf16x8*)(lds + PG8_SA(b, h) + aoff + m * 2048 + k * 1024); } while (0)
; #define PG8_LDB(dst, b, h) do { _Pragma("unroll") for (int n = 0; n < 2; ++n) _Pragma("unroll") for (int k = 0; k < 2; ++k) dst[n][k] = *(const PG8_LAS bf16x8*)(lds + PG8_SB(b, h) + boff + n * 2048 + k * 1024); } while (0)
; #define PG8_MMA(ai, bj, At, Bt) do { __builtin_amdgcn_s_setprio(1); _Pragma("unroll") for (int m = 0; m < 4; ++m) _Pragma("unroll") for (int n = 0; n < 2; ++n) _Pragma("unroll") for (int k = 0; k < 2; ++k) \
;         acc[ai][bj][m][n] = __builtin_amdgcn_mfma_f32_16x16x32_bf16(Bt[n][k], At[m][k], acc[ai][bj][m][n], 0, 0, 0); __builtin_amdgcn_s_setprio(0); } while (0)
; #define PG8_WAIT_V(n) asm volatile("s_waitcnt vmcnt(" #n ")" ::: "memory")
; #define PG8_WAIT_L(n) asm volatile("s_waitcnt lgkmcnt(" #n ")" ::: "memory")
; #define PG8_BAR __builtin_amdgcn_s_barrier()
; #define PG8_SCHED __builtin_amdgcn_sched_barrier(0)
; template <class Epi, class Sched, bool ALIGN_EPI = false, bool SP2 = false, bool KSEG = false>
; __device__ __forceinline__ void gemm_phase(PG8_LAS unsigned char* lds, const Gemm g, const Sched& S, const Epi& E) {
;     ...
;             const char* a2 = last ? nA : cA + (size_t)(t + 2) * kstep; const char* b2 = last ? nB : cB + (size_t)(t + 2) * kstep;
;             const char* a3 = a2 + kstep; const char* b3 = b2 + kstep;
;             if (last && has_next) S.a_ready(nxt);
;             if constexpr (SP2) {
;             PG8_LDB(B0, 0, 0); PG8_LDB(B1, 0, 1); PG8_SCHED; PG8_LDA(At, 0, 0); PG8_STAGE(PG8_SA(1, 1), a1 + hstep, voffA);
;             PG8_WAIT_V(8); PG8_WAIT_L(0); PG8_BAR; PG8_MMA(0, 0, At, B0); PG8_MMA(0, 1, At, B1); PG8_BAR; PG8_SCHED;
;             PG8_LDA(At, 0, 1); PG8_STAGE(PG8_SB(0, 0), b2, voffB); PG8_STAGE(PG8_SB(0, 1), b2 + hstep, voffB); PG8_STAGE(PG8_SA(0, 0), a2, voffA);
;             PG8_WAIT_V(8); PG8_WAIT_L(0); PG8_BAR; PG8_MMA(1, 0, At, B0); PG8_MMA(1, 1, At, B1); PG8_BAR; PG8_SCHED;
.LBB0_581:
	ds_read_b128 v[154:157], v160
	ds_read_b128 v[172:175], v160 offset:1024
	ds_read_b128 v[176:179], v160 offset:2048
	ds_read_b128 v[180:183], v160 offset:3072
	ds_read_b128 v[184:187], v161
	ds_read_b128 v[188:191], v161 offset:1024
	ds_read_b128 v[192:195], v161 offset:2048
	ds_read_b128 v[196:199], v161 offset:3072
	s_add_u32 s33, s40, 0xfff80080
	s_addc_u32 s42, s41, -1
	s_cmp_eq_u32 s79, 28
	s_cselect_b32 s45, s29, s42
	s_cselect_b32 s44, s65, s33
	s_cselect_b32 s43, s27, s78
	s_cselect_b32 s42, s66, s67
	s_add_u32 s98, s40, 0xfff80000
	s_addc_u32 s99, s41, -1
	v_lshl_add_u64 v[232:233], s[98:99], 0, v[132:133]
	s_mov_b32 m0, s60
	s_nop 0
	global_load_lds_dwordx4 v[232:233], off
	v_lshl_add_u64 v[232:233], s[98:99], 0, v[136:137]
	s_mov_b32 m0, s61
	s_nop 0
	global_load_lds_dwordx4 v[232:233], off
	v_lshl_add_u64 v[232:233], s[40:41], 0, v[146:147]
	s_add_i32 m0, s55, 0xc000
	ds_read_b128 v[200:203], v164
	ds_read_b128 v[204:207], v164 offset:1024
	ds_read_b128 v[208:211], v164 offset:2048
	ds_read_b128 v[212:215], v164 offset:3072
	ds_read_b128 v[216:219], v164 offset:4096
	ds_read_b128 v[220:223], v164 offset:5120
	ds_read_b128 v[224:227], v164 offset:6144
	ds_read_b128 v[228:231], v164 offset:7168
	global_load_lds_dwordx4 v[232:233], off
	v_lshl_add_u64 v[232:233], s[40:41], 0, v[148:149]
	s_add_i32 m0, s55, 0xe000
	s_nop 0
	global_load_lds_dwordx4 v[232:233], off
	s_waitcnt vmcnt(8)
	s_waitcnt lgkmcnt(0)
	s_barrier
	s_setprio 1
	s_waitcnt lgkmcnt(0)
	v_mfma_f32_16x16x32_bf16 v[126:129], v[154:157], v[200:203], v[126:129]
	v_mfma_f32_16x16x32_bf16 v[122:125], v[176:179], v[200:203], v[122:125]
	v_mfma_f32_16x16x32_bf16 v[110:113], v[154:157], v[208:211], v[110:113]
	v_mfma_f32_16x16x32_bf16 v[106:109], v[176:179], v[208:211], v[106:109]
	v_mfma_f32_16x16x32_bf16 v[94:97], v[154:157], v[216:219], v[94:97]
	v_mfma_f32_16x16x32_bf16 v[90:93], v[176:179], v[216:219], v[90:93]
	v_mfma_f32_16x16x32_bf16 v[78:81], v[154:157], v[224:227], v[78:81]
	v_mfma_f32_16x16x32_bf16 v[74:77], v[176:179], v[224:227], v[74:77]
	v_mfma_f32_16x16x32_bf16 v[126:129], v[172:175], v[204:207], v[126:129]
	v_mfma_f32_16x16x32_bf16 v[122:125], v[180:183], v[204:207], v[122:125]
	v_mfma_f32_16x16x32_bf16 v[110:113], v[172:175], v[212:215], v[110:113]
	v_mfma_f32_16x16x32_bf16 v[106:109], v[180:183], v[212:215], v[106:109]
	v_mfma_f32_16x16x32_bf16 v[94:97], v[172:175], v[220:223], v[94:97]
	v_mfma_f32_16x16x32_bf16 v[90:93], v[180:183], v[220:223], v[90:93]
	v_mfma_f32_16x16x32_bf16 v[78:81], v[172:175], v[228:231], v[78:81]
	v_mfma_f32_16x16x32_bf16 v[74:77], v[180:183], v[228:231], v[74:77]
	s_setprio 0
	s_setprio 1
	v_mfma_f32_16x16x32_bf16 v[118:121], v[184:187], v[200:203], v[118:121]
	v_mfma_f32_16x16x32_bf16 v[114:117], v[192:195], v[200:203], v[114:117]
	v_mfma_f32_16x16x32_bf16 v[102:105], v[184:187], v[208:211], v[102:105]
	v_mfma_f32_16x16x32_bf16 v[98:101], v[192:195], v[208:211], v[98:101]
	v_mfma_f32_16x16x32_bf16 v[86:89], v[184:187], v[216:219], v[86:89]
	v_mfma_f32_16x16x32_bf16 v[82:85], v[192:195], v[216:219], v[82:85]
	v_mfma_f32_16x16x32_bf16 v[70:73], v[184:187], v[224:227], v[70:73]
	v_mfma_f32_16x16x32_bf16 v[66:69], v[192:195], v[224:227], v[66:69]
	v_mfma_f32_16x16x32_bf16 v[118:121], v[188:191], v[204:207], v[118:121]
	v_mfma_f32_16x16x32_bf16 v[114:117], v[196:199], v[204:207], v[114:117]
	v_mfma_f32_16x16x32_bf16 v[102:105], v[188:191], v[212:215], v[102:105]
	v_mfma_f32_16x16x32_bf16 v[98:101], v[196:199], v[212:215], v[98:101]
	v_mfma_f32_16x16x32_bf16 v[86:89], v[188:191], v[220:223], v[86:89]
	v_mfma_f32_16x16x32_bf16 v[82:85], v[196:199], v[220:223], v[82:85]
	v_mfma_f32_16x16x32_bf16 v[70:73], v[188:191], v[228:231], v[70:73]
	v_mfma_f32_16x16x32_bf16 v[66:69], v[196:199], v[228:231], v[66:69]
	s_setprio 0
	s_barrier
	s_add_i32 s33, s62, s53
	v_lshl_add_u64 v[232:233], s[42:43], 0, v[134:135]
	s_mov_b32 m0, s33
	ds_read_b128 v[200:203], v164 offset:16384
	ds_read_b128 v[204:207], v164 offset:17408
	ds_read_b128 v[208:211], v164 offset:18432
	ds_read_b128 v[212:215], v164 offset:19456
	ds_read_b128 v[216:219], v164 offset:20480
	ds_read_b128 v[220:223], v164 offset:21504
	ds_read_b128 v[224:227], v164 offset:22528
	ds_read_b128 v[228:231], v164 offset:23552
	global_load_lds_dwordx4 v[232:233], off
	s_add_i32 m0, s33, 0x2000
	s_add_u32 s80, s42, 0x80000
	v_lshl_add_u64 v[234:235], s[42:43], 0, v[138:139]
	s_addc_u32 s81, s43, 0
	s_add_i32 s33, s63, s53
	global_load_lds_dwordx4 v[234:235], off
	v_lshl_add_u64 v[236:237], s[80:81], 0, v[134:135]
	s_mov_b32 m0, s33
	s_nop 0
	global_load_lds_dwordx4 v[236:237], off
	v_lshl_add_u64 v[236:237], s[80:81], 0, v[138:139]
	s_add_i32 m0, s33, 0x2000
	s_nop 0
	global_load_lds_dwordx4 v[236:237], off
	s_waitcnt vmcnt(6)
	s_waitcnt lgkmcnt(0)
	s_barrier
; #define PG8_STAGE(bufoff, gbase, voff) do { _Pragma("unroll") for (int _i = 0; _i < 2; ++_i) \
;         __builtin_amdgcn_global_load_lds((const unsigned*)((const char*)(gbase) + (voff)[_i]), (PG8_LAS unsigned*)(lds + (bufoff) + ldsw + _i * 8192), 16, 0, 0); } while (0)
; #define PG8_LDA(dst, b, h) do { _Pragma("unroll") for (int m = 0; m < 4; ++m) _Pragma("unroll") for (int k = 0; k < 2; ++k) dst[m][k] = *(const PG8_LAS bf16x8*)(lds + PG8_SA(b, h) + aoff + m * 2048 + k * 1024); } while (0)
; #define PG8_LDB(dst, b, h) do { _Pragma("unroll") for (int n = 0; n < 2; ++n) _Pragma("unroll") for (int k = 0; k < 2; ++k) dst[n][k] = *(const PG8_LAS bf16x8*)(lds + PG8_SB(b, h) + boff + n * 2048 + k * 1024); } while (0)
; #define PG8_MMA(ai, bj, At, Bt) do { __builtin_amdgcn_s_setprio(1); _Pragma("unroll") for (int m = 0; m < 4; ++m) _Pragma("unroll") for (int n = 0; n < 2; ++n) _Pragma("unroll") for (int k = 0; k < 2; ++k) \
;         acc[ai][bj][m][n] = __builtin_amdgcn_mfma_f32_16x16x32_bf16(Bt[n][k], At[m][k], acc[ai][bj][m][n], 0, 0, 0); __builtin_amdgcn_s_setprio(0); } while (0)
; #define PG8_WAIT_V(n) asm volatile("s_waitcnt vmcnt(" #n ")" ::: "memory")
; #define PG8_WAIT_L(n) asm volatile("s_waitcnt lgkmcnt(" #n ")" ::: "memory")
; #define PG8_BAR __builtin_amdgcn_s_barrier()
; #define PG8_SCHED __builtin_amdgcn_sched_barrier(0)
; template <class Epi, class Sched, bool ALIGN_EPI = false, bool SP2 = false, bool KSEG = false>
; __device__ __forceinline__ void gemm_phase(PG8_LAS unsigned char* lds, const Gemm g, const Sched& S, const Epi& E) {
;     ...
;             PG8_WAIT_V(8); PG8_WAIT_L(0); PG8_BAR; PG8_MMA(1, 0, At, B0); PG8_MMA(1, 1, At, B1); PG8_BAR; PG8_SCHED;
;             PG8_LDB(B0, 1, 0); PG8_LDB(B1, 1, 1); PG8_SCHED; PG8_LDA(At, 1, 0); PG8_STAGE(PG8_SA(0, 1), a2 + hstep, voffA);
;             PG8_WAIT_V(8); PG8_WAIT_L(0); PG8_BAR; PG8_MMA(0, 0, At, B0); PG8_MMA(0, 1, At, B1); PG8_BAR; PG8_SCHED;
	s_setprio 1
	s_waitcnt lgkmcnt(0)
	v_mfma_f32_16x16x32_bf16 v[62:65], v[154:157], v[200:203], v[62:65]
	v_mfma_f32_16x16x32_bf16 v[58:61], v[176:179], v[200:203], v[58:61]
	v_mfma_f32_16x16x32_bf16 v[46:49], v[154:157], v[208:211], v[46:49]
	v_mfma_f32_16x16x32_bf16 v[42:45], v[176:179], v[208:211], v[42:45]
	v_mfma_f32_16x16x32_bf16 v[30:33], v[154:157], v[216:219], v[30:33]
	v_mfma_f32_16x16x32_bf16 v[26:29], v[176:179], v[216:219], v[26:29]
	v_mfma_f32_16x16x32_bf16 v[14:17], v[154:157], v[224:227], v[14:17]
	v_mfma_f32_16x16x32_bf16 v[10:13], v[176:179], v[224:227], v[10:13]
	v_mfma_f32_16x16x32_bf16 v[62:65], v[172:175], v[204:207], v[62:65]
	v_mfma_f32_16x16x32_bf16 v[58:61], v[180:183], v[204:207], v[58:61]
	v_mfma_f32_16x16x32_bf16 v[46:49], v[172:175], v[212:215], v[46:49]
	v_mfma_f32_16x16x32_bf16 v[42:45], v[180:183], v[212:215], v[42:45]
	v_mfma_f32_16x16x32_bf16 v[30:33], v[172:175], v[220:223], v[30:33]
	v_mfma_f32_16x16x32_bf16 v[26:29], v[180:183], v[220:223], v[26:29]
	v_mfma_f32_16x16x32_bf16 v[14:17], v[172:175], v[228:231], v[14:17]
	v_mfma_f32_16x16x32_bf16 v[10:13], v[180:183], v[228:231], v[10:13]
	s_setprio 0
	s_setprio 1
	v_mfma_f32_16x16x32_bf16 v[54:57], v[184:187], v[200:203], v[54:57]
	v_mfma_f32_16x16x32_bf16 v[50:53], v[192:195], v[200:203], v[50:53]
	v_mfma_f32_16x16x32_bf16 v[38:41], v[184:187], v[208:211], v[38:41]
	v_mfma_f32_16x16x32_bf16 v[34:37], v[192:195], v[208:211], v[34:37]
	v_mfma_f32_16x16x32_bf16 v[22:25], v[184:187], v[216:219], v[22:25]
	v_mfma_f32_16x16x32_bf16 v[18:21], v[192:195], v[216:219], v[18:21]
	v_mfma_f32_16x16x32_bf16 v[6:9], v[184:187], v[224:227], v[6:9]
	v_mfma_f32_16x16x32_bf16 v[2:5], v[192:195], v[224:227], v[2:5]
	v_mfma_f32_16x16x32_bf16 v[54:57], v[188:191], v[204:207], v[54:57]
	v_mfma_f32_16x16x32_bf16 v[50:53], v[196:199], v[204:207], v[50:53]
	v_mfma_f32_16x16x32_bf16 v[38:41], v[188:191], v[212:215], v[38:41]
	v_mfma_f32_16x16x32_bf16 v[34:37], v[196:199], v[212:215], v[34:37]
	v_mfma_f32_16x16x32_bf16 v[22:25], v[188:191], v[220:223], v[22:25]
	v_mfma_f32_16x16x32_bf16 v[18:21], v[196:199], v[220:223], v[18:21]
	v_mfma_f32_16x16x32_bf16 v[6:9], v[188:191], v[228:231], v[6:9]
	v_mfma_f32_16x16x32_bf16 v[2:5], v[196:199], v[228:231], v[2:5]
	s_setprio 0
	s_barrier
	s_add_i32 s33, 0, 0x18000
	s_add_i32 s80, 0, 0x1c000
	v_add_u32_e32 v180, s33, v163
	v_add_u32_e32 v196, s80, v163
	ds_read_b128 v[154:157], v180
	ds_read_b128 v[172:175], v180 offset:1024
	ds_read_b128 v[176:179], v180 offset:2048
	ds_read_b128 v[180:183], v180 offset:3072
	ds_read_b128 v[184:187], v196
	ds_read_b128 v[188:191], v196 offset:1024
	ds_read_b128 v[192:195], v196 offset:2048
	ds_read_b128 v[196:199], v196 offset:3072
	v_lshl_add_u64 v[240:241], s[44:45], 0, v[132:133]
	s_mov_b32 m0, s55
	s_nop 0
	global_load_lds_dwordx4 v[240:241], off
	v_lshl_add_u64 v[240:241], s[44:45], 0, v[136:137]
	s_mov_b32 m0, s56
	s_nop 0
	global_load_lds_dwordx4 v[240:241], off
	s_add_u32 s44, s44, 0x80000
	s_addc_u32 s45, s45, 0
	s_mov_b32 m0, s57
	v_lshl_add_u64 v[240:241], s[44:45], 0, v[132:133]
	ds_read_b128 v[200:203], v164 offset:32768
	ds_read_b128 v[204:207], v164 offset:33792
	ds_read_b128 v[208:211], v164 offset:34816
	ds_read_b128 v[212:215], v164 offset:35840
	ds_read_b128 v[216:219], v164 offset:36864
	ds_read_b128 v[220:223], v164 offset:37888
	ds_read_b128 v[224:227], v164 offset:38912
	ds_read_b128 v[228:231], v164 offset:39936
	global_load_lds_dwordx4 v[240:241], off
	v_lshl_add_u64 v[240:241], s[44:45], 0, v[136:137]
	s_mov_b32 m0, s58
	s_nop 0
	global_load_lds_dwordx4 v[240:241], off
	s_waitcnt vmcnt(8)
	s_waitcnt lgkmcnt(0)
	s_barrier
; #define PG8_STAGE(bufoff, gbase, voff) do { _Pragma("unroll") for (int _i = 0; _i < 2; ++_i) \
;         __builtin_amdgcn_global_load_lds((const unsigned*)((const char*)(gbase) + (voff)[_i]), (PG8_LAS unsigned*)(lds + (bufoff) + ldsw + _i * 8192), 16, 0, 0); } while (0)
; #define PG8_LDA(dst, b, h) do { _Pragma("unroll") for (int m = 0; m < 4; ++m) _Pragma("unroll") for (int k = 0; k < 2; ++k) dst[m][k] = *(const PG8_LAS bf16x8*)(lds + PG8_SA(b, h) + aoff + m * 2048 + k * 1024); } while (0)
; #define PG8_MMA(ai, bj, At, Bt) do { __builtin_amdgcn_s_setprio(1); _Pragma("unroll") for (int m = 0; m < 4; ++m) _Pragma("unroll") for (int n = 0; n < 2; ++n) _Pragma("unroll") for (int k = 0; k < 2; ++k) \
;         acc[ai][bj][m][n] = __builtin_amdgcn_mfma_f32_16x16x32_bf16(Bt[n][k], At[m][k], acc[ai][bj][m][n], 0, 0, 0); __builtin_amdgcn_s_setprio(0); } while (0)
; #define PG8_WAIT_V(n) asm volatile("s_waitcnt vmcnt(" #n ")" ::: "memory")
; #define PG8_WAIT_L(n) asm volatile("s_waitcnt lgkmcnt(" #n ")" ::: "memory")
; #define PG8_BAR __builtin_amdgcn_s_barrier()
; #define PG8_SCHED __builtin_amdgcn_sched_barrier(0)
; template <class Epi, class Sched, bool ALIGN_EPI = false, bool SP2 = false, bool KSEG = false>
; __device__ __forceinline__ void gemm_phase(PG8_LAS unsigned char* lds, const Gemm g, const Sched& S, const Epi& E) {
;     ...
;             PG8_WAIT_V(8); PG8_WAIT_L(0); PG8_BAR; PG8_MMA(0, 0, At, B0); PG8_MMA(0, 1, At, B1); PG8_BAR; PG8_SCHED;
;             PG8_LDA(At, 1, 1); PG8_STAGE(PG8_SB(1, 0), b3, voffB); PG8_STAGE(PG8_SB(1, 1), b3 + hstep, voffB); PG8_STAGE(PG8_SA(1, 0), a3, voffA);
;             PG8_WAIT_V(8); PG8_WAIT_L(0); PG8_BAR; PG8_MMA(1, 0, At, B0); PG8_MMA(1, 1, At, B1); PG8_BAR; PG8_SCHED;
	s_setprio 1
	s_waitcnt lgkmcnt(0)
	v_mfma_f32_16x16x32_bf16 v[126:129], v[154:157], v[200:203], v[126:129]
	v_mfma_f32_16x16x32_bf16 v[122:125], v[176:179], v[200:203], v[122:125]
	v_mfma_f32_16x16x32_bf16 v[110:113], v[154:157], v[208:211], v[110:113]
	v_mfma_f32_16x16x32_bf16 v[106:109], v[176:179], v[208:211], v[106:109]
	v_mfma_f32_16x16x32_bf16 v[94:97], v[154:157], v[216:219], v[94:97]
	v_mfma_f32_16x16x32_bf16 v[90:93], v[176:179], v[216:219], v[90:93]
	v_mfma_f32_16x16x32_bf16 v[78:81], v[154:157], v[224:227], v[78:81]
	v_mfma_f32_16x16x32_bf16 v[74:77], v[176:179], v[224:227], v[74:77]
	v_mfma_f32_16x16x32_bf16 v[126:129], v[172:175], v[204:207], v[126:129]
	v_mfma_f32_16x16x32_bf16 v[122:125], v[180:183], v[204:207], v[122:125]
	v_mfma_f32_16x16x32_bf16 v[110:113], v[172:175], v[212:215], v[110:113]
	v_mfma_f32_16x16x32_bf16 v[106:109], v[180:183], v[212:215], v[106:109]
	v_mfma_f32_16x16x32_bf16 v[94:97], v[172:175], v[220:223], v[94:97]
	v_mfma_f32_16x16x32_bf16 v[90:93], v[180:183], v[220:223], v[90:93]
	v_mfma_f32_16x16x32_bf16 v[78:81], v[172:175], v[228:231], v[78:81]
	v_mfma_f32_16x16x32_bf16 v[74:77], v[180:183], v[228:231], v[74:77]
	s_setprio 0
	s_setprio 1
	v_mfma_f32_16x16x32_bf16 v[118:121], v[184:187], v[200:203], v[118:121]
	v_mfma_f32_16x16x32_bf16 v[114:117], v[192:195], v[200:203], v[114:117]
	v_mfma_f32_16x16x32_bf16 v[102:105], v[184:187], v[208:211], v[102:105]
	v_mfma_f32_16x16x32_bf16 v[98:101], v[192:195], v[208:211], v[98:101]
	v_mfma_f32_16x16x32_bf16 v[86:89], v[184:187], v[216:219], v[86:89]
	v_mfma_f32_16x16x32_bf16 v[82:85], v[192:195], v[216:219], v[82:85]
	v_mfma_f32_16x16x32_bf16 v[70:73], v[184:187], v[224:227], v[70:73]
	v_mfma_f32_16x16x32_bf16 v[66:69], v[192:195], v[224:227], v[66:69]
	v_mfma_f32_16x16x32_bf16 v[118:121], v[188:191], v[204:207], v[118:121]
	v_mfma_f32_16x16x32_bf16 v[114:117], v[196:199], v[204:207], v[114:117]
	v_mfma_f32_16x16x32_bf16 v[102:105], v[188:191], v[212:215], v[102:105]
	v_mfma_f32_16x16x32_bf16 v[98:101], v[196:199], v[212:215], v[98:101]
	v_mfma_f32_16x16x32_bf16 v[86:89], v[188:191], v[220:223], v[86:89]
	v_mfma_f32_16x16x32_bf16 v[82:85], v[196:199], v[220:223], v[82:85]
	v_mfma_f32_16x16x32_bf16 v[70:73], v[188:191], v[228:231], v[70:73]
	v_mfma_f32_16x16x32_bf16 v[66:69], v[196:199], v[228:231], v[66:69]
	s_setprio 0
	s_barrier
	s_add_i32 s33, s33, s53
	v_lshl_add_u64 v[232:233], v[232:233], 0, s[12:13]
	s_mov_b32 m0, s33
	ds_read_b128 v[200:203], v164 offset:49152
	ds_read_b128 v[204:207], v164 offset:50176
	ds_read_b128 v[208:211], v164 offset:51200
	ds_read_b128 v[212:215], v164 offset:52224
	ds_read_b128 v[216:219], v164 offset:53248
	ds_read_b128 v[220:223], v164 offset:54272
	ds_read_b128 v[224:227], v164 offset:55296
	ds_read_b128 v[228:231], v164 offset:56320
	global_load_lds_dwordx4 v[232:233], off
	s_add_i32 m0, s33, 0x2000
	s_add_u32 s42, s42, 0x80080
	v_lshl_add_u64 v[232:233], v[234:235], 0, s[12:13]
	s_addc_u32 s43, s43, 0
	s_add_i32 s33, s80, s53
	global_load_lds_dwordx4 v[232:233], off
	v_lshl_add_u64 v[232:233], s[42:43], 0, v[134:135]
	s_mov_b32 m0, s33
	s_nop 0
	global_load_lds_dwordx4 v[232:233], off
	v_lshl_add_u64 v[232:233], s[42:43], 0, v[138:139]
	s_add_i32 m0, s33, 0x2000
	s_nop 0
	global_load_lds_dwordx4 v[232:233], off
	s_waitcnt vmcnt(6)
	s_waitcnt lgkmcnt(0)
	s_barrier
	s_setprio 1
	s_waitcnt lgkmcnt(0)
	v_mfma_f32_16x16x32_bf16 v[62:65], v[154:157], v[200:203], v[62:65]
	v_mfma_f32_16x16x32_bf16 v[58:61], v[176:179], v[200:203], v[58:61]
	v_mfma_f32_16x16x32_bf16 v[46:49], v[154:157], v[208:211], v[46:49]
	v_mfma_f32_16x16x32_bf16 v[42:45], v[176:179], v[208:211], v[42:45]
	v_mfma_f32_16x16x32_bf16 v[30:33], v[154:157], v[216:219], v[30:33]
	v_mfma_f32_16x16x32_bf16 v[26:29], v[176:179], v[216:219], v[26:29]
	v_mfma_f32_16x16x32_bf16 v[14:17], v[154:157], v[224:227], v[14:17]
	v_mfma_f32_16x16x32_bf16 v[10:13], v[176:179], v[224:227], v[10:13]
	v_mfma_f32_16x16x32_bf16 v[62:65], v[172:175], v[204:207], v[62:65]
	v_mfma_f32_16x16x32_bf16 v[58:61], v[180:183], v[204:207], v[58:61]
	v_mfma_f32_16x16x32_bf16 v[46:49], v[172:175], v[212:215], v[46:49]
	v_mfma_f32_16x16x32_bf16 v[42:45], v[180:183], v[212:215], v[42:45]
	v_mfma_f32_16x16x32_bf16 v[30:33], v[172:175], v[220:223], v[30:33]
	v_mfma_f32_16x16x32_bf16 v[26:29], v[180:183], v[220:223], v[26:29]
	v_mfma_f32_16x16x32_bf16 v[14:17], v[172:175], v[228:231], v[14:17]
	v_mfma_f32_16x16x32_bf16 v[10:13], v[180:183], v[228:231], v[10:13]
	s_setprio 0
	s_setprio 1
	v_mfma_f32_16x16x32_bf16 v[54:57], v[184:187], v[200:203], v[54:57]
	v_mfma_f32_16x16x32_bf16 v[50:53], v[192:195], v[200:203], v[50:53]
	v_mfma_f32_16x16x32_bf16 v[38:41], v[184:187], v[208:211], v[38:41]
	v_mfma_f32_16x16x32_bf16 v[34:37], v[192:195], v[208:211], v[34:37]
	v_mfma_f32_16x16x32_bf16 v[22:25], v[184:187], v[216:219], v[22:25]
	v_mfma_f32_16x16x32_bf16 v[18:21], v[192:195], v[216:219], v[18:21]
	v_mfma_f32_16x16x32_bf16 v[6:9], v[184:187], v[224:227], v[6:9]
	v_mfma_f32_16x16x32_bf16 v[2:5], v[192:195], v[224:227], v[2:5]
	v_mfma_f32_16x16x32_bf16 v[54:57], v[188:191], v[204:207], v[54:57]
	v_mfma_f32_16x16x32_bf16 v[50:53], v[196:199], v[204:207], v[50:53]
	v_mfma_f32_16x16x32_bf16 v[38:41], v[188:191], v[212:215], v[38:41]
	v_mfma_f32_16x16x32_bf16 v[34:37], v[196:199], v[212:215], v[34:37]
	v_mfma_f32_16x16x32_bf16 v[22:25], v[188:191], v[220:223], v[22:25]
	v_mfma_f32_16x16x32_bf16 v[18:21], v[196:199], v[220:223], v[18:21]
	v_mfma_f32_16x16x32_bf16 v[6:9], v[188:191], v[228:231], v[6:9]
	v_mfma_f32_16x16x32_bf16 v[2:5], v[196:199], v[228:231], v[2:5]
	s_setprio 0
	s_barrier
	s_add_i32 s79, s79, 2
	s_add_u32 s40, s40, 0x100
	s_addc_u32 s41, s41, 0
	s_add_u32 s67, s67, 0x100
	s_addc_u32 s78, s78, 0
	s_cmp_lt_u32 s79, 30
	s_cbranch_scc1 .LBB0_581
	s_andn2_b64 vcc, exec, s[24:25]
	s_cbranch_vccnz .LBB0_584
	s_barrier

; #define PG8_STAGE(bufoff, gbase, voff) do { _Pragma("unroll") for (int _i = 0; _i < 2; ++_i) \
;         __builtin_amdgcn_global_load_lds((const unsigned*)((const char*)(gbase) + (voff)[_i]), (PG8_LAS unsigned*)(lds + (bufoff) + ldsw + _i * 8192), 16, 0, 0); } while (0)
; #define PG8_LDA(dst, b, h) do { _Pragma("unroll") for (int m = 0; m < 4; ++m) _Pragma("unroll") for (int k = 0; k < 2; ++k) dst[m][k] = *(const PG8_LAS bf16x8*)(lds + PG8_SA(b, h) + aoff + m * 2048 + k * 1024); } while (0)
; #define PG8_LDB(dst, b, h) do { _Pragma("unroll") for (int n = 0; n < 2; ++n) _Pragma("unroll") for (int k = 0; k < 2; ++k) dst[n][k] = *(const PG8_LAS bf16x8*)(lds + PG8_SB(b, h) + boff + n * 2048 + k * 1024); } while (0)
; #define PG8_MMA(ai, bj, At, Bt) do { __builtin_amdgcn_s_setprio(1); _Pragma("unroll") for (int m = 0; m < 4; ++m) _Pragma("unroll") for (int n = 0; n < 2; ++n) _Pragma("unroll") for (int k = 0; k < 2; ++k) \
;         acc[ai][bj][m][n] = __builtin_amdgcn_mfma_f32_16x16x32_bf16(Bt[n][k], At[m][k], acc[ai][bj][m][n], 0, 0, 0); __builtin_amdgcn_s_setprio(0); } while (0)
; #define PG8_WAIT_V(n) asm volatile("s_waitcnt vmcnt(" #n ")" ::: "memory")
; #define PG8_WAIT_L(n) asm volatile("s_waitcnt lgkmcnt(" #n ")" ::: "memory")
; #define PG8_BAR __builtin_amdgcn_s_barrier()
; #define PG8_SCHED __builtin_amdgcn_sched_barrier(0)
; template <class Epi, class Sched, bool ALIGN_EPI = false, bool SP2 = false, bool KSEG = false>
; __device__ __forceinline__ void gemm_phase(PG8_LAS unsigned char* lds, const Gemm g, const Sched& S, const Epi& E) {
;     ...
;             PG8_LDB(B0, 0, 0); PG8_LDB(B1, 0, 1); PG8_SCHED; PG8_LDA(At, 0, 0); PG8_STAGE(PG8_SA(1, 1), a1 + hstep, voffA);
;             PG8_WAIT_V(8); PG8_WAIT_L(0); PG8_BAR; PG8_MMA(0, 0, At, B0); PG8_MMA(0, 1, At, B1); PG8_BAR; PG8_SCHED;
;             PG8_LDA(At, 0, 1); PG8_STAGE(PG8_SB(0, 0), b2, voffB); PG8_STAGE(PG8_SB(0, 1), b2 + hstep, voffB); PG8_STAGE(PG8_SA(0, 0), a2, voffA);
;             PG8_WAIT_V(8); PG8_WAIT_L(0); PG8_BAR; PG8_MMA(1, 0, At, B0); PG8_MMA(1, 1, At, B1); PG8_BAR; PG8_SCHED;
.LBB0_621:
	ds_read_b128 v[146:149], v1
	ds_read_b128 v[156:159], v1 offset:1024
	ds_read_b128 v[160:163], v1 offset:2048
	ds_read_b128 v[164:167], v1 offset:3072
	ds_read_b128 v[168:171], v153
	ds_read_b128 v[172:175], v153 offset:1024
	ds_read_b128 v[176:179], v153 offset:2048
	ds_read_b128 v[180:183], v153 offset:3072
	s_add_u32 s26, s24, 0xffea0080
	s_addc_u32 s27, s25, -1
	s_cmpk_eq_i32 s50, 0x54
	s_cselect_b32 s29, s21, s27
	s_cselect_b32 s28, s20, s26
	s_cselect_b32 s27, s9, s49
	s_cselect_b32 s26, s8, s48
	s_add_u32 s98, s24, 0xffea0000
	s_addc_u32 s99, s25, -1
	v_lshl_add_u64 v[216:217], s[98:99], 0, v[140:141]
	s_mov_b32 m0, s40
	s_nop 0
	global_load_lds_dwordx4 v[216:217], off
	v_lshl_add_u64 v[216:217], s[98:99], 0, v[142:143]
	s_mov_b32 m0, s41
	s_nop 0
	global_load_lds_dwordx4 v[216:217], off
	v_lshl_add_u64 v[216:217], s[24:25], 0, v[132:133]
	s_add_i32 m0, s31, 0xc000
	ds_read_b128 v[184:187], v154
	ds_read_b128 v[188:191], v154 offset:1024
	ds_read_b128 v[192:195], v154 offset:2048
	ds_read_b128 v[196:199], v154 offset:3072
	ds_read_b128 v[200:203], v154 offset:4096
	ds_read_b128 v[204:207], v154 offset:5120
	ds_read_b128 v[208:211], v154 offset:6144
	ds_read_b128 v[212:215], v154 offset:7168
	global_load_lds_dwordx4 v[216:217], off
	v_lshl_add_u64 v[216:217], s[24:25], 0, v[134:135]
	s_add_i32 m0, s31, 0xe000
	s_nop 0
	global_load_lds_dwordx4 v[216:217], off
	s_waitcnt vmcnt(8)
	s_waitcnt lgkmcnt(0)
	s_barrier
	s_setprio 1
	s_waitcnt lgkmcnt(0)
	v_mfma_f32_16x16x32_bf16 v[126:129], v[146:149], v[184:187], v[126:129]
	v_mfma_f32_16x16x32_bf16 v[122:125], v[160:163], v[184:187], v[122:125]
	v_mfma_f32_16x16x32_bf16 v[110:113], v[146:149], v[192:195], v[110:113]
	v_mfma_f32_16x16x32_bf16 v[106:109], v[160:163], v[192:195], v[106:109]
	v_mfma_f32_16x16x32_bf16 v[94:97], v[146:149], v[200:203], v[94:97]
	v_mfma_f32_16x16x32_bf16 v[90:93], v[160:163], v[200:203], v[90:93]
	v_mfma_f32_16x16x32_bf16 v[78:81], v[146:149], v[208:211], v[78:81]
	v_mfma_f32_16x16x32_bf16 v[74:77], v[160:163], v[208:211], v[74:77]
	v_mfma_f32_16x16x32_bf16 v[126:129], v[156:159], v[188:191], v[126:129]
	v_mfma_f32_16x16x32_bf16 v[122:125], v[164:167], v[188:191], v[122:125]
	v_mfma_f32_16x16x32_bf16 v[110:113], v[156:159], v[196:199], v[110:113]
	v_mfma_f32_16x16x32_bf16 v[106:109], v[164:167], v[196:199], v[106:109]
	v_mfma_f32_16x16x32_bf16 v[94:97], v[156:159], v[204:207], v[94:97]
	v_mfma_f32_16x16x32_bf16 v[90:93], v[164:167], v[204:207], v[90:93]
	v_mfma_f32_16x16x32_bf16 v[78:81], v[156:159], v[212:215], v[78:81]
	v_mfma_f32_16x16x32_bf16 v[74:77], v[164:167], v[212:215], v[74:77]
	s_setprio 0
	s_setprio 1
	v_mfma_f32_16x16x32_bf16 v[118:121], v[168:171], v[184:187], v[118:121]
	v_mfma_f32_16x16x32_bf16 v[114:117], v[176:179], v[184:187], v[114:117]
	v_mfma_f32_16x16x32_bf16 v[102:105], v[168:171], v[192:195], v[102:105]
	v_mfma_f32_16x16x32_bf16 v[98:101], v[176:179], v[192:195], v[98:101]
	v_mfma_f32_16x16x32_bf16 v[86:89], v[168:171], v[200:203], v[86:89]
	v_mfma_f32_16x16x32_bf16 v[82:85], v[176:179], v[200:203], v[82:85]
	v_mfma_f32_16x16x32_bf16 v[70:73], v[168:171], v[208:211], v[70:73]
	v_mfma_f32_16x16x32_bf16 v[66:69], v[176:179], v[208:211], v[66:69]
	v_mfma_f32_16x16x32_bf16 v[118:121], v[172:175], v[188:191], v[118:121]
	v_mfma_f32_16x16x32_bf16 v[114:117], v[180:183], v[188:191], v[114:117]
	v_mfma_f32_16x16x32_bf16 v[102:105], v[172:175], v[196:199], v[102:105]
	v_mfma_f32_16x16x32_bf16 v[98:101], v[180:183], v[196:199], v[98:101]
	v_mfma_f32_16x16x32_bf16 v[86:89], v[172:175], v[204:207], v[86:89]
	v_mfma_f32_16x16x32_bf16 v[82:85], v[180:183], v[204:207], v[82:85]
	v_mfma_f32_16x16x32_bf16 v[70:73], v[172:175], v[212:215], v[70:73]
	v_mfma_f32_16x16x32_bf16 v[66:69], v[180:183], v[212:215], v[66:69]
	s_setprio 0
	s_barrier
	s_add_i32 s33, s42, s30
	v_lshl_add_u64 v[216:217], s[26:27], 0, v[130:131]
	s_mov_b32 m0, s33
	ds_read_b128 v[184:187], v154 offset:16384
	ds_read_b128 v[188:191], v154 offset:17408
	ds_read_b128 v[192:195], v154 offset:18432
	ds_read_b128 v[196:199], v154 offset:19456
	ds_read_b128 v[200:203], v154 offset:20480
	ds_read_b128 v[204:207], v154 offset:21504
	ds_read_b128 v[208:211], v154 offset:22528
	ds_read_b128 v[212:215], v154 offset:23552
	global_load_lds_dwordx4 v[216:217], off
	s_add_i32 m0, s33, 0x2000
	s_add_u32 s54, s26, 0x160000
	v_lshl_add_u64 v[218:219], s[26:27], 0, v[144:145]
	s_addc_u32 s55, s27, 0
	s_add_i32 s33, s43, s30
	global_load_lds_dwordx4 v[218:219], off
	v_lshl_add_u64 v[220:221], s[54:55], 0, v[130:131]
	s_mov_b32 m0, s33
	s_nop 0
	global_load_lds_dwordx4 v[220:221], off
	v_lshl_add_u64 v[220:221], s[54:55], 0, v[144:145]
	s_add_i32 m0, s33, 0x2000
	s_nop 0
	global_load_lds_dwordx4 v[220:221], off
	s_waitcnt vmcnt(6)
	s_waitcnt lgkmcnt(0)
	s_barrier
; #define PG8_STAGE(bufoff, gbase, voff) do { _Pragma("unroll") for (int _i = 0; _i < 2; ++_i) \
;         __builtin_amdgcn_global_load_lds((const unsigned*)((const char*)(gbase) + (voff)[_i]), (PG8_LAS unsigned*)(lds + (bufoff) + ldsw + _i * 8192), 16, 0, 0); } while (0)
; #define PG8_LDA(dst, b, h) do { _Pragma("unroll") for (int m = 0; m < 4; ++m) _Pragma("unroll") for (int k = 0; k < 2; ++k) dst[m][k] = *(const PG8_LAS bf16x8*)(lds + PG8_SA(b, h) + aoff + m * 2048 + k * 1024); } while (0)
; #define PG8_LDB(dst, b, h) do { _Pragma("unroll") for (int n = 0; n < 2; ++n) _Pragma("unroll") for (int k = 0; k < 2; ++k) dst[n][k] = *(const PG8_LAS bf16x8*)(lds + PG8_SB(b, h) + boff + n * 2048 + k * 1024); } while (0)
; #define PG8_MMA(ai, bj, At, Bt) do { __builtin_amdgcn_s_setprio(1); _Pragma("unroll") for (int m = 0; m < 4; ++m) _Pragma("unroll") for (int n = 0; n < 2; ++n) _Pragma("unroll") for (int k = 0; k < 2; ++k) \
;         acc[ai][bj][m][n] = __builtin_amdgcn_mfma_f32_16x16x32_bf16(Bt[n][k], At[m][k], acc[ai][bj][m][n], 0, 0, 0); __builtin_amdgcn_s_setprio(0); } while (0)
; #define PG8_WAIT_V(n) asm volatile("s_waitcnt vmcnt(" #n ")" ::: "memory")
; #define PG8_WAIT_L(n) asm volatile("s_waitcnt lgkmcnt(" #n ")" ::: "memory")
; #define PG8_BAR __builtin_amdgcn_s_barrier()
; #define PG8_SCHED __builtin_amdgcn_sched_barrier(0)
; template <class Epi, class Sched, bool ALIGN_EPI = false, bool SP2 = false, bool KSEG = false>
; __device__ __forceinline__ void gemm_phase(PG8_LAS unsigned char* lds, const Gemm g, const Sched& S, const Epi& E) {
;     ...
;             PG8_WAIT_V(8); PG8_WAIT_L(0); PG8_BAR; PG8_MMA(1, 0, At, B0); PG8_MMA(1, 1, At, B1); PG8_BAR; PG8_SCHED;
;             PG8_LDB(B0, 1, 0); PG8_LDB(B1, 1, 1); PG8_SCHED; PG8_LDA(At, 1, 0); PG8_STAGE(PG8_SA(0, 1), a2 + hstep, voffA);
;             PG8_WAIT_V(8); PG8_WAIT_L(0); PG8_BAR; PG8_MMA(0, 0, At, B0); PG8_MMA(0, 1, At, B1); PG8_BAR; PG8_SCHED;
	s_setprio 1
	s_waitcnt lgkmcnt(0)
	v_mfma_f32_16x16x32_bf16 v[62:65], v[146:149], v[184:187], v[62:65]
	v_mfma_f32_16x16x32_bf16 v[58:61], v[160:163], v[184:187], v[58:61]
	v_mfma_f32_16x16x32_bf16 v[46:49], v[146:149], v[192:195], v[46:49]
	v_mfma_f32_16x16x32_bf16 v[42:45], v[160:163], v[192:195], v[42:45]
	v_mfma_f32_16x16x32_bf16 v[30:33], v[146:149], v[200:203], v[30:33]
	v_mfma_f32_16x16x32_bf16 v[26:29], v[160:163], v[200:203], v[26:29]
	v_mfma_f32_16x16x32_bf16 v[14:17], v[146:149], v[208:211], v[14:17]
	v_mfma_f32_16x16x32_bf16 v[10:13], v[160:163], v[208:211], v[10:13]
	v_mfma_f32_16x16x32_bf16 v[62:65], v[156:159], v[188:191], v[62:65]
	v_mfma_f32_16x16x32_bf16 v[58:61], v[164:167], v[188:191], v[58:61]
	v_mfma_f32_16x16x32_bf16 v[46:49], v[156:159], v[196:199], v[46:49]
	v_mfma_f32_16x16x32_bf16 v[42:45], v[164:167], v[196:199], v[42:45]
	v_mfma_f32_16x16x32_bf16 v[30:33], v[156:159], v[204:207], v[30:33]
	v_mfma_f32_16x16x32_bf16 v[26:29], v[164:167], v[204:207], v[26:29]
	v_mfma_f32_16x16x32_bf16 v[14:17], v[156:159], v[212:215], v[14:17]
	v_mfma_f32_16x16x32_bf16 v[10:13], v[164:167], v[212:215], v[10:13]
	s_setprio 0
	s_setprio 1
	v_mfma_f32_16x16x32_bf16 v[54:57], v[168:171], v[184:187], v[54:57]
	v_mfma_f32_16x16x32_bf16 v[50:53], v[176:179], v[184:187], v[50:53]
	v_mfma_f32_16x16x32_bf16 v[38:41], v[168:171], v[192:195], v[38:41]
	v_mfma_f32_16x16x32_bf16 v[34:37], v[176:179], v[192:195], v[34:37]
	v_mfma_f32_16x16x32_bf16 v[22:25], v[168:171], v[200:203], v[22:25]
	v_mfma_f32_16x16x32_bf16 v[18:21], v[176:179], v[200:203], v[18:21]
	v_mfma_f32_16x16x32_bf16 v[6:9], v[168:171], v[208:211], v[6:9]
	v_mfma_f32_16x16x32_bf16 v[2:5], v[176:179], v[208:211], v[2:5]
	v_mfma_f32_16x16x32_bf16 v[54:57], v[172:175], v[188:191], v[54:57]
	v_mfma_f32_16x16x32_bf16 v[50:53], v[180:183], v[188:191], v[50:53]
	v_mfma_f32_16x16x32_bf16 v[38:41], v[172:175], v[196:199], v[38:41]
	v_mfma_f32_16x16x32_bf16 v[34:37], v[180:183], v[196:199], v[34:37]
	v_mfma_f32_16x16x32_bf16 v[22:25], v[172:175], v[204:207], v[22:25]
	v_mfma_f32_16x16x32_bf16 v[18:21], v[180:183], v[204:207], v[18:21]
	v_mfma_f32_16x16x32_bf16 v[6:9], v[172:175], v[212:215], v[6:9]
	v_mfma_f32_16x16x32_bf16 v[2:5], v[180:183], v[212:215], v[2:5]
	s_setprio 0
	s_barrier
	s_add_i32 s33, 0, 0x18000
	v_add_u32_e32 v155, s33, v150
	s_add_i32 s53, 0, 0x1c000
	ds_read_b128 v[146:149], v155
	ds_read_b128 v[156:159], v155 offset:1024
	ds_read_b128 v[160:163], v155 offset:2048
	ds_read_b128 v[164:167], v155 offset:3072
	v_add_u32_e32 v155, s53, v150
	ds_read_b128 v[168:171], v155
	ds_read_b128 v[172:175], v155 offset:1024
	ds_read_b128 v[176:179], v155 offset:2048
	ds_read_b128 v[180:183], v155 offset:3072
	v_lshl_add_u64 v[224:225], s[28:29], 0, v[140:141]
	s_mov_b32 m0, s31
	s_nop 0
	global_load_lds_dwordx4 v[224:225], off
	v_lshl_add_u64 v[224:225], s[28:29], 0, v[142:143]
	s_mov_b32 m0, s36
	s_nop 0
	global_load_lds_dwordx4 v[224:225], off
	s_add_u32 s28, s28, 0x160000
	s_addc_u32 s29, s29, 0
	s_mov_b32 m0, s37
	v_lshl_add_u64 v[224:225], s[28:29], 0, v[140:141]
	ds_read_b128 v[184:187], v154 offset:32768
	ds_read_b128 v[188:191], v154 offset:33792
	ds_read_b128 v[192:195], v154 offset:34816
	ds_read_b128 v[196:199], v154 offset:35840
	ds_read_b128 v[200:203], v154 offset:36864
	ds_read_b128 v[204:207], v154 offset:37888
	ds_read_b128 v[208:211], v154 offset:38912
	ds_read_b128 v[212:215], v154 offset:39936
	global_load_lds_dwordx4 v[224:225], off
	v_lshl_add_u64 v[224:225], s[28:29], 0, v[142:143]
	s_mov_b32 m0, s38
	s_nop 0
	global_load_lds_dwordx4 v[224:225], off
	s_waitcnt vmcnt(8)
	s_waitcnt lgkmcnt(0)
	s_barrier
; #define PG8_STAGE(bufoff, gbase, voff) do { _Pragma("unroll") for (int _i = 0; _i < 2; ++_i) \
;         __builtin_amdgcn_global_load_lds((const unsigned*)((const char*)(gbase) + (voff)[_i]), (PG8_LAS unsigned*)(lds + (bufoff) + ldsw + _i * 8192), 16, 0, 0); } while (0)
; #define PG8_LDA(dst, b, h) do { _Pragma("unroll") for (int m = 0; m < 4; ++m) _Pragma("unroll") for (int k = 0; k < 2; ++k) dst[m][k] = *(const PG8_LAS bf16x8*)(lds + PG8_SA(b, h) + aoff + m * 2048 + k * 1024); } while (0)
; #define PG8_MMA(ai, bj, At, Bt) do { __builtin_amdgcn_s_setprio(1); _Pragma("unroll") for (int m = 0; m < 4; ++m) _Pragma("unroll") for (int n = 0; n < 2; ++n) _Pragma("unroll") for (int k = 0; k < 2; ++k) \
;         acc[ai][bj][m][n] = __builtin_amdgcn_mfma_f32_16x16x32_bf16(Bt[n][k], At[m][k], acc[ai][bj][m][n], 0, 0, 0); __builtin_amdgcn_s_setprio(0); } while (0)
; #define PG8_WAIT_V(n) asm volatile("s_waitcnt vmcnt(" #n ")" ::: "memory")
; #define PG8_WAIT_L(n) asm volatile("s_waitcnt lgkmcnt(" #n ")" ::: "memory")
; #define PG8_BAR __builtin_amdgcn_s_barrier()
; #define PG8_SCHED __builtin_amdgcn_sched_barrier(0)
; template <class Epi, class Sched, bool ALIGN_EPI = false, bool SP2 = false, bool KSEG = false>
; __device__ __forceinline__ void gemm_phase(PG8_LAS unsigned char* lds, const Gemm g, const Sched& S, const Epi& E) {
;     ...
;             PG8_WAIT_V(8); PG8_WAIT_L(0); PG8_BAR; PG8_MMA(0, 0, At, B0); PG8_MMA(0, 1, At, B1); PG8_BAR; PG8_SCHED;
;             PG8_LDA(At, 1, 1); PG8_STAGE(PG8_SB(1, 0), b3, voffB); PG8_STAGE(PG8_SB(1, 1), b3 + hstep, voffB); PG8_STAGE(PG8_SA(1, 0), a3, voffA);
;             PG8_WAIT_V(8); PG8_WAIT_L(0); PG8_BAR; PG8_MMA(1, 0, At, B0); PG8_MMA(1, 1, At, B1); PG8_BAR; PG8_SCHED;
	s_setprio 1
	s_waitcnt lgkmcnt(0)
	v_mfma_f32_16x16x32_bf16 v[126:129], v[146:149], v[184:187], v[126:129]
	v_mfma_f32_16x16x32_bf16 v[122:125], v[160:163], v[184:187], v[122:125]
	v_mfma_f32_16x16x32_bf16 v[110:113], v[146:149], v[192:195], v[110:113]
	v_mfma_f32_16x16x32_bf16 v[106:109], v[160:163], v[192:195], v[106:109]
	v_mfma_f32_16x16x32_bf16 v[94:97], v[146:149], v[200:203], v[94:97]
	v_mfma_f32_16x16x32_bf16 v[90:93], v[160:163], v[200:203], v[90:93]
	v_mfma_f32_16x16x32_bf16 v[78:81], v[146:149], v[208:211], v[78:81]
	v_mfma_f32_16x16x32_bf16 v[74:77], v[160:163], v[208:211], v[74:77]
	v_mfma_f32_16x16x32_bf16 v[126:129], v[156:159], v[188:191], v[126:129]
	v_mfma_f32_16x16x32_bf16 v[122:125], v[164:167], v[188:191], v[122:125]
	v_mfma_f32_16x16x32_bf16 v[110:113], v[156:159], v[196:199], v[110:113]
	v_mfma_f32_16x16x32_bf16 v[106:109], v[164:167], v[196:199], v[106:109]
	v_mfma_f32_16x16x32_bf16 v[94:97], v[156:159], v[204:207], v[94:97]
	v_mfma_f32_16x16x32_bf16 v[90:93], v[164:167], v[204:207], v[90:93]
	v_mfma_f32_16x16x32_bf16 v[78:81], v[156:159], v[212:215], v[78:81]
	v_mfma_f32_16x16x32_bf16 v[74:77], v[164:167], v[212:215], v[74:77]
	s_setprio 0
	s_setprio 1
	v_mfma_f32_16x16x32_bf16 v[118:121], v[168:171], v[184:187], v[118:121]
	v_mfma_f32_16x16x32_bf16 v[114:117], v[176:179], v[184:187], v[114:117]
	v_mfma_f32_16x16x32_bf16 v[102:105], v[168:171], v[192:195], v[102:105]
	v_mfma_f32_16x16x32_bf16 v[98:101], v[176:179], v[192:195], v[98:101]
	v_mfma_f32_16x16x32_bf16 v[86:89], v[168:171], v[200:203], v[86:89]
	v_mfma_f32_16x16x32_bf16 v[82:85], v[176:179], v[200:203], v[82:85]
	v_mfma_f32_16x16x32_bf16 v[70:73], v[168:171], v[208:211], v[70:73]
	v_mfma_f32_16x16x32_bf16 v[66:69], v[176:179], v[208:211], v[66:69]
	v_mfma_f32_16x16x32_bf16 v[118:121], v[172:175], v[188:191], v[118:121]
	v_mfma_f32_16x16x32_bf16 v[114:117], v[180:183], v[188:191], v[114:117]
	v_mfma_f32_16x16x32_bf16 v[102:105], v[172:175], v[196:199], v[102:105]
	v_mfma_f32_16x16x32_bf16 v[98:101], v[180:183], v[196:199], v[98:101]
	v_mfma_f32_16x16x32_bf16 v[86:89], v[172:175], v[204:207], v[86:89]
	v_mfma_f32_16x16x32_bf16 v[82:85], v[180:183], v[204:207], v[82:85]
	v_mfma_f32_16x16x32_bf16 v[70:73], v[172:175], v[212:215], v[70:73]
	v_mfma_f32_16x16x32_bf16 v[66:69], v[180:183], v[212:215], v[66:69]
	s_setprio 0
	s_barrier
	s_add_i32 s28, s33, s30
	v_lshl_add_u64 v[216:217], v[216:217], 0, s[12:13]
	s_mov_b32 m0, s28
	ds_read_b128 v[184:187], v154 offset:49152
	ds_read_b128 v[188:191], v154 offset:50176
	ds_read_b128 v[192:195], v154 offset:51200
	ds_read_b128 v[196:199], v154 offset:52224
	ds_read_b128 v[200:203], v154 offset:53248
	ds_read_b128 v[204:207], v154 offset:54272
	ds_read_b128 v[208:211], v154 offset:55296
	ds_read_b128 v[212:215], v154 offset:56320
	global_load_lds_dwordx4 v[216:217], off
	s_add_i32 m0, s28, 0x2000
	s_add_u32 s26, s26, 0x160080
	v_lshl_add_u64 v[216:217], v[218:219], 0, s[12:13]
	s_addc_u32 s27, s27, 0
	s_add_i32 s28, s53, s30
	global_load_lds_dwordx4 v[216:217], off
	v_lshl_add_u64 v[216:217], s[26:27], 0, v[130:131]
	s_mov_b32 m0, s28
	s_nop 0
	global_load_lds_dwordx4 v[216:217], off
	v_lshl_add_u64 v[216:217], s[26:27], 0, v[144:145]
	s_add_i32 m0, s28, 0x2000
	s_nop 0
	global_load_lds_dwordx4 v[216:217], off
	s_waitcnt vmcnt(6)
	s_waitcnt lgkmcnt(0)
	s_barrier
	s_setprio 1
	s_waitcnt lgkmcnt(0)
	v_mfma_f32_16x16x32_bf16 v[62:65], v[146:149], v[184:187], v[62:65]
	v_mfma_f32_16x16x32_bf16 v[58:61], v[160:163], v[184:187], v[58:61]
	v_mfma_f32_16x16x32_bf16 v[46:49], v[146:149], v[192:195], v[46:49]
	v_mfma_f32_16x16x32_bf16 v[42:45], v[160:163], v[192:195], v[42:45]
	v_mfma_f32_16x16x32_bf16 v[30:33], v[146:149], v[200:203], v[30:33]
	v_mfma_f32_16x16x32_bf16 v[26:29], v[160:163], v[200:203], v[26:29]
	v_mfma_f32_16x16x32_bf16 v[14:17], v[146:149], v[208:211], v[14:17]
	v_mfma_f32_16x16x32_bf16 v[10:13], v[160:163], v[208:211], v[10:13]
	v_mfma_f32_16x16x32_bf16 v[62:65], v[156:159], v[188:191], v[62:65]
	v_mfma_f32_16x16x32_bf16 v[58:61], v[164:167], v[188:191], v[58:61]
	v_mfma_f32_16x16x32_bf16 v[46:49], v[156:159], v[196:199], v[46:49]
	v_mfma_f32_16x16x32_bf16 v[42:45], v[164:167], v[196:199], v[42:45]
	v_mfma_f32_16x16x32_bf16 v[30:33], v[156:159], v[204:207], v[30:33]
	v_mfma_f32_16x16x32_bf16 v[26:29], v[164:167], v[204:207], v[26:29]
	v_mfma_f32_16x16x32_bf16 v[14:17], v[156:159], v[212:215], v[14:17]
	v_mfma_f32_16x16x32_bf16 v[10:13], v[164:167], v[212:215], v[10:13]
	s_setprio 0
	s_setprio 1
	v_mfma_f32_16x16x32_bf16 v[54:57], v[168:171], v[184:187], v[54:57]
	v_mfma_f32_16x16x32_bf16 v[50:53], v[176:179], v[184:187], v[50:53]
	v_mfma_f32_16x16x32_bf16 v[38:41], v[168:171], v[192:195], v[38:41]
	v_mfma_f32_16x16x32_bf16 v[34:37], v[176:179], v[192:195], v[34:37]
	v_mfma_f32_16x16x32_bf16 v[22:25], v[168:171], v[200:203], v[22:25]
	v_mfma_f32_16x16x32_bf16 v[18:21], v[176:179], v[200:203], v[18:21]
	v_mfma_f32_16x16x32_bf16 v[6:9], v[168:171], v[208:211], v[6:9]
	v_mfma_f32_16x16x32_bf16 v[2:5], v[176:179], v[208:211], v[2:5]
	v_mfma_f32_16x16x32_bf16 v[54:57], v[172:175], v[188:191], v[54:57]
	v_mfma_f32_16x16x32_bf16 v[50:53], v[180:183], v[188:191], v[50:53]
	v_mfma_f32_16x16x32_bf16 v[38:41], v[172:175], v[196:199], v[38:41]
	v_mfma_f32_16x16x32_bf16 v[34:37], v[180:183], v[196:199], v[34:37]
	v_mfma_f32_16x16x32_bf16 v[22:25], v[172:175], v[204:207], v[22:25]
	v_mfma_f32_16x16x32_bf16 v[18:21], v[180:183], v[204:207], v[18:21]
	v_mfma_f32_16x16x32_bf16 v[6:9], v[172:175], v[212:215], v[6:9]
	v_mfma_f32_16x16x32_bf16 v[2:5], v[180:183], v[212:215], v[2:5]
	s_setprio 0
	s_barrier
	s_add_i32 s50, s50, 2
	s_add_u32 s24, s24, 0x100
	s_addc_u32 s25, s25, 0
	s_add_u32 s48, s48, 0x100
	s_addc_u32 s49, s49, 0
	s_cmpk_lt_u32 s50, 0x56
	s_cbranch_scc1 .LBB0_621
	s_andn2_b64 vcc, exec, s[18:19]
	s_cbranch_vccnz .LBB0_624
	s_barrier

; __global__ void __launch_bounds__(NWAVES * 64, 2) hymba_fwd(Params P) {
	.amdhsa_kernel _Z9hymba_fwd6Params
		.amdhsa_group_segment_fixed_size 0
		.amdhsa_private_segment_fixed_size 0
		.amdhsa_kernarg_size 416
		.amdhsa_user_sgpr_count 2
		.amdhsa_user_sgpr_dispatch_ptr 0
		.amdhsa_user_sgpr_queue_ptr 0
		.amdhsa_user_sgpr_kernarg_segment_ptr 1
		.amdhsa_user_sgpr_dispatch_id 0
		.amdhsa_user_sgpr_kernarg_preload_length 0
		.amdhsa_user_sgpr_kernarg_preload_offset 0
		.amdhsa_user_sgpr_private_segment_size 0
		.amdhsa_uses_dynamic_stack 0
		.amdhsa_enable_private_segment 0
		.amdhsa_system_sgpr_workgroup_id_x 1
		.amdhsa_system_sgpr_workgroup_id_y 0
		.amdhsa_system_sgpr_workgroup_id_z 0
		.amdhsa_system_sgpr_workgroup_info 0
		.amdhsa_system_vgpr_workitem_id 0
		.amdhsa_next_free_vgpr 255
		.amdhsa_next_free_sgpr 100
		.amdhsa_accum_offset 256
		.amdhsa_reserve_vcc 1
		.amdhsa_float_round_mode_32 0
		.amdhsa_float_round_mode_16_64 0
		.amdhsa_float_denorm_mode_32 3
		.amdhsa_float_denorm_mode_16_64 3
		.amdhsa_dx10_clamp 1
		.amdhsa_ieee_mode 1
		.amdhsa_fp16_overflow 0
		.amdhsa_tg_split 0
		.amdhsa_exception_fp_ieee_invalid_op 0
		.amdhsa_exception_fp_denorm_src 0
		.amdhsa_exception_fp_ieee_div_zero 0
		.amdhsa_exception_fp_ieee_overflow 0
		.amdhsa_exception_fp_ieee_underflow 0
		.amdhsa_exception_fp_ieee_inexact 0
		.amdhsa_exception_int_div_zero 0
	.end_amdhsa_kernel

; __global__ void __launch_bounds__(NWAVES * 64, 2) hymba_fwd(Params P) {
amdhsa.kernels:
  - .agpr_count:     0
    .args:
      - .offset:         0
        .size:           160
        .value_kind:     by_value
      - .offset:         160
        .size:           4
        .value_kind:     hidden_block_count_x
      - .offset:         164
        .size:           4
        .value_kind:     hidden_block_count_y
      - .offset:         168
        .size:           4
        .value_kind:     hidden_block_count_z
      - .offset:         172
        .size:           2
        .value_kind:     hidden_group_size_x
      - .offset:         174
        .size:           2
        .value_kind:     hidden_group_size_y
      - .offset:         176
        .size:           2
        .value_kind:     hidden_group_size_z
      - .offset:         178
        .size:           2
        .value_kind:     hidden_remainder_x
      - .offset:         180
        .size:           2
        .value_kind:     hidden_remainder_y
      - .offset:         182
        .size:           2
        .value_kind:     hidden_remainder_z
      - .offset:         200
        .size:           8
        .value_kind:     hidden_global_offset_x
      - .offset:         208
        .size:           8
        .value_kind:     hidden_global_offset_y
      - .offset:         216
        .size:           8
        .value_kind:     hidden_global_offset_z
      - .offset:         224
        .size:           2
        .value_kind:     hidden_grid_dims
      - .offset:         248
        .size:           8
        .value_kind:     hidden_multigrid_sync_arg
      - .offset:         280
        .size:           4
        .value_kind:     hidden_dynamic_lds_size
    .group_segment_fixed_size: 0
    .kernarg_segment_align: 8
    .kernarg_segment_size: 416
    .language:       OpenCL C
    .language_version:
      - 2
      - 0
    .max_flat_workgroup_size: 512
    .name:           _Z9hymba_fwd6Params
    .private_segment_fixed_size: 0
    .sgpr_count:     106
    .sgpr_spill_count: 3
    .symbol:         _Z9hymba_fwd6Params.kd
    .uniform_work_group_size: 1
    .uses_dynamic_stack: false
    .vgpr_count:     255
    .vgpr_spill_count: 0
    .wavefront_size: 64
